# K-loop MFMA order v3: accumulator pairs, A fragment slow / B fragment fast snake, alternating k order
# baseline (speedup 1.0000x reference)
.LBB0_140:
	s_ashr_i32 s37, s36, 31
	s_lshl_b64 s[42:43], s[36:37], 19
	s_add_u32 s42, s62, s42
	s_addc_u32 s43, s63, s43
	s_and_b64 s[44:45], s[0:1], exec
	s_cselect_b32 s37, s43, s49
	s_cselect_b32 s77, s42, s48
	s_ashr_i32 s39, s38, 31
	s_lshl_b64 s[44:45], s[38:39], 19
	s_add_u32 s44, s54, s44
	s_addc_u32 s45, s55, s45
	s_and_b64 s[52:53], s[0:1], exec
	s_cselect_b32 s39, s45, s51
	s_cselect_b32 s78, s44, s50
	s_add_u32 s48, s48, 0x40080
	s_addc_u32 s49, s49, 0
	s_add_u32 s79, s50, 0x100
	s_addc_u32 s80, s51, 0
	s_mov_b32 s81, -2
	ds_read_b128 v[150:153], v147
	ds_read_b128 v[154:157], v147 offset:1024
	ds_read_b128 v[158:161], v147 offset:2048
	ds_read_b128 v[162:165], v147 offset:3072
	ds_read_b128 v[166:169], v148
	ds_read_b128 v[170:173], v148 offset:1024
	ds_read_b128 v[174:177], v148 offset:2048
	ds_read_b128 v[178:181], v148 offset:3072
	s_add_u32 s50, s48, 0xfffc0080
	s_addc_u32 s51, s49, -1
	s_cmp_eq_u32 s81, 12
	s_cselect_b32 s53, s37, s51
	s_cselect_b32 s52, s77, s50
	s_cselect_b32 s51, s39, s80
	s_cselect_b32 s50, s78, s79
	v_lshl_add_u64 v[214:215], s[48:49], 0, v[136:137]
	s_add_i32 m0, s47, 0xc000
	ds_read_b128 v[182:185], v149
	ds_read_b128 v[186:189], v149 offset:1024
	ds_read_b128 v[190:193], v149 offset:2048
	ds_read_b128 v[194:197], v149 offset:3072
	ds_read_b128 v[198:201], v149 offset:4096
	ds_read_b128 v[202:205], v149 offset:5120
	ds_read_b128 v[206:209], v149 offset:6144
	ds_read_b128 v[210:213], v149 offset:7168
	global_load_lds_dwordx4 v[214:215], off
	v_lshl_add_u64 v[214:215], s[48:49], 0, v[138:139]
	s_add_i32 m0, s47, 0xe000
	s_nop 0
	global_load_lds_dwordx4 v[214:215], off
	s_waitcnt vmcnt(8)
	s_waitcnt lgkmcnt(0)
	s_setprio 1
	s_barrier
	v_mfma_f32_16x16x32_bf16 v[124:127], v[150:153], v[182:185], 0
	v_mfma_f32_16x16x32_bf16 v[124:127], v[154:157], v[186:189], v[124:127]
	v_mfma_f32_16x16x32_bf16 v[108:111], v[154:157], v[194:197], 0
	v_mfma_f32_16x16x32_bf16 v[108:111], v[150:153], v[190:193], v[108:111]
	v_mfma_f32_16x16x32_bf16 v[92:95], v[150:153], v[198:201], 0
	v_mfma_f32_16x16x32_bf16 v[92:95], v[154:157], v[202:205], v[92:95]
	v_mfma_f32_16x16x32_bf16 v[76:79], v[154:157], v[210:213], 0
	v_mfma_f32_16x16x32_bf16 v[76:79], v[150:153], v[206:209], v[76:79]
	v_mfma_f32_16x16x32_bf16 v[68:71], v[158:161], v[206:209], 0
	v_mfma_f32_16x16x32_bf16 v[68:71], v[162:165], v[210:213], v[68:71]
	v_mfma_f32_16x16x32_bf16 v[84:87], v[162:165], v[202:205], 0
	v_mfma_f32_16x16x32_bf16 v[84:87], v[158:161], v[198:201], v[84:87]
	v_mfma_f32_16x16x32_bf16 v[100:103], v[158:161], v[190:193], 0
	v_mfma_f32_16x16x32_bf16 v[100:103], v[162:165], v[194:197], v[100:103]
	v_mfma_f32_16x16x32_bf16 v[116:119], v[162:165], v[186:189], 0
	v_mfma_f32_16x16x32_bf16 v[116:119], v[158:161], v[182:185], v[116:119]
	v_mfma_f32_16x16x32_bf16 v[120:123], v[166:169], v[182:185], 0
	v_mfma_f32_16x16x32_bf16 v[120:123], v[170:173], v[186:189], v[120:123]
	v_mfma_f32_16x16x32_bf16 v[104:107], v[170:173], v[194:197], 0
	v_mfma_f32_16x16x32_bf16 v[104:107], v[166:169], v[190:193], v[104:107]
	v_mfma_f32_16x16x32_bf16 v[88:91], v[166:169], v[198:201], 0
	v_mfma_f32_16x16x32_bf16 v[88:91], v[170:173], v[202:205], v[88:91]
	v_mfma_f32_16x16x32_bf16 v[72:75], v[170:173], v[210:213], 0
	v_mfma_f32_16x16x32_bf16 v[72:75], v[166:169], v[206:209], v[72:75]
	v_mfma_f32_16x16x32_bf16 v[64:67], v[174:177], v[206:209], 0
	v_mfma_f32_16x16x32_bf16 v[64:67], v[178:181], v[210:213], v[64:67]
	v_mfma_f32_16x16x32_bf16 v[80:83], v[178:181], v[202:205], 0
	v_mfma_f32_16x16x32_bf16 v[80:83], v[174:177], v[198:201], v[80:83]
	v_mfma_f32_16x16x32_bf16 v[96:99], v[174:177], v[190:193], 0
	v_mfma_f32_16x16x32_bf16 v[96:99], v[178:181], v[194:197], v[96:99]
	v_mfma_f32_16x16x32_bf16 v[112:115], v[178:181], v[186:189], 0
	v_mfma_f32_16x16x32_bf16 v[112:115], v[174:177], v[182:185], v[112:115]
	s_barrier
	s_setprio 0
	s_add_i32 s82, s73, s56
	v_lshl_add_u64 v[214:215], s[50:51], 0, v[132:133]
	s_mov_b32 m0, s82
	ds_read_b128 v[182:185], v149 offset:16384
	ds_read_b128 v[186:189], v149 offset:17408
	ds_read_b128 v[190:193], v149 offset:18432
	ds_read_b128 v[194:197], v149 offset:19456
	ds_read_b128 v[198:201], v149 offset:20480
	ds_read_b128 v[202:205], v149 offset:21504
	ds_read_b128 v[206:209], v149 offset:22528
	ds_read_b128 v[210:213], v149 offset:23552
	global_load_lds_dwordx4 v[214:215], off
	s_add_i32 m0, s82, 0x2000
	s_add_u32 s88, s50, 0x40000
	v_lshl_add_u64 v[216:217], s[50:51], 0, v[128:129]
	s_addc_u32 s89, s51, 0
	s_add_i32 s82, s74, s56
	global_load_lds_dwordx4 v[216:217], off
	v_lshl_add_u64 v[218:219], s[88:89], 0, v[132:133]
	s_mov_b32 m0, s82
	v_lshl_add_u64 v[220:221], s[52:53], 0, v[130:131]
	global_load_lds_dwordx4 v[218:219], off
	v_lshl_add_u64 v[218:219], s[88:89], 0, v[128:129]
	s_add_i32 m0, s82, 0x2000
	s_nop 0
	global_load_lds_dwordx4 v[218:219], off
	v_lshl_add_u64 v[218:219], s[52:53], 0, v[134:135]
	s_mov_b32 m0, s47
	s_nop 0
	global_load_lds_dwordx4 v[218:219], off
	s_mov_b32 m0, s59
	s_nop 0
	global_load_lds_dwordx4 v[220:221], off
	s_waitcnt vmcnt(8)
	s_waitcnt lgkmcnt(0)
	s_setprio 1
	s_barrier
	v_mfma_f32_16x16x32_bf16 v[60:63], v[150:153], v[182:185], 0
	v_mfma_f32_16x16x32_bf16 v[60:63], v[154:157], v[186:189], v[60:63]
	v_mfma_f32_16x16x32_bf16 v[44:47], v[154:157], v[194:197], 0
	v_mfma_f32_16x16x32_bf16 v[44:47], v[150:153], v[190:193], v[44:47]
	v_mfma_f32_16x16x32_bf16 v[28:31], v[150:153], v[198:201], 0
	v_mfma_f32_16x16x32_bf16 v[28:31], v[154:157], v[202:205], v[28:31]
	v_mfma_f32_16x16x32_bf16 v[12:15], v[154:157], v[210:213], 0
	v_mfma_f32_16x16x32_bf16 v[12:15], v[150:153], v[206:209], v[12:15]
	v_mfma_f32_16x16x32_bf16 v[4:7], v[158:161], v[206:209], 0
	v_mfma_f32_16x16x32_bf16 v[4:7], v[162:165], v[210:213], v[4:7]
	v_mfma_f32_16x16x32_bf16 v[20:23], v[162:165], v[202:205], 0
	v_mfma_f32_16x16x32_bf16 v[20:23], v[158:161], v[198:201], v[20:23]
	v_mfma_f32_16x16x32_bf16 v[36:39], v[158:161], v[190:193], 0
	v_mfma_f32_16x16x32_bf16 v[36:39], v[162:165], v[194:197], v[36:39]
	v_mfma_f32_16x16x32_bf16 v[52:55], v[162:165], v[186:189], 0
	v_mfma_f32_16x16x32_bf16 v[52:55], v[158:161], v[182:185], v[52:55]
	v_mfma_f32_16x16x32_bf16 v[56:59], v[166:169], v[182:185], 0
	v_mfma_f32_16x16x32_bf16 v[56:59], v[170:173], v[186:189], v[56:59]
	v_mfma_f32_16x16x32_bf16 v[40:43], v[170:173], v[194:197], 0
	v_mfma_f32_16x16x32_bf16 v[40:43], v[166:169], v[190:193], v[40:43]
	v_mfma_f32_16x16x32_bf16 v[24:27], v[166:169], v[198:201], 0
	v_mfma_f32_16x16x32_bf16 v[24:27], v[170:173], v[202:205], v[24:27]
	v_mfma_f32_16x16x32_bf16 v[8:11], v[170:173], v[210:213], 0
	v_mfma_f32_16x16x32_bf16 v[8:11], v[166:169], v[206:209], v[8:11]
	v_mfma_f32_16x16x32_bf16 v[0:3], v[174:177], v[206:209], 0
	v_mfma_f32_16x16x32_bf16 v[0:3], v[178:181], v[210:213], v[0:3]
	v_mfma_f32_16x16x32_bf16 v[16:19], v[178:181], v[202:205], 0
	v_mfma_f32_16x16x32_bf16 v[16:19], v[174:177], v[198:201], v[16:19]
	v_mfma_f32_16x16x32_bf16 v[32:35], v[174:177], v[190:193], 0
	v_mfma_f32_16x16x32_bf16 v[32:35], v[178:181], v[194:197], v[32:35]
	v_mfma_f32_16x16x32_bf16 v[48:51], v[178:181], v[186:189], 0
	v_mfma_f32_16x16x32_bf16 v[48:51], v[174:177], v[182:185], v[48:51]
	s_barrier
	s_setprio 0
	s_add_i32 s82, 0, 0x18000
	s_add_i32 s85, 0, 0x1c000
	v_add_u32_e32 v162, s82, v145
	v_add_u32_e32 v178, s85, v145
	ds_read_b128 v[150:153], v162
	ds_read_b128 v[154:157], v162 offset:1024
	ds_read_b128 v[158:161], v162 offset:2048
	ds_read_b128 v[162:165], v162 offset:3072
	ds_read_b128 v[166:169], v178
	ds_read_b128 v[170:173], v178 offset:1024
	ds_read_b128 v[174:177], v178 offset:2048
	ds_read_b128 v[178:181], v178 offset:3072
	s_add_u32 s52, s52, 0x40000
	s_addc_u32 s53, s53, 0
	s_mov_b32 m0, s66
	v_lshl_add_u64 v[222:223], s[52:53], 0, v[134:135]
	ds_read_b128 v[182:185], v149 offset:32768
	ds_read_b128 v[186:189], v149 offset:33792
	ds_read_b128 v[190:193], v149 offset:34816
	ds_read_b128 v[194:197], v149 offset:35840
	ds_read_b128 v[198:201], v149 offset:36864
	ds_read_b128 v[202:205], v149 offset:37888
	ds_read_b128 v[206:209], v149 offset:38912
	ds_read_b128 v[210:213], v149 offset:39936
	global_load_lds_dwordx4 v[222:223], off
	v_lshl_add_u64 v[222:223], s[52:53], 0, v[130:131]
	s_mov_b32 m0, s67
	s_nop 0
	global_load_lds_dwordx4 v[222:223], off
	s_waitcnt vmcnt(8)
	s_waitcnt lgkmcnt(0)
	s_setprio 1
	s_barrier
	v_mfma_f32_16x16x32_bf16 v[124:127], v[150:153], v[182:185], v[124:127]
	v_mfma_f32_16x16x32_bf16 v[124:127], v[154:157], v[186:189], v[124:127]
	v_mfma_f32_16x16x32_bf16 v[108:111], v[154:157], v[194:197], v[108:111]
	v_mfma_f32_16x16x32_bf16 v[108:111], v[150:153], v[190:193], v[108:111]
	v_mfma_f32_16x16x32_bf16 v[92:95], v[150:153], v[198:201], v[92:95]
	v_mfma_f32_16x16x32_bf16 v[92:95], v[154:157], v[202:205], v[92:95]
	v_mfma_f32_16x16x32_bf16 v[76:79], v[154:157], v[210:213], v[76:79]
	v_mfma_f32_16x16x32_bf16 v[76:79], v[150:153], v[206:209], v[76:79]
	v_mfma_f32_16x16x32_bf16 v[68:71], v[158:161], v[206:209], v[68:71]
	v_mfma_f32_16x16x32_bf16 v[68:71], v[162:165], v[210:213], v[68:71]
	v_mfma_f32_16x16x32_bf16 v[84:87], v[162:165], v[202:205], v[84:87]
	v_mfma_f32_16x16x32_bf16 v[84:87], v[158:161], v[198:201], v[84:87]
	v_mfma_f32_16x16x32_bf16 v[100:103], v[158:161], v[190:193], v[100:103]
	v_mfma_f32_16x16x32_bf16 v[100:103], v[162:165], v[194:197], v[100:103]
	v_mfma_f32_16x16x32_bf16 v[116:119], v[162:165], v[186:189], v[116:119]
	v_mfma_f32_16x16x32_bf16 v[116:119], v[158:161], v[182:185], v[116:119]
	v_mfma_f32_16x16x32_bf16 v[120:123], v[166:169], v[182:185], v[120:123]
	v_mfma_f32_16x16x32_bf16 v[120:123], v[170:173], v[186:189], v[120:123]
	v_mfma_f32_16x16x32_bf16 v[104:107], v[170:173], v[194:197], v[104:107]
	v_mfma_f32_16x16x32_bf16 v[104:107], v[166:169], v[190:193], v[104:107]
	v_mfma_f32_16x16x32_bf16 v[88:91], v[166:169], v[198:201], v[88:91]
	v_mfma_f32_16x16x32_bf16 v[88:91], v[170:173], v[202:205], v[88:91]
	v_mfma_f32_16x16x32_bf16 v[72:75], v[170:173], v[210:213], v[72:75]
	v_mfma_f32_16x16x32_bf16 v[72:75], v[166:169], v[206:209], v[72:75]
	v_mfma_f32_16x16x32_bf16 v[64:67], v[174:177], v[206:209], v[64:67]
	v_mfma_f32_16x16x32_bf16 v[64:67], v[178:181], v[210:213], v[64:67]
	v_mfma_f32_16x16x32_bf16 v[80:83], v[178:181], v[202:205], v[80:83]
	v_mfma_f32_16x16x32_bf16 v[80:83], v[174:177], v[198:201], v[80:83]
	v_mfma_f32_16x16x32_bf16 v[96:99], v[174:177], v[190:193], v[96:99]
	v_mfma_f32_16x16x32_bf16 v[96:99], v[178:181], v[194:197], v[96:99]
	v_mfma_f32_16x16x32_bf16 v[112:115], v[178:181], v[186:189], v[112:115]
	v_mfma_f32_16x16x32_bf16 v[112:115], v[174:177], v[182:185], v[112:115]
	s_barrier
	s_setprio 0
	s_add_i32 s52, s82, s56
	v_lshl_add_u64 v[214:215], v[214:215], 0, s[10:11]
	s_mov_b32 m0, s52
	ds_read_b128 v[182:185], v149 offset:49152
	ds_read_b128 v[186:189], v149 offset:50176
	ds_read_b128 v[190:193], v149 offset:51200
	ds_read_b128 v[194:197], v149 offset:52224
	ds_read_b128 v[198:201], v149 offset:53248
	ds_read_b128 v[202:205], v149 offset:54272
	ds_read_b128 v[206:209], v149 offset:55296
	ds_read_b128 v[210:213], v149 offset:56320
	global_load_lds_dwordx4 v[214:215], off
	s_add_i32 m0, s52, 0x2000
	s_add_u32 s50, s50, 0x40080
	v_lshl_add_u64 v[214:215], v[216:217], 0, s[10:11]
	s_addc_u32 s51, s51, 0
	s_add_i32 s52, s85, s56
	global_load_lds_dwordx4 v[214:215], off
	v_lshl_add_u64 v[214:215], s[50:51], 0, v[132:133]
	s_mov_b32 m0, s52
	s_nop 0
	global_load_lds_dwordx4 v[214:215], off
	v_lshl_add_u64 v[214:215], s[50:51], 0, v[128:129]
	s_add_i32 m0, s52, 0x2000
	s_nop 0
	global_load_lds_dwordx4 v[214:215], off
	v_lshl_add_u64 v[214:215], v[218:219], 0, s[10:11]
	s_mov_b32 m0, s69
	s_nop 0
	global_load_lds_dwordx4 v[214:215], off
	v_lshl_add_u64 v[214:215], v[220:221], 0, s[10:11]
	s_mov_b32 m0, s70
	s_nop 0
	global_load_lds_dwordx4 v[214:215], off
	s_waitcnt vmcnt(8)
	s_waitcnt lgkmcnt(0)
	s_setprio 1
	s_barrier
	v_mfma_f32_16x16x32_bf16 v[60:63], v[150:153], v[182:185], v[60:63]
	v_mfma_f32_16x16x32_bf16 v[60:63], v[154:157], v[186:189], v[60:63]
	v_mfma_f32_16x16x32_bf16 v[44:47], v[154:157], v[194:197], v[44:47]
	v_mfma_f32_16x16x32_bf16 v[44:47], v[150:153], v[190:193], v[44:47]
	v_mfma_f32_16x16x32_bf16 v[28:31], v[150:153], v[198:201], v[28:31]
	v_mfma_f32_16x16x32_bf16 v[28:31], v[154:157], v[202:205], v[28:31]
	v_mfma_f32_16x16x32_bf16 v[12:15], v[154:157], v[210:213], v[12:15]
	v_mfma_f32_16x16x32_bf16 v[12:15], v[150:153], v[206:209], v[12:15]
	v_mfma_f32_16x16x32_bf16 v[4:7], v[158:161], v[206:209], v[4:7]
	v_mfma_f32_16x16x32_bf16 v[4:7], v[162:165], v[210:213], v[4:7]
	v_mfma_f32_16x16x32_bf16 v[20:23], v[162:165], v[202:205], v[20:23]
	v_mfma_f32_16x16x32_bf16 v[20:23], v[158:161], v[198:201], v[20:23]
	v_mfma_f32_16x16x32_bf16 v[36:39], v[158:161], v[190:193], v[36:39]
	v_mfma_f32_16x16x32_bf16 v[36:39], v[162:165], v[194:197], v[36:39]
	v_mfma_f32_16x16x32_bf16 v[52:55], v[162:165], v[186:189], v[52:55]
	v_mfma_f32_16x16x32_bf16 v[52:55], v[158:161], v[182:185], v[52:55]
	v_mfma_f32_16x16x32_bf16 v[56:59], v[166:169], v[182:185], v[56:59]
	v_mfma_f32_16x16x32_bf16 v[56:59], v[170:173], v[186:189], v[56:59]
	v_mfma_f32_16x16x32_bf16 v[40:43], v[170:173], v[194:197], v[40:43]
	v_mfma_f32_16x16x32_bf16 v[40:43], v[166:169], v[190:193], v[40:43]
	v_mfma_f32_16x16x32_bf16 v[24:27], v[166:169], v[198:201], v[24:27]
	v_mfma_f32_16x16x32_bf16 v[24:27], v[170:173], v[202:205], v[24:27]
	v_mfma_f32_16x16x32_bf16 v[8:11], v[170:173], v[210:213], v[8:11]
	v_mfma_f32_16x16x32_bf16 v[8:11], v[166:169], v[206:209], v[8:11]
	v_mfma_f32_16x16x32_bf16 v[0:3], v[174:177], v[206:209], v[0:3]
	v_mfma_f32_16x16x32_bf16 v[0:3], v[178:181], v[210:213], v[0:3]
	v_mfma_f32_16x16x32_bf16 v[16:19], v[178:181], v[202:205], v[16:19]
	v_mfma_f32_16x16x32_bf16 v[16:19], v[174:177], v[198:201], v[16:19]
	v_mfma_f32_16x16x32_bf16 v[32:35], v[174:177], v[190:193], v[32:35]
	v_mfma_f32_16x16x32_bf16 v[32:35], v[178:181], v[194:197], v[32:35]
	v_mfma_f32_16x16x32_bf16 v[48:51], v[178:181], v[186:189], v[48:51]
	v_mfma_f32_16x16x32_bf16 v[48:51], v[174:177], v[182:185], v[48:51]
	s_barrier
	s_setprio 0
	s_add_i32 s81, s81, 2
	s_add_u32 s48, s48, 0x100
	s_addc_u32 s49, s49, 0
	s_add_u32 s79, s79, 0x100
	s_addc_u32 s80, s80, 0
	s_cmp_gt_u32 s81, 13
.LBB0_141:
	ds_read_b128 v[150:153], v147
	ds_read_b128 v[154:157], v147 offset:1024
	ds_read_b128 v[158:161], v147 offset:2048
	ds_read_b128 v[162:165], v147 offset:3072
	ds_read_b128 v[166:169], v148
	ds_read_b128 v[170:173], v148 offset:1024
	ds_read_b128 v[174:177], v148 offset:2048
	ds_read_b128 v[178:181], v148 offset:3072
	s_add_u32 s50, s48, 0xfffc0080
	s_addc_u32 s51, s49, -1
	s_cmp_eq_u32 s81, 12
	s_cselect_b32 s53, s37, s51
	s_cselect_b32 s52, s77, s50
	s_cselect_b32 s51, s39, s80
	s_cselect_b32 s50, s78, s79
	v_lshl_add_u64 v[214:215], s[48:49], 0, v[136:137]
	s_add_i32 m0, s47, 0xc000
	ds_read_b128 v[182:185], v149
	ds_read_b128 v[186:189], v149 offset:1024
	ds_read_b128 v[190:193], v149 offset:2048
	ds_read_b128 v[194:197], v149 offset:3072
	ds_read_b128 v[198:201], v149 offset:4096
	ds_read_b128 v[202:205], v149 offset:5120
	ds_read_b128 v[206:209], v149 offset:6144
	ds_read_b128 v[210:213], v149 offset:7168
	global_load_lds_dwordx4 v[214:215], off
	v_lshl_add_u64 v[214:215], s[48:49], 0, v[138:139]
	s_add_i32 m0, s47, 0xe000
	s_nop 0
	global_load_lds_dwordx4 v[214:215], off
	s_waitcnt vmcnt(8)
	s_waitcnt lgkmcnt(0)
	s_setprio 1
	s_barrier
	v_mfma_f32_16x16x32_bf16 v[124:127], v[150:153], v[182:185], v[124:127]
	v_mfma_f32_16x16x32_bf16 v[124:127], v[154:157], v[186:189], v[124:127]
	v_mfma_f32_16x16x32_bf16 v[108:111], v[154:157], v[194:197], v[108:111]
	v_mfma_f32_16x16x32_bf16 v[108:111], v[150:153], v[190:193], v[108:111]
	v_mfma_f32_16x16x32_bf16 v[92:95], v[150:153], v[198:201], v[92:95]
	v_mfma_f32_16x16x32_bf16 v[92:95], v[154:157], v[202:205], v[92:95]
	v_mfma_f32_16x16x32_bf16 v[76:79], v[154:157], v[210:213], v[76:79]
	v_mfma_f32_16x16x32_bf16 v[76:79], v[150:153], v[206:209], v[76:79]
	v_mfma_f32_16x16x32_bf16 v[68:71], v[158:161], v[206:209], v[68:71]
	v_mfma_f32_16x16x32_bf16 v[68:71], v[162:165], v[210:213], v[68:71]
	v_mfma_f32_16x16x32_bf16 v[84:87], v[162:165], v[202:205], v[84:87]
	v_mfma_f32_16x16x32_bf16 v[84:87], v[158:161], v[198:201], v[84:87]
	v_mfma_f32_16x16x32_bf16 v[100:103], v[158:161], v[190:193], v[100:103]
	v_mfma_f32_16x16x32_bf16 v[100:103], v[162:165], v[194:197], v[100:103]
	v_mfma_f32_16x16x32_bf16 v[116:119], v[162:165], v[186:189], v[116:119]
	v_mfma_f32_16x16x32_bf16 v[116:119], v[158:161], v[182:185], v[116:119]
	v_mfma_f32_16x16x32_bf16 v[120:123], v[166:169], v[182:185], v[120:123]
	v_mfma_f32_16x16x32_bf16 v[120:123], v[170:173], v[186:189], v[120:123]
	v_mfma_f32_16x16x32_bf16 v[104:107], v[170:173], v[194:197], v[104:107]
	v_mfma_f32_16x16x32_bf16 v[104:107], v[166:169], v[190:193], v[104:107]
	v_mfma_f32_16x16x32_bf16 v[88:91], v[166:169], v[198:201], v[88:91]
	v_mfma_f32_16x16x32_bf16 v[88:91], v[170:173], v[202:205], v[88:91]
	v_mfma_f32_16x16x32_bf16 v[72:75], v[170:173], v[210:213], v[72:75]
	v_mfma_f32_16x16x32_bf16 v[72:75], v[166:169], v[206:209], v[72:75]
	v_mfma_f32_16x16x32_bf16 v[64:67], v[174:177], v[206:209], v[64:67]
	v_mfma_f32_16x16x32_bf16 v[64:67], v[178:181], v[210:213], v[64:67]
	v_mfma_f32_16x16x32_bf16 v[80:83], v[178:181], v[202:205], v[80:83]
	v_mfma_f32_16x16x32_bf16 v[80:83], v[174:177], v[198:201], v[80:83]
	v_mfma_f32_16x16x32_bf16 v[96:99], v[174:177], v[190:193], v[96:99]
	v_mfma_f32_16x16x32_bf16 v[96:99], v[178:181], v[194:197], v[96:99]
	v_mfma_f32_16x16x32_bf16 v[112:115], v[178:181], v[186:189], v[112:115]
	v_mfma_f32_16x16x32_bf16 v[112:115], v[174:177], v[182:185], v[112:115]
	s_barrier
	s_setprio 0
	s_add_i32 s82, s73, s56
	v_lshl_add_u64 v[214:215], s[50:51], 0, v[132:133]
	s_mov_b32 m0, s82
	ds_read_b128 v[182:185], v149 offset:16384
	ds_read_b128 v[186:189], v149 offset:17408
	ds_read_b128 v[190:193], v149 offset:18432
	ds_read_b128 v[194:197], v149 offset:19456
	ds_read_b128 v[198:201], v149 offset:20480
	ds_read_b128 v[202:205], v149 offset:21504
	ds_read_b128 v[206:209], v149 offset:22528
	ds_read_b128 v[210:213], v149 offset:23552
	global_load_lds_dwordx4 v[214:215], off
	s_add_i32 m0, s82, 0x2000
	s_add_u32 s88, s50, 0x40000
	v_lshl_add_u64 v[216:217], s[50:51], 0, v[128:129]
	s_addc_u32 s89, s51, 0
	s_add_i32 s82, s74, s56
	global_load_lds_dwordx4 v[216:217], off
	v_lshl_add_u64 v[218:219], s[88:89], 0, v[132:133]
	s_mov_b32 m0, s82
	v_lshl_add_u64 v[220:221], s[52:53], 0, v[130:131]
	global_load_lds_dwordx4 v[218:219], off
	v_lshl_add_u64 v[218:219], s[88:89], 0, v[128:129]
	s_add_i32 m0, s82, 0x2000
	s_nop 0
	global_load_lds_dwordx4 v[218:219], off
	v_lshl_add_u64 v[218:219], s[52:53], 0, v[134:135]
	s_mov_b32 m0, s47
	s_nop 0
	global_load_lds_dwordx4 v[218:219], off
	s_mov_b32 m0, s59
	s_nop 0
	global_load_lds_dwordx4 v[220:221], off
	s_waitcnt vmcnt(8)
	s_waitcnt lgkmcnt(0)
	s_setprio 1
	s_barrier
	v_mfma_f32_16x16x32_bf16 v[60:63], v[150:153], v[182:185], v[60:63]
	v_mfma_f32_16x16x32_bf16 v[60:63], v[154:157], v[186:189], v[60:63]
	v_mfma_f32_16x16x32_bf16 v[44:47], v[154:157], v[194:197], v[44:47]
	v_mfma_f32_16x16x32_bf16 v[44:47], v[150:153], v[190:193], v[44:47]
	v_mfma_f32_16x16x32_bf16 v[28:31], v[150:153], v[198:201], v[28:31]
	v_mfma_f32_16x16x32_bf16 v[28:31], v[154:157], v[202:205], v[28:31]
	v_mfma_f32_16x16x32_bf16 v[12:15], v[154:157], v[210:213], v[12:15]
	v_mfma_f32_16x16x32_bf16 v[12:15], v[150:153], v[206:209], v[12:15]
	v_mfma_f32_16x16x32_bf16 v[4:7], v[158:161], v[206:209], v[4:7]
	v_mfma_f32_16x16x32_bf16 v[4:7], v[162:165], v[210:213], v[4:7]
	v_mfma_f32_16x16x32_bf16 v[20:23], v[162:165], v[202:205], v[20:23]
	v_mfma_f32_16x16x32_bf16 v[20:23], v[158:161], v[198:201], v[20:23]
	v_mfma_f32_16x16x32_bf16 v[36:39], v[158:161], v[190:193], v[36:39]
	v_mfma_f32_16x16x32_bf16 v[36:39], v[162:165], v[194:197], v[36:39]
	v_mfma_f32_16x16x32_bf16 v[52:55], v[162:165], v[186:189], v[52:55]
	v_mfma_f32_16x16x32_bf16 v[52:55], v[158:161], v[182:185], v[52:55]
	v_mfma_f32_16x16x32_bf16 v[56:59], v[166:169], v[182:185], v[56:59]
	v_mfma_f32_16x16x32_bf16 v[56:59], v[170:173], v[186:189], v[56:59]
	v_mfma_f32_16x16x32_bf16 v[40:43], v[170:173], v[194:197], v[40:43]
	v_mfma_f32_16x16x32_bf16 v[40:43], v[166:169], v[190:193], v[40:43]
	v_mfma_f32_16x16x32_bf16 v[24:27], v[166:169], v[198:201], v[24:27]
	v_mfma_f32_16x16x32_bf16 v[24:27], v[170:173], v[202:205], v[24:27]
	v_mfma_f32_16x16x32_bf16 v[8:11], v[170:173], v[210:213], v[8:11]
	v_mfma_f32_16x16x32_bf16 v[8:11], v[166:169], v[206:209], v[8:11]
	v_mfma_f32_16x16x32_bf16 v[0:3], v[174:177], v[206:209], v[0:3]
	v_mfma_f32_16x16x32_bf16 v[0:3], v[178:181], v[210:213], v[0:3]
	v_mfma_f32_16x16x32_bf16 v[16:19], v[178:181], v[202:205], v[16:19]
	v_mfma_f32_16x16x32_bf16 v[16:19], v[174:177], v[198:201], v[16:19]
	v_mfma_f32_16x16x32_bf16 v[32:35], v[174:177], v[190:193], v[32:35]
	v_mfma_f32_16x16x32_bf16 v[32:35], v[178:181], v[194:197], v[32:35]
	v_mfma_f32_16x16x32_bf16 v[48:51], v[178:181], v[186:189], v[48:51]
	v_mfma_f32_16x16x32_bf16 v[48:51], v[174:177], v[182:185], v[48:51]
	s_barrier
	s_setprio 0
	s_add_i32 s82, 0, 0x18000
	s_add_i32 s85, 0, 0x1c000
	v_add_u32_e32 v162, s82, v145
	v_add_u32_e32 v178, s85, v145
	ds_read_b128 v[150:153], v162
	ds_read_b128 v[154:157], v162 offset:1024
	ds_read_b128 v[158:161], v162 offset:2048
	ds_read_b128 v[162:165], v162 offset:3072
	ds_read_b128 v[166:169], v178
	ds_read_b128 v[170:173], v178 offset:1024
	ds_read_b128 v[174:177], v178 offset:2048
	ds_read_b128 v[178:181], v178 offset:3072
	s_add_u32 s52, s52, 0x40000
	s_addc_u32 s53, s53, 0
	s_mov_b32 m0, s66
	v_lshl_add_u64 v[222:223], s[52:53], 0, v[134:135]
	ds_read_b128 v[182:185], v149 offset:32768
	ds_read_b128 v[186:189], v149 offset:33792
	ds_read_b128 v[190:193], v149 offset:34816
	ds_read_b128 v[194:197], v149 offset:35840
	ds_read_b128 v[198:201], v149 offset:36864
	ds_read_b128 v[202:205], v149 offset:37888
	ds_read_b128 v[206:209], v149 offset:38912
	ds_read_b128 v[210:213], v149 offset:39936
	global_load_lds_dwordx4 v[222:223], off
	v_lshl_add_u64 v[222:223], s[52:53], 0, v[130:131]
	s_mov_b32 m0, s67
	s_nop 0
	global_load_lds_dwordx4 v[222:223], off
	s_waitcnt vmcnt(8)
	s_waitcnt lgkmcnt(0)
	s_setprio 1
	s_barrier
	v_mfma_f32_16x16x32_bf16 v[124:127], v[150:153], v[182:185], v[124:127]
	v_mfma_f32_16x16x32_bf16 v[124:127], v[154:157], v[186:189], v[124:127]
	v_mfma_f32_16x16x32_bf16 v[108:111], v[154:157], v[194:197], v[108:111]
	v_mfma_f32_16x16x32_bf16 v[108:111], v[150:153], v[190:193], v[108:111]
	v_mfma_f32_16x16x32_bf16 v[92:95], v[150:153], v[198:201], v[92:95]
	v_mfma_f32_16x16x32_bf16 v[92:95], v[154:157], v[202:205], v[92:95]
	v_mfma_f32_16x16x32_bf16 v[76:79], v[154:157], v[210:213], v[76:79]
	v_mfma_f32_16x16x32_bf16 v[76:79], v[150:153], v[206:209], v[76:79]
	v_mfma_f32_16x16x32_bf16 v[68:71], v[158:161], v[206:209], v[68:71]
	v_mfma_f32_16x16x32_bf16 v[68:71], v[162:165], v[210:213], v[68:71]
	v_mfma_f32_16x16x32_bf16 v[84:87], v[162:165], v[202:205], v[84:87]
	v_mfma_f32_16x16x32_bf16 v[84:87], v[158:161], v[198:201], v[84:87]
	v_mfma_f32_16x16x32_bf16 v[100:103], v[158:161], v[190:193], v[100:103]
	v_mfma_f32_16x16x32_bf16 v[100:103], v[162:165], v[194:197], v[100:103]
	v_mfma_f32_16x16x32_bf16 v[116:119], v[162:165], v[186:189], v[116:119]
	v_mfma_f32_16x16x32_bf16 v[116:119], v[158:161], v[182:185], v[116:119]
	v_mfma_f32_16x16x32_bf16 v[120:123], v[166:169], v[182:185], v[120:123]
	v_mfma_f32_16x16x32_bf16 v[120:123], v[170:173], v[186:189], v[120:123]
	v_mfma_f32_16x16x32_bf16 v[104:107], v[170:173], v[194:197], v[104:107]
	v_mfma_f32_16x16x32_bf16 v[104:107], v[166:169], v[190:193], v[104:107]
	v_mfma_f32_16x16x32_bf16 v[88:91], v[166:169], v[198:201], v[88:91]
	v_mfma_f32_16x16x32_bf16 v[88:91], v[170:173], v[202:205], v[88:91]
	v_mfma_f32_16x16x32_bf16 v[72:75], v[170:173], v[210:213], v[72:75]
	v_mfma_f32_16x16x32_bf16 v[72:75], v[166:169], v[206:209], v[72:75]
	v_mfma_f32_16x16x32_bf16 v[64:67], v[174:177], v[206:209], v[64:67]
	v_mfma_f32_16x16x32_bf16 v[64:67], v[178:181], v[210:213], v[64:67]
	v_mfma_f32_16x16x32_bf16 v[80:83], v[178:181], v[202:205], v[80:83]
	v_mfma_f32_16x16x32_bf16 v[80:83], v[174:177], v[198:201], v[80:83]
	v_mfma_f32_16x16x32_bf16 v[96:99], v[174:177], v[190:193], v[96:99]
	v_mfma_f32_16x16x32_bf16 v[96:99], v[178:181], v[194:197], v[96:99]
	v_mfma_f32_16x16x32_bf16 v[112:115], v[178:181], v[186:189], v[112:115]
	v_mfma_f32_16x16x32_bf16 v[112:115], v[174:177], v[182:185], v[112:115]
	s_barrier
	s_setprio 0
	s_add_i32 s52, s82, s56
	v_lshl_add_u64 v[214:215], v[214:215], 0, s[10:11]
	s_mov_b32 m0, s52
	ds_read_b128 v[182:185], v149 offset:49152
	ds_read_b128 v[186:189], v149 offset:50176
	ds_read_b128 v[190:193], v149 offset:51200
	ds_read_b128 v[194:197], v149 offset:52224
	ds_read_b128 v[198:201], v149 offset:53248
	ds_read_b128 v[202:205], v149 offset:54272
	ds_read_b128 v[206:209], v149 offset:55296
	ds_read_b128 v[210:213], v149 offset:56320
	global_load_lds_dwordx4 v[214:215], off
	s_add_i32 m0, s52, 0x2000
	s_add_u32 s50, s50, 0x40080
	v_lshl_add_u64 v[214:215], v[216:217], 0, s[10:11]
	s_addc_u32 s51, s51, 0
	s_add_i32 s52, s85, s56
	global_load_lds_dwordx4 v[214:215], off
	v_lshl_add_u64 v[214:215], s[50:51], 0, v[132:133]
	s_mov_b32 m0, s52
	s_nop 0
	global_load_lds_dwordx4 v[214:215], off
	v_lshl_add_u64 v[214:215], s[50:51], 0, v[128:129]
	s_add_i32 m0, s52, 0x2000
	s_nop 0
	global_load_lds_dwordx4 v[214:215], off
	v_lshl_add_u64 v[214:215], v[218:219], 0, s[10:11]
	s_mov_b32 m0, s69
	s_nop 0
	global_load_lds_dwordx4 v[214:215], off
	v_lshl_add_u64 v[214:215], v[220:221], 0, s[10:11]
	s_mov_b32 m0, s70
	s_nop 0
	global_load_lds_dwordx4 v[214:215], off
	s_waitcnt vmcnt(8)
	s_waitcnt lgkmcnt(0)
	s_setprio 1
	s_barrier
	v_mfma_f32_16x16x32_bf16 v[60:63], v[150:153], v[182:185], v[60:63]
	v_mfma_f32_16x16x32_bf16 v[60:63], v[154:157], v[186:189], v[60:63]
	v_mfma_f32_16x16x32_bf16 v[44:47], v[154:157], v[194:197], v[44:47]
	v_mfma_f32_16x16x32_bf16 v[44:47], v[150:153], v[190:193], v[44:47]
	v_mfma_f32_16x16x32_bf16 v[28:31], v[150:153], v[198:201], v[28:31]
	v_mfma_f32_16x16x32_bf16 v[28:31], v[154:157], v[202:205], v[28:31]
	v_mfma_f32_16x16x32_bf16 v[12:15], v[154:157], v[210:213], v[12:15]
	v_mfma_f32_16x16x32_bf16 v[12:15], v[150:153], v[206:209], v[12:15]
	v_mfma_f32_16x16x32_bf16 v[4:7], v[158:161], v[206:209], v[4:7]
	v_mfma_f32_16x16x32_bf16 v[4:7], v[162:165], v[210:213], v[4:7]
	v_mfma_f32_16x16x32_bf16 v[20:23], v[162:165], v[202:205], v[20:23]
	v_mfma_f32_16x16x32_bf16 v[20:23], v[158:161], v[198:201], v[20:23]
	v_mfma_f32_16x16x32_bf16 v[36:39], v[158:161], v[190:193], v[36:39]
	v_mfma_f32_16x16x32_bf16 v[36:39], v[162:165], v[194:197], v[36:39]
	v_mfma_f32_16x16x32_bf16 v[52:55], v[162:165], v[186:189], v[52:55]
	v_mfma_f32_16x16x32_bf16 v[52:55], v[158:161], v[182:185], v[52:55]
	v_mfma_f32_16x16x32_bf16 v[56:59], v[166:169], v[182:185], v[56:59]
	v_mfma_f32_16x16x32_bf16 v[56:59], v[170:173], v[186:189], v[56:59]
	v_mfma_f32_16x16x32_bf16 v[40:43], v[170:173], v[194:197], v[40:43]
	v_mfma_f32_16x16x32_bf16 v[40:43], v[166:169], v[190:193], v[40:43]
	v_mfma_f32_16x16x32_bf16 v[24:27], v[166:169], v[198:201], v[24:27]
	v_mfma_f32_16x16x32_bf16 v[24:27], v[170:173], v[202:205], v[24:27]
	v_mfma_f32_16x16x32_bf16 v[8:11], v[170:173], v[210:213], v[8:11]
	v_mfma_f32_16x16x32_bf16 v[8:11], v[166:169], v[206:209], v[8:11]
	v_mfma_f32_16x16x32_bf16 v[0:3], v[174:177], v[206:209], v[0:3]
	v_mfma_f32_16x16x32_bf16 v[0:3], v[178:181], v[210:213], v[0:3]
	v_mfma_f32_16x16x32_bf16 v[16:19], v[178:181], v[202:205], v[16:19]
	v_mfma_f32_16x16x32_bf16 v[16:19], v[174:177], v[198:201], v[16:19]
	v_mfma_f32_16x16x32_bf16 v[32:35], v[174:177], v[190:193], v[32:35]
	v_mfma_f32_16x16x32_bf16 v[32:35], v[178:181], v[194:197], v[32:35]
	v_mfma_f32_16x16x32_bf16 v[48:51], v[178:181], v[186:189], v[48:51]
	v_mfma_f32_16x16x32_bf16 v[48:51], v[174:177], v[182:185], v[48:51]
	s_barrier
	s_setprio 0
	s_add_i32 s81, s81, 2
	s_add_u32 s48, s48, 0x100
	s_addc_u32 s49, s49, 0
	s_add_u32 s79, s79, 0x100
	s_addc_u32 s80, s80, 0
	s_cmp_gt_u32 s81, 13
	s_cbranch_scc0 .LBB0_141
	s_and_b64 vcc, exec, s[26:27]
	s_cbranch_vccz .LBB0_144
	s_barrier

.LBB0_220:
	s_add_u32 s95, s52, 0x100
	s_addc_u32 s96, s53, 0
	s_mov_b32 s97, -2
	ds_read_b128 v[88:91], v233
	ds_read_b128 v[92:95], v233 offset:1024
	ds_read_b128 v[112:115], v233 offset:2048
	ds_read_b128 v[116:119], v233 offset:3072
	ds_read_b128 v[132:135], v234
	ds_read_b128 v[136:139], v234 offset:1024
	ds_read_b128 v[152:155], v234 offset:2048
	ds_read_b128 v[156:159], v234 offset:3072
	s_add_u32 s52, s50, 0x100
	s_addc_u32 s53, s51, 0
	s_cmp_eq_u32 s97, 40
	s_cselect_b32 s57, s9, s53
	s_cselect_b32 s56, s8, s52
	s_cselect_b32 s55, s41, s96
	s_cselect_b32 s54, s40, s95
	v_lshl_add_u64 v[216:217], s[50:51], 0, v[196:197]
	s_add_i32 m0, s67, 0xc000
	ds_read_b128 v[160:163], v235
	ds_read_b128 v[164:167], v235 offset:1024
	ds_read_b128 v[168:171], v235 offset:2048
	ds_read_b128 v[172:175], v235 offset:3072
	ds_read_b128 v[176:179], v235 offset:4096
	ds_read_b128 v[180:183], v235 offset:5120
	ds_read_b128 v[208:211], v235 offset:6144
	ds_read_b128 v[212:215], v235 offset:7168
	global_load_lds_dwordx4 v[216:217], off
	v_lshl_add_u64 v[216:217], s[50:51], 0, v[198:199]
	s_add_i32 m0, s67, 0xe000
	s_nop 0
	global_load_lds_dwordx4 v[216:217], off
	s_waitcnt vmcnt(8)
	s_waitcnt lgkmcnt(0)
	s_setprio 1
	s_barrier
	v_mfma_f32_16x16x32_bf16 v[148:151], v[88:91], v[160:163], 0
	v_mfma_f32_16x16x32_bf16 v[148:151], v[92:95], v[164:167], v[148:151]
	v_mfma_f32_16x16x32_bf16 v[124:127], v[92:95], v[172:175], 0
	v_mfma_f32_16x16x32_bf16 v[124:127], v[88:91], v[168:171], v[124:127]
	v_mfma_f32_16x16x32_bf16 v[100:103], v[88:91], v[176:179], 0
	v_mfma_f32_16x16x32_bf16 v[100:103], v[92:95], v[180:183], v[100:103]
	v_mfma_f32_16x16x32_bf16 v[76:79], v[92:95], v[212:215], 0
	v_mfma_f32_16x16x32_bf16 v[76:79], v[88:91], v[208:211], v[76:79]
	v_mfma_f32_16x16x32_bf16 v[72:75], v[112:115], v[208:211], 0
	v_mfma_f32_16x16x32_bf16 v[72:75], v[116:119], v[212:215], v[72:75]
	v_mfma_f32_16x16x32_bf16 v[96:99], v[116:119], v[180:183], 0
	v_mfma_f32_16x16x32_bf16 v[96:99], v[112:115], v[176:179], v[96:99]
	v_mfma_f32_16x16x32_bf16 v[120:123], v[112:115], v[168:171], 0
	v_mfma_f32_16x16x32_bf16 v[120:123], v[116:119], v[172:175], v[120:123]
	v_mfma_f32_16x16x32_bf16 v[144:147], v[116:119], v[164:167], 0
	v_mfma_f32_16x16x32_bf16 v[144:147], v[112:115], v[160:163], v[144:147]
	v_mfma_f32_16x16x32_bf16 v[140:143], v[132:135], v[160:163], 0
	v_mfma_f32_16x16x32_bf16 v[140:143], v[136:139], v[164:167], v[140:143]
	v_mfma_f32_16x16x32_bf16 v[108:111], v[136:139], v[172:175], 0
	v_mfma_f32_16x16x32_bf16 v[108:111], v[132:135], v[168:171], v[108:111]
	v_mfma_f32_16x16x32_bf16 v[84:87], v[132:135], v[176:179], 0
	v_mfma_f32_16x16x32_bf16 v[84:87], v[136:139], v[180:183], v[84:87]
	v_mfma_f32_16x16x32_bf16 v[68:71], v[136:139], v[212:215], 0
	v_mfma_f32_16x16x32_bf16 v[68:71], v[132:135], v[208:211], v[68:71]
	v_mfma_f32_16x16x32_bf16 v[64:67], v[152:155], v[208:211], 0
	v_mfma_f32_16x16x32_bf16 v[64:67], v[156:159], v[212:215], v[64:67]
	v_mfma_f32_16x16x32_bf16 v[80:83], v[156:159], v[180:183], 0
	v_mfma_f32_16x16x32_bf16 v[80:83], v[152:155], v[176:179], v[80:83]
	v_mfma_f32_16x16x32_bf16 v[104:107], v[152:155], v[168:171], 0
	v_mfma_f32_16x16x32_bf16 v[104:107], v[156:159], v[172:175], v[104:107]
	v_mfma_f32_16x16x32_bf16 v[128:131], v[156:159], v[164:167], 0
	v_mfma_f32_16x16x32_bf16 v[128:131], v[152:155], v[160:163], v[128:131]
	s_barrier
	s_setprio 0
	s_add_i32 s50, s82, s66
	v_lshl_add_u64 v[216:217], s[54:55], 0, v[186:187]
	s_mov_b32 m0, s50
	ds_read_b128 v[160:163], v235 offset:16384
	ds_read_b128 v[164:167], v235 offset:17408
	ds_read_b128 v[168:171], v235 offset:18432
	ds_read_b128 v[172:175], v235 offset:19456
	ds_read_b128 v[176:179], v235 offset:20480
	ds_read_b128 v[180:183], v235 offset:21504
	ds_read_b128 v[208:211], v235 offset:22528
	ds_read_b128 v[212:215], v235 offset:23552
	global_load_lds_dwordx4 v[216:217], off
	s_add_i32 m0, s50, 0x2000
	s_add_u32 s50, s54, 0xb0000
	v_lshl_add_u64 v[218:219], s[54:55], 0, v[190:191]
	s_addc_u32 s51, s55, 0
	s_add_i32 vcc_lo, s85, s66
	global_load_lds_dwordx4 v[218:219], off
	v_lshl_add_u64 v[220:221], s[50:51], 0, v[186:187]
	s_mov_b32 m0, vcc_lo
	v_lshl_add_u64 v[222:223], s[56:57], 0, v[188:189]
	global_load_lds_dwordx4 v[220:221], off
	v_lshl_add_u64 v[220:221], s[50:51], 0, v[190:191]
	s_add_i32 m0, vcc_lo, 0x2000
	s_nop 0
	global_load_lds_dwordx4 v[220:221], off
	v_lshl_add_u64 v[220:221], s[56:57], 0, v[184:185]
	s_mov_b32 m0, s67
	s_nop 0
	global_load_lds_dwordx4 v[220:221], off
	s_mov_b32 m0, s68
	s_nop 0
	global_load_lds_dwordx4 v[222:223], off
	s_waitcnt vmcnt(8)
	s_waitcnt lgkmcnt(0)
	s_setprio 1
	s_barrier
	v_mfma_f32_16x16x32_bf16 v[60:63], v[88:91], v[160:163], 0
	v_mfma_f32_16x16x32_bf16 v[60:63], v[92:95], v[164:167], v[60:63]
	v_mfma_f32_16x16x32_bf16 v[44:47], v[92:95], v[172:175], 0
	v_mfma_f32_16x16x32_bf16 v[44:47], v[88:91], v[168:171], v[44:47]
	v_mfma_f32_16x16x32_bf16 v[28:31], v[88:91], v[176:179], 0
	v_mfma_f32_16x16x32_bf16 v[28:31], v[92:95], v[180:183], v[28:31]
	v_mfma_f32_16x16x32_bf16 v[12:15], v[92:95], v[212:215], 0
	v_mfma_f32_16x16x32_bf16 v[12:15], v[88:91], v[208:211], v[12:15]
	v_mfma_f32_16x16x32_bf16 v[8:11], v[112:115], v[208:211], 0
	v_mfma_f32_16x16x32_bf16 v[8:11], v[116:119], v[212:215], v[8:11]
	v_mfma_f32_16x16x32_bf16 v[24:27], v[116:119], v[180:183], 0
	v_mfma_f32_16x16x32_bf16 v[24:27], v[112:115], v[176:179], v[24:27]
	v_mfma_f32_16x16x32_bf16 v[40:43], v[112:115], v[168:171], 0
	v_mfma_f32_16x16x32_bf16 v[40:43], v[116:119], v[172:175], v[40:43]
	v_mfma_f32_16x16x32_bf16 v[56:59], v[116:119], v[164:167], 0
	v_mfma_f32_16x16x32_bf16 v[56:59], v[112:115], v[160:163], v[56:59]
	v_mfma_f32_16x16x32_bf16 v[52:55], v[132:135], v[160:163], 0
	v_mfma_f32_16x16x32_bf16 v[52:55], v[136:139], v[164:167], v[52:55]
	v_mfma_f32_16x16x32_bf16 v[36:39], v[136:139], v[172:175], 0
	v_mfma_f32_16x16x32_bf16 v[36:39], v[132:135], v[168:171], v[36:39]
	v_mfma_f32_16x16x32_bf16 v[20:23], v[132:135], v[176:179], 0
	v_mfma_f32_16x16x32_bf16 v[20:23], v[136:139], v[180:183], v[20:23]
	v_mfma_f32_16x16x32_bf16 v[4:7], v[136:139], v[212:215], 0
	v_mfma_f32_16x16x32_bf16 v[4:7], v[132:135], v[208:211], v[4:7]
	v_mfma_f32_16x16x32_bf16 v[0:3], v[152:155], v[208:211], 0
	v_mfma_f32_16x16x32_bf16 v[0:3], v[156:159], v[212:215], v[0:3]
	v_mfma_f32_16x16x32_bf16 v[16:19], v[156:159], v[180:183], 0
	v_mfma_f32_16x16x32_bf16 v[16:19], v[152:155], v[176:179], v[16:19]
	v_mfma_f32_16x16x32_bf16 v[32:35], v[152:155], v[168:171], 0
	v_mfma_f32_16x16x32_bf16 v[32:35], v[156:159], v[172:175], v[32:35]
	v_mfma_f32_16x16x32_bf16 v[48:51], v[156:159], v[164:167], 0
	v_mfma_f32_16x16x32_bf16 v[48:51], v[152:155], v[160:163], v[48:51]
	s_barrier
	s_setprio 0
	s_add_i32 vcc_lo, 0, 0x18000
	s_add_i32 vcc_hi, 0, 0x1c000
	v_add_u32_e32 v116, vcc_lo, v230
	v_add_u32_e32 v156, vcc_hi, v230
	ds_read_b128 v[88:91], v116
	ds_read_b128 v[92:95], v116 offset:1024
	ds_read_b128 v[112:115], v116 offset:2048
	ds_read_b128 v[116:119], v116 offset:3072
	ds_read_b128 v[132:135], v156
	ds_read_b128 v[136:139], v156 offset:1024
	ds_read_b128 v[152:155], v156 offset:2048
	ds_read_b128 v[156:159], v156 offset:3072
	s_add_u32 s50, s56, 0xb0000
	s_addc_u32 s51, s57, 0
	s_mov_b32 m0, s69
	v_lshl_add_u64 v[224:225], s[50:51], 0, v[184:185]
	ds_read_b128 v[160:163], v235 offset:32768
	ds_read_b128 v[164:167], v235 offset:33792
	ds_read_b128 v[168:171], v235 offset:34816
	ds_read_b128 v[172:175], v235 offset:35840
	ds_read_b128 v[176:179], v235 offset:36864
	ds_read_b128 v[180:183], v235 offset:37888
	ds_read_b128 v[208:211], v235 offset:38912
	ds_read_b128 v[212:215], v235 offset:39936
	global_load_lds_dwordx4 v[224:225], off
	v_lshl_add_u64 v[224:225], s[50:51], 0, v[188:189]
	s_mov_b32 m0, s70
	s_nop 0
	global_load_lds_dwordx4 v[224:225], off
	s_waitcnt vmcnt(8)
	s_waitcnt lgkmcnt(0)
	s_setprio 1
	s_barrier
	v_mfma_f32_16x16x32_bf16 v[148:151], v[88:91], v[160:163], v[148:151]
	v_mfma_f32_16x16x32_bf16 v[148:151], v[92:95], v[164:167], v[148:151]
	v_mfma_f32_16x16x32_bf16 v[124:127], v[92:95], v[172:175], v[124:127]
	v_mfma_f32_16x16x32_bf16 v[124:127], v[88:91], v[168:171], v[124:127]
	v_mfma_f32_16x16x32_bf16 v[100:103], v[88:91], v[176:179], v[100:103]
	v_mfma_f32_16x16x32_bf16 v[100:103], v[92:95], v[180:183], v[100:103]
	v_mfma_f32_16x16x32_bf16 v[76:79], v[92:95], v[212:215], v[76:79]
	v_mfma_f32_16x16x32_bf16 v[76:79], v[88:91], v[208:211], v[76:79]
	v_mfma_f32_16x16x32_bf16 v[72:75], v[112:115], v[208:211], v[72:75]
	v_mfma_f32_16x16x32_bf16 v[72:75], v[116:119], v[212:215], v[72:75]
	v_mfma_f32_16x16x32_bf16 v[96:99], v[116:119], v[180:183], v[96:99]
	v_mfma_f32_16x16x32_bf16 v[96:99], v[112:115], v[176:179], v[96:99]
	v_mfma_f32_16x16x32_bf16 v[120:123], v[112:115], v[168:171], v[120:123]
	v_mfma_f32_16x16x32_bf16 v[120:123], v[116:119], v[172:175], v[120:123]
	v_mfma_f32_16x16x32_bf16 v[144:147], v[116:119], v[164:167], v[144:147]
	v_mfma_f32_16x16x32_bf16 v[144:147], v[112:115], v[160:163], v[144:147]
	v_mfma_f32_16x16x32_bf16 v[140:143], v[132:135], v[160:163], v[140:143]
	v_mfma_f32_16x16x32_bf16 v[140:143], v[136:139], v[164:167], v[140:143]
	v_mfma_f32_16x16x32_bf16 v[108:111], v[136:139], v[172:175], v[108:111]
	v_mfma_f32_16x16x32_bf16 v[108:111], v[132:135], v[168:171], v[108:111]
	v_mfma_f32_16x16x32_bf16 v[84:87], v[132:135], v[176:179], v[84:87]
	v_mfma_f32_16x16x32_bf16 v[84:87], v[136:139], v[180:183], v[84:87]
	v_mfma_f32_16x16x32_bf16 v[68:71], v[136:139], v[212:215], v[68:71]
	v_mfma_f32_16x16x32_bf16 v[68:71], v[132:135], v[208:211], v[68:71]
	v_mfma_f32_16x16x32_bf16 v[64:67], v[152:155], v[208:211], v[64:67]
	v_mfma_f32_16x16x32_bf16 v[64:67], v[156:159], v[212:215], v[64:67]
	v_mfma_f32_16x16x32_bf16 v[80:83], v[156:159], v[180:183], v[80:83]
	v_mfma_f32_16x16x32_bf16 v[80:83], v[152:155], v[176:179], v[80:83]
	v_mfma_f32_16x16x32_bf16 v[104:107], v[152:155], v[168:171], v[104:107]
	v_mfma_f32_16x16x32_bf16 v[104:107], v[156:159], v[172:175], v[104:107]
	v_mfma_f32_16x16x32_bf16 v[128:131], v[156:159], v[164:167], v[128:131]
	v_mfma_f32_16x16x32_bf16 v[128:131], v[152:155], v[160:163], v[128:131]
	s_barrier
	s_setprio 0
	s_add_i32 s50, vcc_lo, s66
	v_lshl_add_u64 v[216:217], v[216:217], 0, s[46:47]
	s_mov_b32 m0, s50
	ds_read_b128 v[160:163], v235 offset:49152
	ds_read_b128 v[164:167], v235 offset:50176
	ds_read_b128 v[168:171], v235 offset:51200
	ds_read_b128 v[172:175], v235 offset:52224
	ds_read_b128 v[176:179], v235 offset:53248
	ds_read_b128 v[180:183], v235 offset:54272
	ds_read_b128 v[208:211], v235 offset:55296
	ds_read_b128 v[212:215], v235 offset:56320
	global_load_lds_dwordx4 v[216:217], off
	s_add_i32 m0, s50, 0x2000
	s_add_u32 s50, s54, 0xb0080
	v_lshl_add_u64 v[216:217], v[218:219], 0, s[46:47]
	s_addc_u32 s51, s55, 0
	s_add_i32 s54, vcc_hi, s66
	global_load_lds_dwordx4 v[216:217], off
	v_lshl_add_u64 v[216:217], s[50:51], 0, v[186:187]
	s_mov_b32 m0, s54
	s_nop 0
	global_load_lds_dwordx4 v[216:217], off
	v_lshl_add_u64 v[216:217], s[50:51], 0, v[190:191]
	s_add_i32 m0, s54, 0x2000
	s_nop 0
	global_load_lds_dwordx4 v[216:217], off
	v_lshl_add_u64 v[216:217], v[220:221], 0, s[46:47]
	s_mov_b32 m0, s74
	s_nop 0
	global_load_lds_dwordx4 v[216:217], off
	v_lshl_add_u64 v[216:217], v[222:223], 0, s[46:47]
	s_mov_b32 m0, s75
	s_nop 0
	global_load_lds_dwordx4 v[216:217], off
	s_waitcnt vmcnt(8)
	s_waitcnt lgkmcnt(0)
	s_setprio 1
	s_barrier
	v_mfma_f32_16x16x32_bf16 v[60:63], v[88:91], v[160:163], v[60:63]
	v_mfma_f32_16x16x32_bf16 v[60:63], v[92:95], v[164:167], v[60:63]
	v_mfma_f32_16x16x32_bf16 v[44:47], v[92:95], v[172:175], v[44:47]
	v_mfma_f32_16x16x32_bf16 v[44:47], v[88:91], v[168:171], v[44:47]
	v_mfma_f32_16x16x32_bf16 v[28:31], v[88:91], v[176:179], v[28:31]
	v_mfma_f32_16x16x32_bf16 v[28:31], v[92:95], v[180:183], v[28:31]
	v_mfma_f32_16x16x32_bf16 v[12:15], v[92:95], v[212:215], v[12:15]
	v_mfma_f32_16x16x32_bf16 v[12:15], v[88:91], v[208:211], v[12:15]
	v_mfma_f32_16x16x32_bf16 v[8:11], v[112:115], v[208:211], v[8:11]
	v_mfma_f32_16x16x32_bf16 v[8:11], v[116:119], v[212:215], v[8:11]
	v_mfma_f32_16x16x32_bf16 v[24:27], v[116:119], v[180:183], v[24:27]
	v_mfma_f32_16x16x32_bf16 v[24:27], v[112:115], v[176:179], v[24:27]
	v_mfma_f32_16x16x32_bf16 v[40:43], v[112:115], v[168:171], v[40:43]
	v_mfma_f32_16x16x32_bf16 v[40:43], v[116:119], v[172:175], v[40:43]
	v_mfma_f32_16x16x32_bf16 v[56:59], v[116:119], v[164:167], v[56:59]
	v_mfma_f32_16x16x32_bf16 v[56:59], v[112:115], v[160:163], v[56:59]
	v_mfma_f32_16x16x32_bf16 v[52:55], v[132:135], v[160:163], v[52:55]
	v_mfma_f32_16x16x32_bf16 v[52:55], v[136:139], v[164:167], v[52:55]
	v_mfma_f32_16x16x32_bf16 v[36:39], v[136:139], v[172:175], v[36:39]
	v_mfma_f32_16x16x32_bf16 v[36:39], v[132:135], v[168:171], v[36:39]
	v_mfma_f32_16x16x32_bf16 v[20:23], v[132:135], v[176:179], v[20:23]
	v_mfma_f32_16x16x32_bf16 v[20:23], v[136:139], v[180:183], v[20:23]
	v_mfma_f32_16x16x32_bf16 v[4:7], v[136:139], v[212:215], v[4:7]
	v_mfma_f32_16x16x32_bf16 v[4:7], v[132:135], v[208:211], v[4:7]
	v_mfma_f32_16x16x32_bf16 v[0:3], v[152:155], v[208:211], v[0:3]
	v_mfma_f32_16x16x32_bf16 v[0:3], v[156:159], v[212:215], v[0:3]
	v_mfma_f32_16x16x32_bf16 v[16:19], v[156:159], v[180:183], v[16:19]
	v_mfma_f32_16x16x32_bf16 v[16:19], v[152:155], v[176:179], v[16:19]
	v_mfma_f32_16x16x32_bf16 v[32:35], v[152:155], v[168:171], v[32:35]
	v_mfma_f32_16x16x32_bf16 v[32:35], v[156:159], v[172:175], v[32:35]
	v_mfma_f32_16x16x32_bf16 v[48:51], v[156:159], v[164:167], v[48:51]
	v_mfma_f32_16x16x32_bf16 v[48:51], v[152:155], v[160:163], v[48:51]
	s_barrier
	s_setprio 0
	s_add_i32 s97, s97, 2
	s_add_u32 s95, s95, 0x100
	s_addc_u32 s96, s96, 0
	s_cmp_gt_u32 s97, 41
	s_mov_b64 s[50:51], s[52:53]
.LBB0_221:
	ds_read_b128 v[88:91], v233
	ds_read_b128 v[92:95], v233 offset:1024
	ds_read_b128 v[112:115], v233 offset:2048
	ds_read_b128 v[116:119], v233 offset:3072
	ds_read_b128 v[132:135], v234
	ds_read_b128 v[136:139], v234 offset:1024
	ds_read_b128 v[152:155], v234 offset:2048
	ds_read_b128 v[156:159], v234 offset:3072
	s_add_u32 s52, s50, 0x100
	s_addc_u32 s53, s51, 0
	s_cmp_eq_u32 s97, 40
	s_cselect_b32 s57, s9, s53
	s_cselect_b32 s56, s8, s52
	s_cselect_b32 s55, s41, s96
	s_cselect_b32 s54, s40, s95
	v_lshl_add_u64 v[216:217], s[50:51], 0, v[196:197]
	s_add_i32 m0, s67, 0xc000
	ds_read_b128 v[160:163], v235
	ds_read_b128 v[164:167], v235 offset:1024
	ds_read_b128 v[168:171], v235 offset:2048
	ds_read_b128 v[172:175], v235 offset:3072
	ds_read_b128 v[176:179], v235 offset:4096
	ds_read_b128 v[180:183], v235 offset:5120
	ds_read_b128 v[208:211], v235 offset:6144
	ds_read_b128 v[212:215], v235 offset:7168
	global_load_lds_dwordx4 v[216:217], off
	v_lshl_add_u64 v[216:217], s[50:51], 0, v[198:199]
	s_add_i32 m0, s67, 0xe000
	s_nop 0
	global_load_lds_dwordx4 v[216:217], off
	s_waitcnt vmcnt(8)
	s_waitcnt lgkmcnt(0)
	s_setprio 1
	s_barrier
	v_mfma_f32_16x16x32_bf16 v[148:151], v[88:91], v[160:163], v[148:151]
	v_mfma_f32_16x16x32_bf16 v[148:151], v[92:95], v[164:167], v[148:151]
	v_mfma_f32_16x16x32_bf16 v[124:127], v[92:95], v[172:175], v[124:127]
	v_mfma_f32_16x16x32_bf16 v[124:127], v[88:91], v[168:171], v[124:127]
	v_mfma_f32_16x16x32_bf16 v[100:103], v[88:91], v[176:179], v[100:103]
	v_mfma_f32_16x16x32_bf16 v[100:103], v[92:95], v[180:183], v[100:103]
	v_mfma_f32_16x16x32_bf16 v[76:79], v[92:95], v[212:215], v[76:79]
	v_mfma_f32_16x16x32_bf16 v[76:79], v[88:91], v[208:211], v[76:79]
	v_mfma_f32_16x16x32_bf16 v[72:75], v[112:115], v[208:211], v[72:75]
	v_mfma_f32_16x16x32_bf16 v[72:75], v[116:119], v[212:215], v[72:75]
	v_mfma_f32_16x16x32_bf16 v[96:99], v[116:119], v[180:183], v[96:99]
	v_mfma_f32_16x16x32_bf16 v[96:99], v[112:115], v[176:179], v[96:99]
	v_mfma_f32_16x16x32_bf16 v[120:123], v[112:115], v[168:171], v[120:123]
	v_mfma_f32_16x16x32_bf16 v[120:123], v[116:119], v[172:175], v[120:123]
	v_mfma_f32_16x16x32_bf16 v[144:147], v[116:119], v[164:167], v[144:147]
	v_mfma_f32_16x16x32_bf16 v[144:147], v[112:115], v[160:163], v[144:147]
	v_mfma_f32_16x16x32_bf16 v[140:143], v[132:135], v[160:163], v[140:143]
	v_mfma_f32_16x16x32_bf16 v[140:143], v[136:139], v[164:167], v[140:143]
	v_mfma_f32_16x16x32_bf16 v[108:111], v[136:139], v[172:175], v[108:111]
	v_mfma_f32_16x16x32_bf16 v[108:111], v[132:135], v[168:171], v[108:111]
	v_mfma_f32_16x16x32_bf16 v[84:87], v[132:135], v[176:179], v[84:87]
	v_mfma_f32_16x16x32_bf16 v[84:87], v[136:139], v[180:183], v[84:87]
	v_mfma_f32_16x16x32_bf16 v[68:71], v[136:139], v[212:215], v[68:71]
	v_mfma_f32_16x16x32_bf16 v[68:71], v[132:135], v[208:211], v[68:71]
	v_mfma_f32_16x16x32_bf16 v[64:67], v[152:155], v[208:211], v[64:67]
	v_mfma_f32_16x16x32_bf16 v[64:67], v[156:159], v[212:215], v[64:67]
	v_mfma_f32_16x16x32_bf16 v[80:83], v[156:159], v[180:183], v[80:83]
	v_mfma_f32_16x16x32_bf16 v[80:83], v[152:155], v[176:179], v[80:83]
	v_mfma_f32_16x16x32_bf16 v[104:107], v[152:155], v[168:171], v[104:107]
	v_mfma_f32_16x16x32_bf16 v[104:107], v[156:159], v[172:175], v[104:107]
	v_mfma_f32_16x16x32_bf16 v[128:131], v[156:159], v[164:167], v[128:131]
	v_mfma_f32_16x16x32_bf16 v[128:131], v[152:155], v[160:163], v[128:131]
	s_barrier
	s_setprio 0
	s_add_i32 s50, s82, s66
	v_lshl_add_u64 v[216:217], s[54:55], 0, v[186:187]
	s_mov_b32 m0, s50
	ds_read_b128 v[160:163], v235 offset:16384
	ds_read_b128 v[164:167], v235 offset:17408
	ds_read_b128 v[168:171], v235 offset:18432
	ds_read_b128 v[172:175], v235 offset:19456
	ds_read_b128 v[176:179], v235 offset:20480
	ds_read_b128 v[180:183], v235 offset:21504
	ds_read_b128 v[208:211], v235 offset:22528
	ds_read_b128 v[212:215], v235 offset:23552
	global_load_lds_dwordx4 v[216:217], off
	s_add_i32 m0, s50, 0x2000
	s_add_u32 s50, s54, 0xb0000
	v_lshl_add_u64 v[218:219], s[54:55], 0, v[190:191]
	s_addc_u32 s51, s55, 0
	s_add_i32 vcc_lo, s85, s66
	global_load_lds_dwordx4 v[218:219], off
	v_lshl_add_u64 v[220:221], s[50:51], 0, v[186:187]
	s_mov_b32 m0, vcc_lo
	v_lshl_add_u64 v[222:223], s[56:57], 0, v[188:189]
	global_load_lds_dwordx4 v[220:221], off
	v_lshl_add_u64 v[220:221], s[50:51], 0, v[190:191]
	s_add_i32 m0, vcc_lo, 0x2000
	s_nop 0
	global_load_lds_dwordx4 v[220:221], off
	v_lshl_add_u64 v[220:221], s[56:57], 0, v[184:185]
	s_mov_b32 m0, s67
	s_nop 0
	global_load_lds_dwordx4 v[220:221], off
	s_mov_b32 m0, s68
	s_nop 0
	global_load_lds_dwordx4 v[222:223], off
	s_waitcnt vmcnt(8)
	s_waitcnt lgkmcnt(0)
	s_setprio 1
	s_barrier
	v_mfma_f32_16x16x32_bf16 v[60:63], v[88:91], v[160:163], v[60:63]
	v_mfma_f32_16x16x32_bf16 v[60:63], v[92:95], v[164:167], v[60:63]
	v_mfma_f32_16x16x32_bf16 v[44:47], v[92:95], v[172:175], v[44:47]
	v_mfma_f32_16x16x32_bf16 v[44:47], v[88:91], v[168:171], v[44:47]
	v_mfma_f32_16x16x32_bf16 v[28:31], v[88:91], v[176:179], v[28:31]
	v_mfma_f32_16x16x32_bf16 v[28:31], v[92:95], v[180:183], v[28:31]
	v_mfma_f32_16x16x32_bf16 v[12:15], v[92:95], v[212:215], v[12:15]
	v_mfma_f32_16x16x32_bf16 v[12:15], v[88:91], v[208:211], v[12:15]
	v_mfma_f32_16x16x32_bf16 v[8:11], v[112:115], v[208:211], v[8:11]
	v_mfma_f32_16x16x32_bf16 v[8:11], v[116:119], v[212:215], v[8:11]
	v_mfma_f32_16x16x32_bf16 v[24:27], v[116:119], v[180:183], v[24:27]
	v_mfma_f32_16x16x32_bf16 v[24:27], v[112:115], v[176:179], v[24:27]
	v_mfma_f32_16x16x32_bf16 v[40:43], v[112:115], v[168:171], v[40:43]
	v_mfma_f32_16x16x32_bf16 v[40:43], v[116:119], v[172:175], v[40:43]
	v_mfma_f32_16x16x32_bf16 v[56:59], v[116:119], v[164:167], v[56:59]
	v_mfma_f32_16x16x32_bf16 v[56:59], v[112:115], v[160:163], v[56:59]
	v_mfma_f32_16x16x32_bf16 v[52:55], v[132:135], v[160:163], v[52:55]
	v_mfma_f32_16x16x32_bf16 v[52:55], v[136:139], v[164:167], v[52:55]
	v_mfma_f32_16x16x32_bf16 v[36:39], v[136:139], v[172:175], v[36:39]
	v_mfma_f32_16x16x32_bf16 v[36:39], v[132:135], v[168:171], v[36:39]
	v_mfma_f32_16x16x32_bf16 v[20:23], v[132:135], v[176:179], v[20:23]
	v_mfma_f32_16x16x32_bf16 v[20:23], v[136:139], v[180:183], v[20:23]
	v_mfma_f32_16x16x32_bf16 v[4:7], v[136:139], v[212:215], v[4:7]
	v_mfma_f32_16x16x32_bf16 v[4:7], v[132:135], v[208:211], v[4:7]
	v_mfma_f32_16x16x32_bf16 v[0:3], v[152:155], v[208:211], v[0:3]
	v_mfma_f32_16x16x32_bf16 v[0:3], v[156:159], v[212:215], v[0:3]
	v_mfma_f32_16x16x32_bf16 v[16:19], v[156:159], v[180:183], v[16:19]
	v_mfma_f32_16x16x32_bf16 v[16:19], v[152:155], v[176:179], v[16:19]
	v_mfma_f32_16x16x32_bf16 v[32:35], v[152:155], v[168:171], v[32:35]
	v_mfma_f32_16x16x32_bf16 v[32:35], v[156:159], v[172:175], v[32:35]
	v_mfma_f32_16x16x32_bf16 v[48:51], v[156:159], v[164:167], v[48:51]
	v_mfma_f32_16x16x32_bf16 v[48:51], v[152:155], v[160:163], v[48:51]
	s_barrier
	s_setprio 0
	s_add_i32 vcc_lo, 0, 0x18000
	s_add_i32 vcc_hi, 0, 0x1c000
	v_add_u32_e32 v116, vcc_lo, v230
	v_add_u32_e32 v156, vcc_hi, v230
	ds_read_b128 v[88:91], v116
	ds_read_b128 v[92:95], v116 offset:1024
	ds_read_b128 v[112:115], v116 offset:2048
	ds_read_b128 v[116:119], v116 offset:3072
	ds_read_b128 v[132:135], v156
	ds_read_b128 v[136:139], v156 offset:1024
	ds_read_b128 v[152:155], v156 offset:2048
	ds_read_b128 v[156:159], v156 offset:3072
	s_add_u32 s50, s56, 0xb0000
	s_addc_u32 s51, s57, 0
	s_mov_b32 m0, s69
	v_lshl_add_u64 v[224:225], s[50:51], 0, v[184:185]
	ds_read_b128 v[160:163], v235 offset:32768
	ds_read_b128 v[164:167], v235 offset:33792
	ds_read_b128 v[168:171], v235 offset:34816
	ds_read_b128 v[172:175], v235 offset:35840
	ds_read_b128 v[176:179], v235 offset:36864
	ds_read_b128 v[180:183], v235 offset:37888
	ds_read_b128 v[208:211], v235 offset:38912
	ds_read_b128 v[212:215], v235 offset:39936
	global_load_lds_dwordx4 v[224:225], off
	v_lshl_add_u64 v[224:225], s[50:51], 0, v[188:189]
	s_mov_b32 m0, s70
	s_nop 0
	global_load_lds_dwordx4 v[224:225], off
	s_waitcnt vmcnt(8)
	s_waitcnt lgkmcnt(0)
	s_setprio 1
	s_barrier
	v_mfma_f32_16x16x32_bf16 v[148:151], v[88:91], v[160:163], v[148:151]
	v_mfma_f32_16x16x32_bf16 v[148:151], v[92:95], v[164:167], v[148:151]
	v_mfma_f32_16x16x32_bf16 v[124:127], v[92:95], v[172:175], v[124:127]
	v_mfma_f32_16x16x32_bf16 v[124:127], v[88:91], v[168:171], v[124:127]
	v_mfma_f32_16x16x32_bf16 v[100:103], v[88:91], v[176:179], v[100:103]
	v_mfma_f32_16x16x32_bf16 v[100:103], v[92:95], v[180:183], v[100:103]
	v_mfma_f32_16x16x32_bf16 v[76:79], v[92:95], v[212:215], v[76:79]
	v_mfma_f32_16x16x32_bf16 v[76:79], v[88:91], v[208:211], v[76:79]
	v_mfma_f32_16x16x32_bf16 v[72:75], v[112:115], v[208:211], v[72:75]
	v_mfma_f32_16x16x32_bf16 v[72:75], v[116:119], v[212:215], v[72:75]
	v_mfma_f32_16x16x32_bf16 v[96:99], v[116:119], v[180:183], v[96:99]
	v_mfma_f32_16x16x32_bf16 v[96:99], v[112:115], v[176:179], v[96:99]
	v_mfma_f32_16x16x32_bf16 v[120:123], v[112:115], v[168:171], v[120:123]
	v_mfma_f32_16x16x32_bf16 v[120:123], v[116:119], v[172:175], v[120:123]
	v_mfma_f32_16x16x32_bf16 v[144:147], v[116:119], v[164:167], v[144:147]
	v_mfma_f32_16x16x32_bf16 v[144:147], v[112:115], v[160:163], v[144:147]
	v_mfma_f32_16x16x32_bf16 v[140:143], v[132:135], v[160:163], v[140:143]
	v_mfma_f32_16x16x32_bf16 v[140:143], v[136:139], v[164:167], v[140:143]
	v_mfma_f32_16x16x32_bf16 v[108:111], v[136:139], v[172:175], v[108:111]
	v_mfma_f32_16x16x32_bf16 v[108:111], v[132:135], v[168:171], v[108:111]
	v_mfma_f32_16x16x32_bf16 v[84:87], v[132:135], v[176:179], v[84:87]
	v_mfma_f32_16x16x32_bf16 v[84:87], v[136:139], v[180:183], v[84:87]
	v_mfma_f32_16x16x32_bf16 v[68:71], v[136:139], v[212:215], v[68:71]
	v_mfma_f32_16x16x32_bf16 v[68:71], v[132:135], v[208:211], v[68:71]
	v_mfma_f32_16x16x32_bf16 v[64:67], v[152:155], v[208:211], v[64:67]
	v_mfma_f32_16x16x32_bf16 v[64:67], v[156:159], v[212:215], v[64:67]
	v_mfma_f32_16x16x32_bf16 v[80:83], v[156:159], v[180:183], v[80:83]
	v_mfma_f32_16x16x32_bf16 v[80:83], v[152:155], v[176:179], v[80:83]
	v_mfma_f32_16x16x32_bf16 v[104:107], v[152:155], v[168:171], v[104:107]
	v_mfma_f32_16x16x32_bf16 v[104:107], v[156:159], v[172:175], v[104:107]
	v_mfma_f32_16x16x32_bf16 v[128:131], v[156:159], v[164:167], v[128:131]
	v_mfma_f32_16x16x32_bf16 v[128:131], v[152:155], v[160:163], v[128:131]
	s_barrier
	s_setprio 0
	s_add_i32 s50, vcc_lo, s66
	v_lshl_add_u64 v[216:217], v[216:217], 0, s[46:47]
	s_mov_b32 m0, s50
	ds_read_b128 v[160:163], v235 offset:49152
	ds_read_b128 v[164:167], v235 offset:50176
	ds_read_b128 v[168:171], v235 offset:51200
	ds_read_b128 v[172:175], v235 offset:52224
	ds_read_b128 v[176:179], v235 offset:53248
	ds_read_b128 v[180:183], v235 offset:54272
	ds_read_b128 v[208:211], v235 offset:55296
	ds_read_b128 v[212:215], v235 offset:56320
	global_load_lds_dwordx4 v[216:217], off
	s_add_i32 m0, s50, 0x2000
	s_add_u32 s50, s54, 0xb0080
	v_lshl_add_u64 v[216:217], v[218:219], 0, s[46:47]
	s_addc_u32 s51, s55, 0
	s_add_i32 s54, vcc_hi, s66
	global_load_lds_dwordx4 v[216:217], off
	v_lshl_add_u64 v[216:217], s[50:51], 0, v[186:187]
	s_mov_b32 m0, s54
	s_nop 0
	global_load_lds_dwordx4 v[216:217], off
	v_lshl_add_u64 v[216:217], s[50:51], 0, v[190:191]
	s_add_i32 m0, s54, 0x2000
	s_nop 0
	global_load_lds_dwordx4 v[216:217], off
	v_lshl_add_u64 v[216:217], v[220:221], 0, s[46:47]
	s_mov_b32 m0, s74
	s_nop 0
	global_load_lds_dwordx4 v[216:217], off
	v_lshl_add_u64 v[216:217], v[222:223], 0, s[46:47]
	s_mov_b32 m0, s75
	s_nop 0
	global_load_lds_dwordx4 v[216:217], off
	s_waitcnt vmcnt(8)
	s_waitcnt lgkmcnt(0)
	s_setprio 1
	s_barrier
	v_mfma_f32_16x16x32_bf16 v[60:63], v[88:91], v[160:163], v[60:63]
	v_mfma_f32_16x16x32_bf16 v[60:63], v[92:95], v[164:167], v[60:63]
	v_mfma_f32_16x16x32_bf16 v[44:47], v[92:95], v[172:175], v[44:47]
	v_mfma_f32_16x16x32_bf16 v[44:47], v[88:91], v[168:171], v[44:47]
	v_mfma_f32_16x16x32_bf16 v[28:31], v[88:91], v[176:179], v[28:31]
	v_mfma_f32_16x16x32_bf16 v[28:31], v[92:95], v[180:183], v[28:31]
	v_mfma_f32_16x16x32_bf16 v[12:15], v[92:95], v[212:215], v[12:15]
	v_mfma_f32_16x16x32_bf16 v[12:15], v[88:91], v[208:211], v[12:15]
	v_mfma_f32_16x16x32_bf16 v[8:11], v[112:115], v[208:211], v[8:11]
	v_mfma_f32_16x16x32_bf16 v[8:11], v[116:119], v[212:215], v[8:11]
	v_mfma_f32_16x16x32_bf16 v[24:27], v[116:119], v[180:183], v[24:27]
	v_mfma_f32_16x16x32_bf16 v[24:27], v[112:115], v[176:179], v[24:27]
	v_mfma_f32_16x16x32_bf16 v[40:43], v[112:115], v[168:171], v[40:43]
	v_mfma_f32_16x16x32_bf16 v[40:43], v[116:119], v[172:175], v[40:43]
	v_mfma_f32_16x16x32_bf16 v[56:59], v[116:119], v[164:167], v[56:59]
	v_mfma_f32_16x16x32_bf16 v[56:59], v[112:115], v[160:163], v[56:59]
	v_mfma_f32_16x16x32_bf16 v[52:55], v[132:135], v[160:163], v[52:55]
	v_mfma_f32_16x16x32_bf16 v[52:55], v[136:139], v[164:167], v[52:55]
	v_mfma_f32_16x16x32_bf16 v[36:39], v[136:139], v[172:175], v[36:39]
	v_mfma_f32_16x16x32_bf16 v[36:39], v[132:135], v[168:171], v[36:39]
	v_mfma_f32_16x16x32_bf16 v[20:23], v[132:135], v[176:179], v[20:23]
	v_mfma_f32_16x16x32_bf16 v[20:23], v[136:139], v[180:183], v[20:23]
	v_mfma_f32_16x16x32_bf16 v[4:7], v[136:139], v[212:215], v[4:7]
	v_mfma_f32_16x16x32_bf16 v[4:7], v[132:135], v[208:211], v[4:7]
	v_mfma_f32_16x16x32_bf16 v[0:3], v[152:155], v[208:211], v[0:3]
	v_mfma_f32_16x16x32_bf16 v[0:3], v[156:159], v[212:215], v[0:3]
	v_mfma_f32_16x16x32_bf16 v[16:19], v[156:159], v[180:183], v[16:19]
	v_mfma_f32_16x16x32_bf16 v[16:19], v[152:155], v[176:179], v[16:19]
	v_mfma_f32_16x16x32_bf16 v[32:35], v[152:155], v[168:171], v[32:35]
	v_mfma_f32_16x16x32_bf16 v[32:35], v[156:159], v[172:175], v[32:35]
	v_mfma_f32_16x16x32_bf16 v[48:51], v[156:159], v[164:167], v[48:51]
	v_mfma_f32_16x16x32_bf16 v[48:51], v[152:155], v[160:163], v[48:51]
	s_barrier
	s_setprio 0
	s_add_i32 s97, s97, 2
	s_add_u32 s95, s95, 0x100
	s_addc_u32 s96, s96, 0
	s_cmp_gt_u32 s97, 41
	s_mov_b64 s[50:51], s[52:53]
	s_cbranch_scc0 .LBB0_221
	s_and_b64 vcc, exec, s[48:49]
	s_cbranch_vccz .LBB0_224
	s_barrier

.LBB0_312:
	s_ashr_i32 s43, s42, 31
	s_lshl_b64 s[46:47], s[42:43], 19
	s_add_u32 s46, s62, s46
	s_addc_u32 s47, s63, s47
	s_and_b64 s[48:49], s[4:5], exec
	s_cselect_b32 s10, s47, s53
	s_cselect_b32 s43, s46, s52
	s_ashr_i32 s45, s44, 31
	s_lshl_b64 s[48:49], s[44:45], 19
	s_add_u32 s48, s70, s48
	s_addc_u32 s49, s71, s49
	s_and_b64 s[56:57], s[4:5], exec
	s_cselect_b32 s45, s49, s55
	s_cselect_b32 s51, s48, s54
	s_add_u32 s52, s52, 0x40080
	s_addc_u32 s53, s53, 0
	s_add_u32 s67, s54, 0x100
	s_addc_u32 s68, s55, 0
	s_mov_b32 s69, -2
	ds_read_b128 v[128:131], v179
	ds_read_b128 v[132:135], v179 offset:1024
	ds_read_b128 v[136:139], v179 offset:2048
	ds_read_b128 v[140:143], v179 offset:3072
	ds_read_b128 v[188:191], v181
	ds_read_b128 v[192:195], v181 offset:1024
	ds_read_b128 v[196:199], v181 offset:2048
	ds_read_b128 v[200:203], v181 offset:3072
	s_add_u32 s54, s52, 0xfffc0080
	s_addc_u32 s55, s53, -1
	s_cmp_eq_u32 s69, 12
	s_cselect_b32 s57, s10, s55
	s_cselect_b32 s56, s43, s54
	s_cselect_b32 s55, s45, s68
	s_cselect_b32 s54, s51, s67
	v_lshl_add_u64 v[238:239], s[52:53], 0, v[162:163]
	s_add_i32 m0, s75, 0xc000
	ds_read_b128 v[204:207], v183
	ds_read_b128 v[208:211], v183 offset:1024
	ds_read_b128 v[212:215], v183 offset:2048
	ds_read_b128 v[216:219], v183 offset:3072
	ds_read_b128 v[220:223], v183 offset:4096
	ds_read_b128 v[224:227], v183 offset:5120
	ds_read_b128 v[230:233], v183 offset:6144
	ds_read_b128 v[234:237], v183 offset:7168
	global_load_lds_dwordx4 v[238:239], off
	v_lshl_add_u64 v[238:239], s[52:53], 0, v[164:165]
	s_add_i32 m0, s75, 0xe000
	s_nop 0
	global_load_lds_dwordx4 v[238:239], off
	s_waitcnt vmcnt(8)
	s_waitcnt lgkmcnt(0)
	s_setprio 1
	s_barrier
	v_mfma_f32_16x16x32_bf16 v[124:127], v[128:131], v[204:207], 0
	v_mfma_f32_16x16x32_bf16 v[124:127], v[132:135], v[208:211], v[124:127]
	v_mfma_f32_16x16x32_bf16 v[108:111], v[132:135], v[216:219], 0
	v_mfma_f32_16x16x32_bf16 v[108:111], v[128:131], v[212:215], v[108:111]
	v_mfma_f32_16x16x32_bf16 v[92:95], v[128:131], v[220:223], 0
	v_mfma_f32_16x16x32_bf16 v[92:95], v[132:135], v[224:227], v[92:95]
	v_mfma_f32_16x16x32_bf16 v[76:79], v[132:135], v[234:237], 0
	v_mfma_f32_16x16x32_bf16 v[76:79], v[128:131], v[230:233], v[76:79]
	v_mfma_f32_16x16x32_bf16 v[72:75], v[136:139], v[230:233], 0
	v_mfma_f32_16x16x32_bf16 v[72:75], v[140:143], v[234:237], v[72:75]
	v_mfma_f32_16x16x32_bf16 v[88:91], v[140:143], v[224:227], 0
	v_mfma_f32_16x16x32_bf16 v[88:91], v[136:139], v[220:223], v[88:91]
	v_mfma_f32_16x16x32_bf16 v[104:107], v[136:139], v[212:215], 0
	v_mfma_f32_16x16x32_bf16 v[104:107], v[140:143], v[216:219], v[104:107]
	v_mfma_f32_16x16x32_bf16 v[120:123], v[140:143], v[208:211], 0
	v_mfma_f32_16x16x32_bf16 v[120:123], v[136:139], v[204:207], v[120:123]
	v_mfma_f32_16x16x32_bf16 v[116:119], v[188:191], v[204:207], 0
	v_mfma_f32_16x16x32_bf16 v[116:119], v[192:195], v[208:211], v[116:119]
	v_mfma_f32_16x16x32_bf16 v[100:103], v[192:195], v[216:219], 0
	v_mfma_f32_16x16x32_bf16 v[100:103], v[188:191], v[212:215], v[100:103]
	v_mfma_f32_16x16x32_bf16 v[84:87], v[188:191], v[220:223], 0
	v_mfma_f32_16x16x32_bf16 v[84:87], v[192:195], v[224:227], v[84:87]
	v_mfma_f32_16x16x32_bf16 v[68:71], v[192:195], v[234:237], 0
	v_mfma_f32_16x16x32_bf16 v[68:71], v[188:191], v[230:233], v[68:71]
	v_mfma_f32_16x16x32_bf16 v[64:67], v[196:199], v[230:233], 0
	v_mfma_f32_16x16x32_bf16 v[64:67], v[200:203], v[234:237], v[64:67]
	v_mfma_f32_16x16x32_bf16 v[80:83], v[200:203], v[224:227], 0
	v_mfma_f32_16x16x32_bf16 v[80:83], v[196:199], v[220:223], v[80:83]
	v_mfma_f32_16x16x32_bf16 v[96:99], v[196:199], v[212:215], 0
	v_mfma_f32_16x16x32_bf16 v[96:99], v[200:203], v[216:219], v[96:99]
	v_mfma_f32_16x16x32_bf16 v[112:115], v[200:203], v[208:211], 0
	v_mfma_f32_16x16x32_bf16 v[112:115], v[196:199], v[204:207], v[112:115]
	s_barrier
	s_setprio 0
	s_add_i32 vcc_lo, s92, s72
	v_lshl_add_u64 v[238:239], s[54:55], 0, v[148:149]
	s_mov_b32 m0, vcc_lo
	ds_read_b128 v[204:207], v183 offset:16384
	ds_read_b128 v[208:211], v183 offset:17408
	ds_read_b128 v[212:215], v183 offset:18432
	ds_read_b128 v[216:219], v183 offset:19456
	ds_read_b128 v[220:223], v183 offset:20480
	ds_read_b128 v[224:227], v183 offset:21504
	ds_read_b128 v[230:233], v183 offset:22528
	ds_read_b128 v[234:237], v183 offset:23552
	global_load_lds_dwordx4 v[238:239], off
	s_add_i32 m0, vcc_lo, 0x2000
	s_add_u32 vcc_lo, s54, 0x40000
	v_lshl_add_u64 v[240:241], s[54:55], 0, v[144:145]
	s_addc_u32 vcc_hi, s55, 0
	s_add_i32 s83, s93, s72
	global_load_lds_dwordx4 v[240:241], off
	v_lshl_add_u64 v[242:243], vcc, 0, v[148:149]
	s_mov_b32 m0, s83
	v_lshl_add_u64 v[244:245], s[56:57], 0, v[146:147]
	global_load_lds_dwordx4 v[242:243], off
	v_lshl_add_u64 v[242:243], vcc, 0, v[144:145]
	s_add_i32 m0, s83, 0x2000
	s_nop 0
	global_load_lds_dwordx4 v[242:243], off
	v_lshl_add_u64 v[242:243], s[56:57], 0, v[150:151]
	s_mov_b32 m0, s75
	s_nop 0
	global_load_lds_dwordx4 v[242:243], off
	s_mov_b32 m0, s76
	s_nop 0
	global_load_lds_dwordx4 v[244:245], off
	s_waitcnt vmcnt(8)
	s_waitcnt lgkmcnt(0)
	s_setprio 1
	s_barrier
	v_mfma_f32_16x16x32_bf16 v[60:63], v[128:131], v[204:207], 0
	v_mfma_f32_16x16x32_bf16 v[60:63], v[132:135], v[208:211], v[60:63]
	v_mfma_f32_16x16x32_bf16 v[44:47], v[132:135], v[216:219], 0
	v_mfma_f32_16x16x32_bf16 v[44:47], v[128:131], v[212:215], v[44:47]
	v_mfma_f32_16x16x32_bf16 v[28:31], v[128:131], v[220:223], 0
	v_mfma_f32_16x16x32_bf16 v[28:31], v[132:135], v[224:227], v[28:31]
	v_mfma_f32_16x16x32_bf16 v[12:15], v[132:135], v[234:237], 0
	v_mfma_f32_16x16x32_bf16 v[12:15], v[128:131], v[230:233], v[12:15]
	v_mfma_f32_16x16x32_bf16 v[8:11], v[136:139], v[230:233], 0
	v_mfma_f32_16x16x32_bf16 v[8:11], v[140:143], v[234:237], v[8:11]
	v_mfma_f32_16x16x32_bf16 v[24:27], v[140:143], v[224:227], 0
	v_mfma_f32_16x16x32_bf16 v[24:27], v[136:139], v[220:223], v[24:27]
	v_mfma_f32_16x16x32_bf16 v[40:43], v[136:139], v[212:215], 0
	v_mfma_f32_16x16x32_bf16 v[40:43], v[140:143], v[216:219], v[40:43]
	v_mfma_f32_16x16x32_bf16 v[56:59], v[140:143], v[208:211], 0
	v_mfma_f32_16x16x32_bf16 v[56:59], v[136:139], v[204:207], v[56:59]
	v_mfma_f32_16x16x32_bf16 v[52:55], v[188:191], v[204:207], 0
	v_mfma_f32_16x16x32_bf16 v[52:55], v[192:195], v[208:211], v[52:55]
	v_mfma_f32_16x16x32_bf16 v[36:39], v[192:195], v[216:219], 0
	v_mfma_f32_16x16x32_bf16 v[36:39], v[188:191], v[212:215], v[36:39]
	v_mfma_f32_16x16x32_bf16 v[20:23], v[188:191], v[220:223], 0
	v_mfma_f32_16x16x32_bf16 v[20:23], v[192:195], v[224:227], v[20:23]
	v_mfma_f32_16x16x32_bf16 v[4:7], v[192:195], v[234:237], 0
	v_mfma_f32_16x16x32_bf16 v[4:7], v[188:191], v[230:233], v[4:7]
	v_mfma_f32_16x16x32_bf16 v[0:3], v[196:199], v[230:233], 0
	v_mfma_f32_16x16x32_bf16 v[0:3], v[200:203], v[234:237], v[0:3]
	v_mfma_f32_16x16x32_bf16 v[16:19], v[200:203], v[224:227], 0
	v_mfma_f32_16x16x32_bf16 v[16:19], v[196:199], v[220:223], v[16:19]
	v_mfma_f32_16x16x32_bf16 v[32:35], v[196:199], v[212:215], 0
	v_mfma_f32_16x16x32_bf16 v[32:35], v[200:203], v[216:219], v[32:35]
	v_mfma_f32_16x16x32_bf16 v[48:51], v[200:203], v[208:211], 0
	v_mfma_f32_16x16x32_bf16 v[48:51], v[196:199], v[204:207], v[48:51]
	s_barrier
	s_setprio 0
	s_add_i32 s83, 0, 0x18000
	s_add_i32 vcc_lo, 0, 0x1c000
	v_add_u32_e32 v140, s83, v157
	v_add_u32_e32 v171, vcc_lo, v157
	ds_read_b128 v[128:131], v140
	ds_read_b128 v[132:135], v140 offset:1024
	ds_read_b128 v[136:139], v140 offset:2048
	ds_read_b128 v[140:143], v140 offset:3072
	ds_read_b128 v[188:191], v171
	ds_read_b128 v[192:195], v171 offset:1024
	ds_read_b128 v[196:199], v171 offset:2048
	ds_read_b128 v[200:203], v171 offset:3072
	s_add_u32 s56, s56, 0x40000
	s_addc_u32 s57, s57, 0
	s_mov_b32 m0, s77
	v_lshl_add_u64 v[246:247], s[56:57], 0, v[150:151]
	ds_read_b128 v[204:207], v183 offset:32768
	ds_read_b128 v[208:211], v183 offset:33792
	ds_read_b128 v[212:215], v183 offset:34816
	ds_read_b128 v[216:219], v183 offset:35840
	ds_read_b128 v[220:223], v183 offset:36864
	ds_read_b128 v[224:227], v183 offset:37888
	ds_read_b128 v[230:233], v183 offset:38912
	ds_read_b128 v[234:237], v183 offset:39936
	global_load_lds_dwordx4 v[246:247], off
	v_lshl_add_u64 v[246:247], s[56:57], 0, v[146:147]
	s_mov_b32 m0, s78
	s_nop 0
	global_load_lds_dwordx4 v[246:247], off
	s_waitcnt vmcnt(8)
	s_waitcnt lgkmcnt(0)
	s_setprio 1
	s_barrier
	v_mfma_f32_16x16x32_bf16 v[124:127], v[128:131], v[204:207], v[124:127]
	v_mfma_f32_16x16x32_bf16 v[124:127], v[132:135], v[208:211], v[124:127]
	v_mfma_f32_16x16x32_bf16 v[108:111], v[132:135], v[216:219], v[108:111]
	v_mfma_f32_16x16x32_bf16 v[108:111], v[128:131], v[212:215], v[108:111]
	v_mfma_f32_16x16x32_bf16 v[92:95], v[128:131], v[220:223], v[92:95]
	v_mfma_f32_16x16x32_bf16 v[92:95], v[132:135], v[224:227], v[92:95]
	v_mfma_f32_16x16x32_bf16 v[76:79], v[132:135], v[234:237], v[76:79]
	v_mfma_f32_16x16x32_bf16 v[76:79], v[128:131], v[230:233], v[76:79]
	v_mfma_f32_16x16x32_bf16 v[72:75], v[136:139], v[230:233], v[72:75]
	v_mfma_f32_16x16x32_bf16 v[72:75], v[140:143], v[234:237], v[72:75]
	v_mfma_f32_16x16x32_bf16 v[88:91], v[140:143], v[224:227], v[88:91]
	v_mfma_f32_16x16x32_bf16 v[88:91], v[136:139], v[220:223], v[88:91]
	v_mfma_f32_16x16x32_bf16 v[104:107], v[136:139], v[212:215], v[104:107]
	v_mfma_f32_16x16x32_bf16 v[104:107], v[140:143], v[216:219], v[104:107]
	v_mfma_f32_16x16x32_bf16 v[120:123], v[140:143], v[208:211], v[120:123]
	v_mfma_f32_16x16x32_bf16 v[120:123], v[136:139], v[204:207], v[120:123]
	v_mfma_f32_16x16x32_bf16 v[116:119], v[188:191], v[204:207], v[116:119]
	v_mfma_f32_16x16x32_bf16 v[116:119], v[192:195], v[208:211], v[116:119]
	v_mfma_f32_16x16x32_bf16 v[100:103], v[192:195], v[216:219], v[100:103]
	v_mfma_f32_16x16x32_bf16 v[100:103], v[188:191], v[212:215], v[100:103]
	v_mfma_f32_16x16x32_bf16 v[84:87], v[188:191], v[220:223], v[84:87]
	v_mfma_f32_16x16x32_bf16 v[84:87], v[192:195], v[224:227], v[84:87]
	v_mfma_f32_16x16x32_bf16 v[68:71], v[192:195], v[234:237], v[68:71]
	v_mfma_f32_16x16x32_bf16 v[68:71], v[188:191], v[230:233], v[68:71]
	v_mfma_f32_16x16x32_bf16 v[64:67], v[196:199], v[230:233], v[64:67]
	v_mfma_f32_16x16x32_bf16 v[64:67], v[200:203], v[234:237], v[64:67]
	v_mfma_f32_16x16x32_bf16 v[80:83], v[200:203], v[224:227], v[80:83]
	v_mfma_f32_16x16x32_bf16 v[80:83], v[196:199], v[220:223], v[80:83]
	v_mfma_f32_16x16x32_bf16 v[96:99], v[196:199], v[212:215], v[96:99]
	v_mfma_f32_16x16x32_bf16 v[96:99], v[200:203], v[216:219], v[96:99]
	v_mfma_f32_16x16x32_bf16 v[112:115], v[200:203], v[208:211], v[112:115]
	v_mfma_f32_16x16x32_bf16 v[112:115], v[196:199], v[204:207], v[112:115]
	s_barrier
	s_setprio 0
	s_add_i32 s56, s83, s72
	v_lshl_add_u64 v[238:239], v[238:239], 0, s[38:39]
	s_mov_b32 m0, s56
	ds_read_b128 v[204:207], v183 offset:49152
	ds_read_b128 v[208:211], v183 offset:50176
	ds_read_b128 v[212:215], v183 offset:51200
	ds_read_b128 v[216:219], v183 offset:52224
	ds_read_b128 v[220:223], v183 offset:53248
	ds_read_b128 v[224:227], v183 offset:54272
	ds_read_b128 v[230:233], v183 offset:55296
	ds_read_b128 v[234:237], v183 offset:56320
	global_load_lds_dwordx4 v[238:239], off
	s_add_i32 m0, s56, 0x2000
	s_add_u32 s54, s54, 0x40080
	v_lshl_add_u64 v[238:239], v[240:241], 0, s[38:39]
	s_addc_u32 s55, s55, 0
	s_add_i32 s56, vcc_lo, s72
	global_load_lds_dwordx4 v[238:239], off
	v_lshl_add_u64 v[238:239], s[54:55], 0, v[148:149]
	s_mov_b32 m0, s56
	s_nop 0
	global_load_lds_dwordx4 v[238:239], off
	v_lshl_add_u64 v[238:239], s[54:55], 0, v[144:145]
	s_add_i32 m0, s56, 0x2000
	s_nop 0
	global_load_lds_dwordx4 v[238:239], off
	v_lshl_add_u64 v[238:239], v[242:243], 0, s[38:39]
	s_mov_b32 m0, s87
	s_nop 0
	global_load_lds_dwordx4 v[238:239], off
	v_lshl_add_u64 v[238:239], v[244:245], 0, s[38:39]
	s_mov_b32 m0, s88
	s_nop 0
	global_load_lds_dwordx4 v[238:239], off
	s_waitcnt vmcnt(8)
	s_waitcnt lgkmcnt(0)
	s_setprio 1
	s_barrier
	v_mfma_f32_16x16x32_bf16 v[60:63], v[128:131], v[204:207], v[60:63]
	v_mfma_f32_16x16x32_bf16 v[60:63], v[132:135], v[208:211], v[60:63]
	v_mfma_f32_16x16x32_bf16 v[44:47], v[132:135], v[216:219], v[44:47]
	v_mfma_f32_16x16x32_bf16 v[44:47], v[128:131], v[212:215], v[44:47]
	v_mfma_f32_16x16x32_bf16 v[28:31], v[128:131], v[220:223], v[28:31]
	v_mfma_f32_16x16x32_bf16 v[28:31], v[132:135], v[224:227], v[28:31]
	v_mfma_f32_16x16x32_bf16 v[12:15], v[132:135], v[234:237], v[12:15]
	v_mfma_f32_16x16x32_bf16 v[12:15], v[128:131], v[230:233], v[12:15]
	v_mfma_f32_16x16x32_bf16 v[8:11], v[136:139], v[230:233], v[8:11]
	v_mfma_f32_16x16x32_bf16 v[8:11], v[140:143], v[234:237], v[8:11]
	v_mfma_f32_16x16x32_bf16 v[24:27], v[140:143], v[224:227], v[24:27]
	v_mfma_f32_16x16x32_bf16 v[24:27], v[136:139], v[220:223], v[24:27]
	v_mfma_f32_16x16x32_bf16 v[40:43], v[136:139], v[212:215], v[40:43]
	v_mfma_f32_16x16x32_bf16 v[40:43], v[140:143], v[216:219], v[40:43]
	v_mfma_f32_16x16x32_bf16 v[56:59], v[140:143], v[208:211], v[56:59]
	v_mfma_f32_16x16x32_bf16 v[56:59], v[136:139], v[204:207], v[56:59]
	v_mfma_f32_16x16x32_bf16 v[52:55], v[188:191], v[204:207], v[52:55]
	v_mfma_f32_16x16x32_bf16 v[52:55], v[192:195], v[208:211], v[52:55]
	v_mfma_f32_16x16x32_bf16 v[36:39], v[192:195], v[216:219], v[36:39]
	v_mfma_f32_16x16x32_bf16 v[36:39], v[188:191], v[212:215], v[36:39]
	v_mfma_f32_16x16x32_bf16 v[20:23], v[188:191], v[220:223], v[20:23]
	v_mfma_f32_16x16x32_bf16 v[20:23], v[192:195], v[224:227], v[20:23]
	v_mfma_f32_16x16x32_bf16 v[4:7], v[192:195], v[234:237], v[4:7]
	v_mfma_f32_16x16x32_bf16 v[4:7], v[188:191], v[230:233], v[4:7]
	v_mfma_f32_16x16x32_bf16 v[0:3], v[196:199], v[230:233], v[0:3]
	v_mfma_f32_16x16x32_bf16 v[0:3], v[200:203], v[234:237], v[0:3]
	v_mfma_f32_16x16x32_bf16 v[16:19], v[200:203], v[224:227], v[16:19]
	v_mfma_f32_16x16x32_bf16 v[16:19], v[196:199], v[220:223], v[16:19]
	v_mfma_f32_16x16x32_bf16 v[32:35], v[196:199], v[212:215], v[32:35]
	v_mfma_f32_16x16x32_bf16 v[32:35], v[200:203], v[216:219], v[32:35]
	v_mfma_f32_16x16x32_bf16 v[48:51], v[200:203], v[208:211], v[48:51]
	v_mfma_f32_16x16x32_bf16 v[48:51], v[196:199], v[204:207], v[48:51]
	s_barrier
	s_setprio 0
	s_add_i32 s69, s69, 2
	s_add_u32 s52, s52, 0x100
	s_addc_u32 s53, s53, 0
	s_add_u32 s67, s67, 0x100
	s_addc_u32 s68, s68, 0
	s_cmp_gt_u32 s69, 13
.LBB0_313:
	ds_read_b128 v[128:131], v179
	ds_read_b128 v[132:135], v179 offset:1024
	ds_read_b128 v[136:139], v179 offset:2048
	ds_read_b128 v[140:143], v179 offset:3072
	ds_read_b128 v[188:191], v181
	ds_read_b128 v[192:195], v181 offset:1024
	ds_read_b128 v[196:199], v181 offset:2048
	ds_read_b128 v[200:203], v181 offset:3072
	s_add_u32 s54, s52, 0xfffc0080
	s_addc_u32 s55, s53, -1
	s_cmp_eq_u32 s69, 12
	s_cselect_b32 s57, s10, s55
	s_cselect_b32 s56, s43, s54
	s_cselect_b32 s55, s45, s68
	s_cselect_b32 s54, s51, s67
	v_lshl_add_u64 v[238:239], s[52:53], 0, v[162:163]
	s_add_i32 m0, s75, 0xc000
	ds_read_b128 v[204:207], v183
	ds_read_b128 v[208:211], v183 offset:1024
	ds_read_b128 v[212:215], v183 offset:2048
	ds_read_b128 v[216:219], v183 offset:3072
	ds_read_b128 v[220:223], v183 offset:4096
	ds_read_b128 v[224:227], v183 offset:5120
	ds_read_b128 v[230:233], v183 offset:6144
	ds_read_b128 v[234:237], v183 offset:7168
	global_load_lds_dwordx4 v[238:239], off
	v_lshl_add_u64 v[238:239], s[52:53], 0, v[164:165]
	s_add_i32 m0, s75, 0xe000
	s_nop 0
	global_load_lds_dwordx4 v[238:239], off
	s_waitcnt vmcnt(8)
	s_waitcnt lgkmcnt(0)
	s_setprio 1
	s_barrier
	v_mfma_f32_16x16x32_bf16 v[124:127], v[128:131], v[204:207], v[124:127]
	v_mfma_f32_16x16x32_bf16 v[124:127], v[132:135], v[208:211], v[124:127]
	v_mfma_f32_16x16x32_bf16 v[108:111], v[132:135], v[216:219], v[108:111]
	v_mfma_f32_16x16x32_bf16 v[108:111], v[128:131], v[212:215], v[108:111]
	v_mfma_f32_16x16x32_bf16 v[92:95], v[128:131], v[220:223], v[92:95]
	v_mfma_f32_16x16x32_bf16 v[92:95], v[132:135], v[224:227], v[92:95]
	v_mfma_f32_16x16x32_bf16 v[76:79], v[132:135], v[234:237], v[76:79]
	v_mfma_f32_16x16x32_bf16 v[76:79], v[128:131], v[230:233], v[76:79]
	v_mfma_f32_16x16x32_bf16 v[72:75], v[136:139], v[230:233], v[72:75]
	v_mfma_f32_16x16x32_bf16 v[72:75], v[140:143], v[234:237], v[72:75]
	v_mfma_f32_16x16x32_bf16 v[88:91], v[140:143], v[224:227], v[88:91]
	v_mfma_f32_16x16x32_bf16 v[88:91], v[136:139], v[220:223], v[88:91]
	v_mfma_f32_16x16x32_bf16 v[104:107], v[136:139], v[212:215], v[104:107]
	v_mfma_f32_16x16x32_bf16 v[104:107], v[140:143], v[216:219], v[104:107]
	v_mfma_f32_16x16x32_bf16 v[120:123], v[140:143], v[208:211], v[120:123]
	v_mfma_f32_16x16x32_bf16 v[120:123], v[136:139], v[204:207], v[120:123]
	v_mfma_f32_16x16x32_bf16 v[116:119], v[188:191], v[204:207], v[116:119]
	v_mfma_f32_16x16x32_bf16 v[116:119], v[192:195], v[208:211], v[116:119]
	v_mfma_f32_16x16x32_bf16 v[100:103], v[192:195], v[216:219], v[100:103]
	v_mfma_f32_16x16x32_bf16 v[100:103], v[188:191], v[212:215], v[100:103]
	v_mfma_f32_16x16x32_bf16 v[84:87], v[188:191], v[220:223], v[84:87]
	v_mfma_f32_16x16x32_bf16 v[84:87], v[192:195], v[224:227], v[84:87]
	v_mfma_f32_16x16x32_bf16 v[68:71], v[192:195], v[234:237], v[68:71]
	v_mfma_f32_16x16x32_bf16 v[68:71], v[188:191], v[230:233], v[68:71]
	v_mfma_f32_16x16x32_bf16 v[64:67], v[196:199], v[230:233], v[64:67]
	v_mfma_f32_16x16x32_bf16 v[64:67], v[200:203], v[234:237], v[64:67]
	v_mfma_f32_16x16x32_bf16 v[80:83], v[200:203], v[224:227], v[80:83]
	v_mfma_f32_16x16x32_bf16 v[80:83], v[196:199], v[220:223], v[80:83]
	v_mfma_f32_16x16x32_bf16 v[96:99], v[196:199], v[212:215], v[96:99]
	v_mfma_f32_16x16x32_bf16 v[96:99], v[200:203], v[216:219], v[96:99]
	v_mfma_f32_16x16x32_bf16 v[112:115], v[200:203], v[208:211], v[112:115]
	v_mfma_f32_16x16x32_bf16 v[112:115], v[196:199], v[204:207], v[112:115]
	s_barrier
	s_setprio 0
	s_add_i32 vcc_lo, s92, s72
	v_lshl_add_u64 v[238:239], s[54:55], 0, v[148:149]
	s_mov_b32 m0, vcc_lo
	ds_read_b128 v[204:207], v183 offset:16384
	ds_read_b128 v[208:211], v183 offset:17408
	ds_read_b128 v[212:215], v183 offset:18432
	ds_read_b128 v[216:219], v183 offset:19456
	ds_read_b128 v[220:223], v183 offset:20480
	ds_read_b128 v[224:227], v183 offset:21504
	ds_read_b128 v[230:233], v183 offset:22528
	ds_read_b128 v[234:237], v183 offset:23552
	global_load_lds_dwordx4 v[238:239], off
	s_add_i32 m0, vcc_lo, 0x2000
	s_add_u32 vcc_lo, s54, 0x40000
	v_lshl_add_u64 v[240:241], s[54:55], 0, v[144:145]
	s_addc_u32 vcc_hi, s55, 0
	s_add_i32 s83, s93, s72
	global_load_lds_dwordx4 v[240:241], off
	v_lshl_add_u64 v[242:243], vcc, 0, v[148:149]
	s_mov_b32 m0, s83
	v_lshl_add_u64 v[244:245], s[56:57], 0, v[146:147]
	global_load_lds_dwordx4 v[242:243], off
	v_lshl_add_u64 v[242:243], vcc, 0, v[144:145]
	s_add_i32 m0, s83, 0x2000
	s_nop 0
	global_load_lds_dwordx4 v[242:243], off
	v_lshl_add_u64 v[242:243], s[56:57], 0, v[150:151]
	s_mov_b32 m0, s75
	s_nop 0
	global_load_lds_dwordx4 v[242:243], off
	s_mov_b32 m0, s76
	s_nop 0
	global_load_lds_dwordx4 v[244:245], off
	s_waitcnt vmcnt(8)
	s_waitcnt lgkmcnt(0)
	s_setprio 1
	s_barrier
	v_mfma_f32_16x16x32_bf16 v[60:63], v[128:131], v[204:207], v[60:63]
	v_mfma_f32_16x16x32_bf16 v[60:63], v[132:135], v[208:211], v[60:63]
	v_mfma_f32_16x16x32_bf16 v[44:47], v[132:135], v[216:219], v[44:47]
	v_mfma_f32_16x16x32_bf16 v[44:47], v[128:131], v[212:215], v[44:47]
	v_mfma_f32_16x16x32_bf16 v[28:31], v[128:131], v[220:223], v[28:31]
	v_mfma_f32_16x16x32_bf16 v[28:31], v[132:135], v[224:227], v[28:31]
	v_mfma_f32_16x16x32_bf16 v[12:15], v[132:135], v[234:237], v[12:15]
	v_mfma_f32_16x16x32_bf16 v[12:15], v[128:131], v[230:233], v[12:15]
	v_mfma_f32_16x16x32_bf16 v[8:11], v[136:139], v[230:233], v[8:11]
	v_mfma_f32_16x16x32_bf16 v[8:11], v[140:143], v[234:237], v[8:11]
	v_mfma_f32_16x16x32_bf16 v[24:27], v[140:143], v[224:227], v[24:27]
	v_mfma_f32_16x16x32_bf16 v[24:27], v[136:139], v[220:223], v[24:27]
	v_mfma_f32_16x16x32_bf16 v[40:43], v[136:139], v[212:215], v[40:43]
	v_mfma_f32_16x16x32_bf16 v[40:43], v[140:143], v[216:219], v[40:43]
	v_mfma_f32_16x16x32_bf16 v[56:59], v[140:143], v[208:211], v[56:59]
	v_mfma_f32_16x16x32_bf16 v[56:59], v[136:139], v[204:207], v[56:59]
	v_mfma_f32_16x16x32_bf16 v[52:55], v[188:191], v[204:207], v[52:55]
	v_mfma_f32_16x16x32_bf16 v[52:55], v[192:195], v[208:211], v[52:55]
	v_mfma_f32_16x16x32_bf16 v[36:39], v[192:195], v[216:219], v[36:39]
	v_mfma_f32_16x16x32_bf16 v[36:39], v[188:191], v[212:215], v[36:39]
	v_mfma_f32_16x16x32_bf16 v[20:23], v[188:191], v[220:223], v[20:23]
	v_mfma_f32_16x16x32_bf16 v[20:23], v[192:195], v[224:227], v[20:23]
	v_mfma_f32_16x16x32_bf16 v[4:7], v[192:195], v[234:237], v[4:7]
	v_mfma_f32_16x16x32_bf16 v[4:7], v[188:191], v[230:233], v[4:7]
	v_mfma_f32_16x16x32_bf16 v[0:3], v[196:199], v[230:233], v[0:3]
	v_mfma_f32_16x16x32_bf16 v[0:3], v[200:203], v[234:237], v[0:3]
	v_mfma_f32_16x16x32_bf16 v[16:19], v[200:203], v[224:227], v[16:19]
	v_mfma_f32_16x16x32_bf16 v[16:19], v[196:199], v[220:223], v[16:19]
	v_mfma_f32_16x16x32_bf16 v[32:35], v[196:199], v[212:215], v[32:35]
	v_mfma_f32_16x16x32_bf16 v[32:35], v[200:203], v[216:219], v[32:35]
	v_mfma_f32_16x16x32_bf16 v[48:51], v[200:203], v[208:211], v[48:51]
	v_mfma_f32_16x16x32_bf16 v[48:51], v[196:199], v[204:207], v[48:51]
	s_barrier
	s_setprio 0
	s_add_i32 s83, 0, 0x18000
	s_add_i32 vcc_lo, 0, 0x1c000
	v_add_u32_e32 v140, s83, v157
	v_add_u32_e32 v171, vcc_lo, v157
	ds_read_b128 v[128:131], v140
	ds_read_b128 v[132:135], v140 offset:1024
	ds_read_b128 v[136:139], v140 offset:2048
	ds_read_b128 v[140:143], v140 offset:3072
	ds_read_b128 v[188:191], v171
	ds_read_b128 v[192:195], v171 offset:1024
	ds_read_b128 v[196:199], v171 offset:2048
	ds_read_b128 v[200:203], v171 offset:3072
	s_add_u32 s56, s56, 0x40000
	s_addc_u32 s57, s57, 0
	s_mov_b32 m0, s77
	v_lshl_add_u64 v[246:247], s[56:57], 0, v[150:151]
	ds_read_b128 v[204:207], v183 offset:32768
	ds_read_b128 v[208:211], v183 offset:33792
	ds_read_b128 v[212:215], v183 offset:34816
	ds_read_b128 v[216:219], v183 offset:35840
	ds_read_b128 v[220:223], v183 offset:36864
	ds_read_b128 v[224:227], v183 offset:37888
	ds_read_b128 v[230:233], v183 offset:38912
	ds_read_b128 v[234:237], v183 offset:39936
	global_load_lds_dwordx4 v[246:247], off
	v_lshl_add_u64 v[246:247], s[56:57], 0, v[146:147]
	s_mov_b32 m0, s78
	s_nop 0
	global_load_lds_dwordx4 v[246:247], off
	s_waitcnt vmcnt(8)
	s_waitcnt lgkmcnt(0)
	s_setprio 1
	s_barrier
	v_mfma_f32_16x16x32_bf16 v[124:127], v[128:131], v[204:207], v[124:127]
	v_mfma_f32_16x16x32_bf16 v[124:127], v[132:135], v[208:211], v[124:127]
	v_mfma_f32_16x16x32_bf16 v[108:111], v[132:135], v[216:219], v[108:111]
	v_mfma_f32_16x16x32_bf16 v[108:111], v[128:131], v[212:215], v[108:111]
	v_mfma_f32_16x16x32_bf16 v[92:95], v[128:131], v[220:223], v[92:95]
	v_mfma_f32_16x16x32_bf16 v[92:95], v[132:135], v[224:227], v[92:95]
	v_mfma_f32_16x16x32_bf16 v[76:79], v[132:135], v[234:237], v[76:79]
	v_mfma_f32_16x16x32_bf16 v[76:79], v[128:131], v[230:233], v[76:79]
	v_mfma_f32_16x16x32_bf16 v[72:75], v[136:139], v[230:233], v[72:75]
	v_mfma_f32_16x16x32_bf16 v[72:75], v[140:143], v[234:237], v[72:75]
	v_mfma_f32_16x16x32_bf16 v[88:91], v[140:143], v[224:227], v[88:91]
	v_mfma_f32_16x16x32_bf16 v[88:91], v[136:139], v[220:223], v[88:91]
	v_mfma_f32_16x16x32_bf16 v[104:107], v[136:139], v[212:215], v[104:107]
	v_mfma_f32_16x16x32_bf16 v[104:107], v[140:143], v[216:219], v[104:107]
	v_mfma_f32_16x16x32_bf16 v[120:123], v[140:143], v[208:211], v[120:123]
	v_mfma_f32_16x16x32_bf16 v[120:123], v[136:139], v[204:207], v[120:123]
	v_mfma_f32_16x16x32_bf16 v[116:119], v[188:191], v[204:207], v[116:119]
	v_mfma_f32_16x16x32_bf16 v[116:119], v[192:195], v[208:211], v[116:119]
	v_mfma_f32_16x16x32_bf16 v[100:103], v[192:195], v[216:219], v[100:103]
	v_mfma_f32_16x16x32_bf16 v[100:103], v[188:191], v[212:215], v[100:103]
	v_mfma_f32_16x16x32_bf16 v[84:87], v[188:191], v[220:223], v[84:87]
	v_mfma_f32_16x16x32_bf16 v[84:87], v[192:195], v[224:227], v[84:87]
	v_mfma_f32_16x16x32_bf16 v[68:71], v[192:195], v[234:237], v[68:71]
	v_mfma_f32_16x16x32_bf16 v[68:71], v[188:191], v[230:233], v[68:71]
	v_mfma_f32_16x16x32_bf16 v[64:67], v[196:199], v[230:233], v[64:67]
	v_mfma_f32_16x16x32_bf16 v[64:67], v[200:203], v[234:237], v[64:67]
	v_mfma_f32_16x16x32_bf16 v[80:83], v[200:203], v[224:227], v[80:83]
	v_mfma_f32_16x16x32_bf16 v[80:83], v[196:199], v[220:223], v[80:83]
	v_mfma_f32_16x16x32_bf16 v[96:99], v[196:199], v[212:215], v[96:99]
	v_mfma_f32_16x16x32_bf16 v[96:99], v[200:203], v[216:219], v[96:99]
	v_mfma_f32_16x16x32_bf16 v[112:115], v[200:203], v[208:211], v[112:115]
	v_mfma_f32_16x16x32_bf16 v[112:115], v[196:199], v[204:207], v[112:115]
	s_barrier
	s_setprio 0
	s_add_i32 s56, s83, s72
	v_lshl_add_u64 v[238:239], v[238:239], 0, s[38:39]
	s_mov_b32 m0, s56
	ds_read_b128 v[204:207], v183 offset:49152
	ds_read_b128 v[208:211], v183 offset:50176
	ds_read_b128 v[212:215], v183 offset:51200
	ds_read_b128 v[216:219], v183 offset:52224
	ds_read_b128 v[220:223], v183 offset:53248
	ds_read_b128 v[224:227], v183 offset:54272
	ds_read_b128 v[230:233], v183 offset:55296
	ds_read_b128 v[234:237], v183 offset:56320
	global_load_lds_dwordx4 v[238:239], off
	s_add_i32 m0, s56, 0x2000
	s_add_u32 s54, s54, 0x40080
	v_lshl_add_u64 v[238:239], v[240:241], 0, s[38:39]
	s_addc_u32 s55, s55, 0
	s_add_i32 s56, vcc_lo, s72
	global_load_lds_dwordx4 v[238:239], off
	v_lshl_add_u64 v[238:239], s[54:55], 0, v[148:149]
	s_mov_b32 m0, s56
	s_nop 0
	global_load_lds_dwordx4 v[238:239], off
	v_lshl_add_u64 v[238:239], s[54:55], 0, v[144:145]
	s_add_i32 m0, s56, 0x2000
	s_nop 0
	global_load_lds_dwordx4 v[238:239], off
	v_lshl_add_u64 v[238:239], v[242:243], 0, s[38:39]
	s_mov_b32 m0, s87
	s_nop 0
	global_load_lds_dwordx4 v[238:239], off
	v_lshl_add_u64 v[238:239], v[244:245], 0, s[38:39]
	s_mov_b32 m0, s88
	s_nop 0
	global_load_lds_dwordx4 v[238:239], off
	s_waitcnt vmcnt(8)
	s_waitcnt lgkmcnt(0)
	s_setprio 1
	s_barrier
	v_mfma_f32_16x16x32_bf16 v[60:63], v[128:131], v[204:207], v[60:63]
	v_mfma_f32_16x16x32_bf16 v[60:63], v[132:135], v[208:211], v[60:63]
	v_mfma_f32_16x16x32_bf16 v[44:47], v[132:135], v[216:219], v[44:47]
	v_mfma_f32_16x16x32_bf16 v[44:47], v[128:131], v[212:215], v[44:47]
	v_mfma_f32_16x16x32_bf16 v[28:31], v[128:131], v[220:223], v[28:31]
	v_mfma_f32_16x16x32_bf16 v[28:31], v[132:135], v[224:227], v[28:31]
	v_mfma_f32_16x16x32_bf16 v[12:15], v[132:135], v[234:237], v[12:15]
	v_mfma_f32_16x16x32_bf16 v[12:15], v[128:131], v[230:233], v[12:15]
	v_mfma_f32_16x16x32_bf16 v[8:11], v[136:139], v[230:233], v[8:11]
	v_mfma_f32_16x16x32_bf16 v[8:11], v[140:143], v[234:237], v[8:11]
	v_mfma_f32_16x16x32_bf16 v[24:27], v[140:143], v[224:227], v[24:27]
	v_mfma_f32_16x16x32_bf16 v[24:27], v[136:139], v[220:223], v[24:27]
	v_mfma_f32_16x16x32_bf16 v[40:43], v[136:139], v[212:215], v[40:43]
	v_mfma_f32_16x16x32_bf16 v[40:43], v[140:143], v[216:219], v[40:43]
	v_mfma_f32_16x16x32_bf16 v[56:59], v[140:143], v[208:211], v[56:59]
	v_mfma_f32_16x16x32_bf16 v[56:59], v[136:139], v[204:207], v[56:59]
	v_mfma_f32_16x16x32_bf16 v[52:55], v[188:191], v[204:207], v[52:55]
	v_mfma_f32_16x16x32_bf16 v[52:55], v[192:195], v[208:211], v[52:55]
	v_mfma_f32_16x16x32_bf16 v[36:39], v[192:195], v[216:219], v[36:39]
	v_mfma_f32_16x16x32_bf16 v[36:39], v[188:191], v[212:215], v[36:39]
	v_mfma_f32_16x16x32_bf16 v[20:23], v[188:191], v[220:223], v[20:23]
	v_mfma_f32_16x16x32_bf16 v[20:23], v[192:195], v[224:227], v[20:23]
	v_mfma_f32_16x16x32_bf16 v[4:7], v[192:195], v[234:237], v[4:7]
	v_mfma_f32_16x16x32_bf16 v[4:7], v[188:191], v[230:233], v[4:7]
	v_mfma_f32_16x16x32_bf16 v[0:3], v[196:199], v[230:233], v[0:3]
	v_mfma_f32_16x16x32_bf16 v[0:3], v[200:203], v[234:237], v[0:3]
	v_mfma_f32_16x16x32_bf16 v[16:19], v[200:203], v[224:227], v[16:19]
	v_mfma_f32_16x16x32_bf16 v[16:19], v[196:199], v[220:223], v[16:19]
	v_mfma_f32_16x16x32_bf16 v[32:35], v[196:199], v[212:215], v[32:35]
	v_mfma_f32_16x16x32_bf16 v[32:35], v[200:203], v[216:219], v[32:35]
	v_mfma_f32_16x16x32_bf16 v[48:51], v[200:203], v[208:211], v[48:51]
	v_mfma_f32_16x16x32_bf16 v[48:51], v[196:199], v[204:207], v[48:51]
	s_barrier
	s_setprio 0
	s_add_i32 s69, s69, 2
	s_add_u32 s52, s52, 0x100
	s_addc_u32 s53, s53, 0
	s_add_u32 s67, s67, 0x100
	s_addc_u32 s68, s68, 0
	s_cmp_gt_u32 s69, 13
	s_cbranch_scc0 .LBB0_313
	s_and_b64 vcc, exec, s[40:41]
	s_cbranch_vccz .LBB0_316
	s_barrier

.LBB0_667:
	s_ashr_i32 s23, s22, 31
	s_lshl_b64 s[38:39], s[22:23], 19
	s_add_u32 s38, s26, s38
	s_addc_u32 s39, s27, s39
	s_and_b64 s[40:41], s[6:7], exec
	s_cselect_b32 s23, s39, s45
	s_cselect_b32 s43, s38, s44
	s_ashr_i32 s37, s36, 31
	s_lshl_b64 s[40:41], s[36:37], 19
	s_add_u32 s40, s50, s40
	s_addc_u32 s41, s51, s41
	s_and_b64 s[48:49], s[6:7], exec
	s_cselect_b32 s37, s41, s47
	s_cselect_b32 s92, s40, s46
	s_add_u32 s44, s44, 0x40080
	s_addc_u32 s45, s45, 0
	s_add_u32 s93, s46, 0x100
	s_addc_u32 s94, s47, 0
	s_mov_b32 s95, -2
	s_waitcnt lgkmcnt(0)
	ds_read_b128 v[80:83], v216
	ds_read_b128 v[84:87], v216 offset:1024
	ds_read_b128 v[104:107], v216 offset:2048
	ds_read_b128 v[108:111], v216 offset:3072
	ds_read_b128 v[128:131], v217
	ds_read_b128 v[132:135], v217 offset:1024
	ds_read_b128 v[152:155], v217 offset:2048
	ds_read_b128 v[156:159], v217 offset:3072
	s_add_u32 s46, s44, 0xfffc0080
	s_addc_u32 s47, s45, -1
	s_cmp_eq_u32 s95, 12
	s_cselect_b32 s49, s23, s47
	s_cselect_b32 s48, s43, s46
	s_cselect_b32 s47, s37, s94
	s_cselect_b32 s46, s92, s93
	v_lshl_add_u64 v[224:225], s[44:45], 0, v[194:195]
	s_add_i32 m0, s53, 0xc000
	ds_read_b128 v[160:163], v218
	ds_read_b128 v[164:167], v218 offset:1024
	ds_read_b128 v[168:171], v218 offset:2048
	ds_read_b128 v[172:175], v218 offset:3072
	ds_read_b128 v[176:179], v218 offset:4096
	ds_read_b128 v[180:183], v218 offset:5120
	ds_read_b128 v[208:211], v218 offset:6144
	ds_read_b128 v[220:223], v218 offset:7168
	global_load_lds_dwordx4 v[224:225], off
	v_lshl_add_u64 v[224:225], s[44:45], 0, v[196:197]
	s_add_i32 m0, s53, 0xe000
	s_nop 0
	global_load_lds_dwordx4 v[224:225], off
	s_waitcnt vmcnt(8)
	s_waitcnt lgkmcnt(0)
	s_setprio 1
	s_barrier
	v_mfma_f32_16x16x32_bf16 v[148:151], v[80:83], v[160:163], 0
	v_mfma_f32_16x16x32_bf16 v[148:151], v[84:87], v[164:167], v[148:151]
	v_mfma_f32_16x16x32_bf16 v[124:127], v[84:87], v[172:175], 0
	v_mfma_f32_16x16x32_bf16 v[124:127], v[80:83], v[168:171], v[124:127]
	v_mfma_f32_16x16x32_bf16 v[100:103], v[80:83], v[176:179], 0
	v_mfma_f32_16x16x32_bf16 v[100:103], v[84:87], v[180:183], v[100:103]
	v_mfma_f32_16x16x32_bf16 v[76:79], v[84:87], v[220:223], 0
	v_mfma_f32_16x16x32_bf16 v[76:79], v[80:83], v[208:211], v[76:79]
	v_mfma_f32_16x16x32_bf16 v[72:75], v[104:107], v[208:211], 0
	v_mfma_f32_16x16x32_bf16 v[72:75], v[108:111], v[220:223], v[72:75]
	v_mfma_f32_16x16x32_bf16 v[96:99], v[108:111], v[180:183], 0
	v_mfma_f32_16x16x32_bf16 v[96:99], v[104:107], v[176:179], v[96:99]
	v_mfma_f32_16x16x32_bf16 v[120:123], v[104:107], v[168:171], 0
	v_mfma_f32_16x16x32_bf16 v[120:123], v[108:111], v[172:175], v[120:123]
	v_mfma_f32_16x16x32_bf16 v[144:147], v[108:111], v[164:167], 0
	v_mfma_f32_16x16x32_bf16 v[144:147], v[104:107], v[160:163], v[144:147]
	v_mfma_f32_16x16x32_bf16 v[140:143], v[128:131], v[160:163], 0
	v_mfma_f32_16x16x32_bf16 v[140:143], v[132:135], v[164:167], v[140:143]
	v_mfma_f32_16x16x32_bf16 v[116:119], v[132:135], v[172:175], 0
	v_mfma_f32_16x16x32_bf16 v[116:119], v[128:131], v[168:171], v[116:119]
	v_mfma_f32_16x16x32_bf16 v[92:95], v[128:131], v[176:179], 0
	v_mfma_f32_16x16x32_bf16 v[92:95], v[132:135], v[180:183], v[92:95]
	v_mfma_f32_16x16x32_bf16 v[68:71], v[132:135], v[220:223], 0
	v_mfma_f32_16x16x32_bf16 v[68:71], v[128:131], v[208:211], v[68:71]
	v_mfma_f32_16x16x32_bf16 v[64:67], v[152:155], v[208:211], 0
	v_mfma_f32_16x16x32_bf16 v[64:67], v[156:159], v[220:223], v[64:67]
	v_mfma_f32_16x16x32_bf16 v[88:91], v[156:159], v[180:183], 0
	v_mfma_f32_16x16x32_bf16 v[88:91], v[152:155], v[176:179], v[88:91]
	v_mfma_f32_16x16x32_bf16 v[112:115], v[152:155], v[168:171], 0
	v_mfma_f32_16x16x32_bf16 v[112:115], v[156:159], v[172:175], v[112:115]
	v_mfma_f32_16x16x32_bf16 v[136:139], v[156:159], v[164:167], 0
	v_mfma_f32_16x16x32_bf16 v[136:139], v[152:155], v[160:163], v[136:139]
	s_barrier
	s_setprio 0
	s_add_i32 s83, s78, s52
	v_lshl_add_u64 v[224:225], s[46:47], 0, v[186:187]
	s_mov_b32 m0, s83
	ds_read_b128 v[160:163], v218 offset:16384
	ds_read_b128 v[164:167], v218 offset:17408
	ds_read_b128 v[168:171], v218 offset:18432
	ds_read_b128 v[172:175], v218 offset:19456
	ds_read_b128 v[176:179], v218 offset:20480
	ds_read_b128 v[180:183], v218 offset:21504
	ds_read_b128 v[208:211], v218 offset:22528
	ds_read_b128 v[220:223], v218 offset:23552
	global_load_lds_dwordx4 v[224:225], off
	s_add_i32 m0, s83, 0x2000
	s_add_u32 s96, s46, 0x40000
	v_lshl_add_u64 v[226:227], s[46:47], 0, v[190:191]
	s_addc_u32 s97, s47, 0
	s_add_i32 s83, s79, s52
	global_load_lds_dwordx4 v[226:227], off
	v_lshl_add_u64 v[230:231], s[96:97], 0, v[186:187]
	s_mov_b32 m0, s83
	v_lshl_add_u64 v[232:233], s[48:49], 0, v[188:189]
	global_load_lds_dwordx4 v[230:231], off
	v_lshl_add_u64 v[230:231], s[96:97], 0, v[190:191]
	s_add_i32 m0, s83, 0x2000
	s_nop 0
	global_load_lds_dwordx4 v[230:231], off
	v_lshl_add_u64 v[230:231], s[48:49], 0, v[184:185]
	s_mov_b32 m0, s53
	s_nop 0
	global_load_lds_dwordx4 v[230:231], off
	s_mov_b32 m0, s54
	s_nop 0
	global_load_lds_dwordx4 v[232:233], off
	s_waitcnt vmcnt(8)
	s_waitcnt lgkmcnt(0)
	s_setprio 1
	s_barrier
	v_mfma_f32_16x16x32_bf16 v[60:63], v[80:83], v[160:163], 0
	v_mfma_f32_16x16x32_bf16 v[60:63], v[84:87], v[164:167], v[60:63]
	v_mfma_f32_16x16x32_bf16 v[44:47], v[84:87], v[172:175], 0
	v_mfma_f32_16x16x32_bf16 v[44:47], v[80:83], v[168:171], v[44:47]
	v_mfma_f32_16x16x32_bf16 v[28:31], v[80:83], v[176:179], 0
	v_mfma_f32_16x16x32_bf16 v[28:31], v[84:87], v[180:183], v[28:31]
	v_mfma_f32_16x16x32_bf16 v[12:15], v[84:87], v[220:223], 0
	v_mfma_f32_16x16x32_bf16 v[12:15], v[80:83], v[208:211], v[12:15]
	v_mfma_f32_16x16x32_bf16 v[8:11], v[104:107], v[208:211], 0
	v_mfma_f32_16x16x32_bf16 v[8:11], v[108:111], v[220:223], v[8:11]
	v_mfma_f32_16x16x32_bf16 v[24:27], v[108:111], v[180:183], 0
	v_mfma_f32_16x16x32_bf16 v[24:27], v[104:107], v[176:179], v[24:27]
	v_mfma_f32_16x16x32_bf16 v[40:43], v[104:107], v[168:171], 0
	v_mfma_f32_16x16x32_bf16 v[40:43], v[108:111], v[172:175], v[40:43]
	v_mfma_f32_16x16x32_bf16 v[56:59], v[108:111], v[164:167], 0
	v_mfma_f32_16x16x32_bf16 v[56:59], v[104:107], v[160:163], v[56:59]
	v_mfma_f32_16x16x32_bf16 v[52:55], v[128:131], v[160:163], 0
	v_mfma_f32_16x16x32_bf16 v[52:55], v[132:135], v[164:167], v[52:55]
	v_mfma_f32_16x16x32_bf16 v[36:39], v[132:135], v[172:175], 0
	v_mfma_f32_16x16x32_bf16 v[36:39], v[128:131], v[168:171], v[36:39]
	v_mfma_f32_16x16x32_bf16 v[20:23], v[128:131], v[176:179], 0
	v_mfma_f32_16x16x32_bf16 v[20:23], v[132:135], v[180:183], v[20:23]
	v_mfma_f32_16x16x32_bf16 v[4:7], v[132:135], v[220:223], 0
	v_mfma_f32_16x16x32_bf16 v[4:7], v[128:131], v[208:211], v[4:7]
	v_mfma_f32_16x16x32_bf16 v[0:3], v[152:155], v[208:211], 0
	v_mfma_f32_16x16x32_bf16 v[0:3], v[156:159], v[220:223], v[0:3]
	v_mfma_f32_16x16x32_bf16 v[16:19], v[156:159], v[180:183], 0
	v_mfma_f32_16x16x32_bf16 v[16:19], v[152:155], v[176:179], v[16:19]
	v_mfma_f32_16x16x32_bf16 v[32:35], v[152:155], v[168:171], 0
	v_mfma_f32_16x16x32_bf16 v[32:35], v[156:159], v[172:175], v[32:35]
	v_mfma_f32_16x16x32_bf16 v[48:51], v[156:159], v[164:167], 0
	v_mfma_f32_16x16x32_bf16 v[48:51], v[152:155], v[160:163], v[48:51]
	s_barrier
	s_setprio 0
	s_add_i32 s83, 0, 0x18000
	s_add_i32 s96, 0, 0x1c000
	v_add_u32_e32 v108, s83, v213
	v_add_u32_e32 v156, s96, v213
	ds_read_b128 v[80:83], v108
	ds_read_b128 v[84:87], v108 offset:1024
	ds_read_b128 v[104:107], v108 offset:2048
	ds_read_b128 v[108:111], v108 offset:3072
	ds_read_b128 v[128:131], v156
	ds_read_b128 v[132:135], v156 offset:1024
	ds_read_b128 v[152:155], v156 offset:2048
	ds_read_b128 v[156:159], v156 offset:3072
	s_add_u32 s48, s48, 0x40000
	s_addc_u32 s49, s49, 0
	s_mov_b32 m0, s55
	v_lshl_add_u64 v[234:235], s[48:49], 0, v[184:185]
	ds_read_b128 v[160:163], v218 offset:32768
	ds_read_b128 v[164:167], v218 offset:33792
	ds_read_b128 v[168:171], v218 offset:34816
	ds_read_b128 v[172:175], v218 offset:35840
	ds_read_b128 v[176:179], v218 offset:36864
	ds_read_b128 v[180:183], v218 offset:37888
	ds_read_b128 v[208:211], v218 offset:38912
	ds_read_b128 v[220:223], v218 offset:39936
	global_load_lds_dwordx4 v[234:235], off
	v_lshl_add_u64 v[234:235], s[48:49], 0, v[188:189]
	s_mov_b32 m0, s56
	s_nop 0
	global_load_lds_dwordx4 v[234:235], off
	s_waitcnt vmcnt(8)
	s_waitcnt lgkmcnt(0)
	s_setprio 1
	s_barrier
	v_mfma_f32_16x16x32_bf16 v[148:151], v[80:83], v[160:163], v[148:151]
	v_mfma_f32_16x16x32_bf16 v[148:151], v[84:87], v[164:167], v[148:151]
	v_mfma_f32_16x16x32_bf16 v[124:127], v[84:87], v[172:175], v[124:127]
	v_mfma_f32_16x16x32_bf16 v[124:127], v[80:83], v[168:171], v[124:127]
	v_mfma_f32_16x16x32_bf16 v[100:103], v[80:83], v[176:179], v[100:103]
	v_mfma_f32_16x16x32_bf16 v[100:103], v[84:87], v[180:183], v[100:103]
	v_mfma_f32_16x16x32_bf16 v[76:79], v[84:87], v[220:223], v[76:79]
	v_mfma_f32_16x16x32_bf16 v[76:79], v[80:83], v[208:211], v[76:79]
	v_mfma_f32_16x16x32_bf16 v[72:75], v[104:107], v[208:211], v[72:75]
	v_mfma_f32_16x16x32_bf16 v[72:75], v[108:111], v[220:223], v[72:75]
	v_mfma_f32_16x16x32_bf16 v[96:99], v[108:111], v[180:183], v[96:99]
	v_mfma_f32_16x16x32_bf16 v[96:99], v[104:107], v[176:179], v[96:99]
	v_mfma_f32_16x16x32_bf16 v[120:123], v[104:107], v[168:171], v[120:123]
	v_mfma_f32_16x16x32_bf16 v[120:123], v[108:111], v[172:175], v[120:123]
	v_mfma_f32_16x16x32_bf16 v[144:147], v[108:111], v[164:167], v[144:147]
	v_mfma_f32_16x16x32_bf16 v[144:147], v[104:107], v[160:163], v[144:147]
	v_mfma_f32_16x16x32_bf16 v[140:143], v[128:131], v[160:163], v[140:143]
	v_mfma_f32_16x16x32_bf16 v[140:143], v[132:135], v[164:167], v[140:143]
	v_mfma_f32_16x16x32_bf16 v[116:119], v[132:135], v[172:175], v[116:119]
	v_mfma_f32_16x16x32_bf16 v[116:119], v[128:131], v[168:171], v[116:119]
	v_mfma_f32_16x16x32_bf16 v[92:95], v[128:131], v[176:179], v[92:95]
	v_mfma_f32_16x16x32_bf16 v[92:95], v[132:135], v[180:183], v[92:95]
	v_mfma_f32_16x16x32_bf16 v[68:71], v[132:135], v[220:223], v[68:71]
	v_mfma_f32_16x16x32_bf16 v[68:71], v[128:131], v[208:211], v[68:71]
	v_mfma_f32_16x16x32_bf16 v[64:67], v[152:155], v[208:211], v[64:67]
	v_mfma_f32_16x16x32_bf16 v[64:67], v[156:159], v[220:223], v[64:67]
	v_mfma_f32_16x16x32_bf16 v[88:91], v[156:159], v[180:183], v[88:91]
	v_mfma_f32_16x16x32_bf16 v[88:91], v[152:155], v[176:179], v[88:91]
	v_mfma_f32_16x16x32_bf16 v[112:115], v[152:155], v[168:171], v[112:115]
	v_mfma_f32_16x16x32_bf16 v[112:115], v[156:159], v[172:175], v[112:115]
	v_mfma_f32_16x16x32_bf16 v[136:139], v[156:159], v[164:167], v[136:139]
	v_mfma_f32_16x16x32_bf16 v[136:139], v[152:155], v[160:163], v[136:139]
	s_barrier
	s_setprio 0
	s_add_i32 s48, s83, s52
	v_lshl_add_u64 v[224:225], v[224:225], 0, s[18:19]
	s_mov_b32 m0, s48
	ds_read_b128 v[160:163], v218 offset:49152
	ds_read_b128 v[164:167], v218 offset:50176
	ds_read_b128 v[168:171], v218 offset:51200
	ds_read_b128 v[172:175], v218 offset:52224
	ds_read_b128 v[176:179], v218 offset:53248
	ds_read_b128 v[180:183], v218 offset:54272
	ds_read_b128 v[208:211], v218 offset:55296
	ds_read_b128 v[220:223], v218 offset:56320
	global_load_lds_dwordx4 v[224:225], off
	s_add_i32 m0, s48, 0x2000
	s_add_u32 s46, s46, 0x40080
	v_lshl_add_u64 v[224:225], v[226:227], 0, s[18:19]
	s_addc_u32 s47, s47, 0
	s_add_i32 s48, s96, s52
	global_load_lds_dwordx4 v[224:225], off
	v_lshl_add_u64 v[224:225], s[46:47], 0, v[186:187]
	s_mov_b32 m0, s48
	s_nop 0
	global_load_lds_dwordx4 v[224:225], off
	v_lshl_add_u64 v[224:225], s[46:47], 0, v[190:191]
	s_add_i32 m0, s48, 0x2000
	s_nop 0
	global_load_lds_dwordx4 v[224:225], off
	v_lshl_add_u64 v[224:225], v[230:231], 0, s[18:19]
	s_mov_b32 m0, s68
	s_nop 0
	global_load_lds_dwordx4 v[224:225], off
	v_lshl_add_u64 v[224:225], v[232:233], 0, s[18:19]
	s_mov_b32 m0, s69
	s_nop 0
	global_load_lds_dwordx4 v[224:225], off
	s_waitcnt vmcnt(8)
	s_waitcnt lgkmcnt(0)
	s_setprio 1
	s_barrier
	v_mfma_f32_16x16x32_bf16 v[60:63], v[80:83], v[160:163], v[60:63]
	v_mfma_f32_16x16x32_bf16 v[60:63], v[84:87], v[164:167], v[60:63]
	v_mfma_f32_16x16x32_bf16 v[44:47], v[84:87], v[172:175], v[44:47]
	v_mfma_f32_16x16x32_bf16 v[44:47], v[80:83], v[168:171], v[44:47]
	v_mfma_f32_16x16x32_bf16 v[28:31], v[80:83], v[176:179], v[28:31]
	v_mfma_f32_16x16x32_bf16 v[28:31], v[84:87], v[180:183], v[28:31]
	v_mfma_f32_16x16x32_bf16 v[12:15], v[84:87], v[220:223], v[12:15]
	v_mfma_f32_16x16x32_bf16 v[12:15], v[80:83], v[208:211], v[12:15]
	v_mfma_f32_16x16x32_bf16 v[8:11], v[104:107], v[208:211], v[8:11]
	v_mfma_f32_16x16x32_bf16 v[8:11], v[108:111], v[220:223], v[8:11]
	v_mfma_f32_16x16x32_bf16 v[24:27], v[108:111], v[180:183], v[24:27]
	v_mfma_f32_16x16x32_bf16 v[24:27], v[104:107], v[176:179], v[24:27]
	v_mfma_f32_16x16x32_bf16 v[40:43], v[104:107], v[168:171], v[40:43]
	v_mfma_f32_16x16x32_bf16 v[40:43], v[108:111], v[172:175], v[40:43]
	v_mfma_f32_16x16x32_bf16 v[56:59], v[108:111], v[164:167], v[56:59]
	v_mfma_f32_16x16x32_bf16 v[56:59], v[104:107], v[160:163], v[56:59]
	v_mfma_f32_16x16x32_bf16 v[52:55], v[128:131], v[160:163], v[52:55]
	v_mfma_f32_16x16x32_bf16 v[52:55], v[132:135], v[164:167], v[52:55]
	v_mfma_f32_16x16x32_bf16 v[36:39], v[132:135], v[172:175], v[36:39]
	v_mfma_f32_16x16x32_bf16 v[36:39], v[128:131], v[168:171], v[36:39]
	v_mfma_f32_16x16x32_bf16 v[20:23], v[128:131], v[176:179], v[20:23]
	v_mfma_f32_16x16x32_bf16 v[20:23], v[132:135], v[180:183], v[20:23]
	v_mfma_f32_16x16x32_bf16 v[4:7], v[132:135], v[220:223], v[4:7]
	v_mfma_f32_16x16x32_bf16 v[4:7], v[128:131], v[208:211], v[4:7]
	v_mfma_f32_16x16x32_bf16 v[0:3], v[152:155], v[208:211], v[0:3]
	v_mfma_f32_16x16x32_bf16 v[0:3], v[156:159], v[220:223], v[0:3]
	v_mfma_f32_16x16x32_bf16 v[16:19], v[156:159], v[180:183], v[16:19]
	v_mfma_f32_16x16x32_bf16 v[16:19], v[152:155], v[176:179], v[16:19]
	v_mfma_f32_16x16x32_bf16 v[32:35], v[152:155], v[168:171], v[32:35]
	v_mfma_f32_16x16x32_bf16 v[32:35], v[156:159], v[172:175], v[32:35]
	v_mfma_f32_16x16x32_bf16 v[48:51], v[156:159], v[164:167], v[48:51]
	v_mfma_f32_16x16x32_bf16 v[48:51], v[152:155], v[160:163], v[48:51]
	s_barrier
	s_setprio 0
	s_add_i32 s95, s95, 2
	s_add_u32 s44, s44, 0x100
	s_addc_u32 s45, s45, 0
	s_add_u32 s93, s93, 0x100
	s_addc_u32 s94, s94, 0
	s_cmp_gt_u32 s95, 13
.LBB0_668:
	ds_read_b128 v[80:83], v216
	ds_read_b128 v[84:87], v216 offset:1024
	ds_read_b128 v[104:107], v216 offset:2048
	ds_read_b128 v[108:111], v216 offset:3072
	ds_read_b128 v[128:131], v217
	ds_read_b128 v[132:135], v217 offset:1024
	ds_read_b128 v[152:155], v217 offset:2048
	ds_read_b128 v[156:159], v217 offset:3072
	s_add_u32 s46, s44, 0xfffc0080
	s_addc_u32 s47, s45, -1
	s_cmp_eq_u32 s95, 12
	s_cselect_b32 s49, s23, s47
	s_cselect_b32 s48, s43, s46
	s_cselect_b32 s47, s37, s94
	s_cselect_b32 s46, s92, s93
	v_lshl_add_u64 v[224:225], s[44:45], 0, v[194:195]
	s_add_i32 m0, s53, 0xc000
	ds_read_b128 v[160:163], v218
	ds_read_b128 v[164:167], v218 offset:1024
	ds_read_b128 v[168:171], v218 offset:2048
	ds_read_b128 v[172:175], v218 offset:3072
	ds_read_b128 v[176:179], v218 offset:4096
	ds_read_b128 v[180:183], v218 offset:5120
	ds_read_b128 v[208:211], v218 offset:6144
	ds_read_b128 v[220:223], v218 offset:7168
	global_load_lds_dwordx4 v[224:225], off
	v_lshl_add_u64 v[224:225], s[44:45], 0, v[196:197]
	s_add_i32 m0, s53, 0xe000
	s_nop 0
	global_load_lds_dwordx4 v[224:225], off
	s_waitcnt vmcnt(8)
	s_waitcnt lgkmcnt(0)
	s_setprio 1
	s_barrier
	v_mfma_f32_16x16x32_bf16 v[148:151], v[80:83], v[160:163], v[148:151]
	v_mfma_f32_16x16x32_bf16 v[148:151], v[84:87], v[164:167], v[148:151]
	v_mfma_f32_16x16x32_bf16 v[124:127], v[84:87], v[172:175], v[124:127]
	v_mfma_f32_16x16x32_bf16 v[124:127], v[80:83], v[168:171], v[124:127]
	v_mfma_f32_16x16x32_bf16 v[100:103], v[80:83], v[176:179], v[100:103]
	v_mfma_f32_16x16x32_bf16 v[100:103], v[84:87], v[180:183], v[100:103]
	v_mfma_f32_16x16x32_bf16 v[76:79], v[84:87], v[220:223], v[76:79]
	v_mfma_f32_16x16x32_bf16 v[76:79], v[80:83], v[208:211], v[76:79]
	v_mfma_f32_16x16x32_bf16 v[72:75], v[104:107], v[208:211], v[72:75]
	v_mfma_f32_16x16x32_bf16 v[72:75], v[108:111], v[220:223], v[72:75]
	v_mfma_f32_16x16x32_bf16 v[96:99], v[108:111], v[180:183], v[96:99]
	v_mfma_f32_16x16x32_bf16 v[96:99], v[104:107], v[176:179], v[96:99]
	v_mfma_f32_16x16x32_bf16 v[120:123], v[104:107], v[168:171], v[120:123]
	v_mfma_f32_16x16x32_bf16 v[120:123], v[108:111], v[172:175], v[120:123]
	v_mfma_f32_16x16x32_bf16 v[144:147], v[108:111], v[164:167], v[144:147]
	v_mfma_f32_16x16x32_bf16 v[144:147], v[104:107], v[160:163], v[144:147]
	v_mfma_f32_16x16x32_bf16 v[140:143], v[128:131], v[160:163], v[140:143]
	v_mfma_f32_16x16x32_bf16 v[140:143], v[132:135], v[164:167], v[140:143]
	v_mfma_f32_16x16x32_bf16 v[116:119], v[132:135], v[172:175], v[116:119]
	v_mfma_f32_16x16x32_bf16 v[116:119], v[128:131], v[168:171], v[116:119]
	v_mfma_f32_16x16x32_bf16 v[92:95], v[128:131], v[176:179], v[92:95]
	v_mfma_f32_16x16x32_bf16 v[92:95], v[132:135], v[180:183], v[92:95]
	v_mfma_f32_16x16x32_bf16 v[68:71], v[132:135], v[220:223], v[68:71]
	v_mfma_f32_16x16x32_bf16 v[68:71], v[128:131], v[208:211], v[68:71]
	v_mfma_f32_16x16x32_bf16 v[64:67], v[152:155], v[208:211], v[64:67]
	v_mfma_f32_16x16x32_bf16 v[64:67], v[156:159], v[220:223], v[64:67]
	v_mfma_f32_16x16x32_bf16 v[88:91], v[156:159], v[180:183], v[88:91]
	v_mfma_f32_16x16x32_bf16 v[88:91], v[152:155], v[176:179], v[88:91]
	v_mfma_f32_16x16x32_bf16 v[112:115], v[152:155], v[168:171], v[112:115]
	v_mfma_f32_16x16x32_bf16 v[112:115], v[156:159], v[172:175], v[112:115]
	v_mfma_f32_16x16x32_bf16 v[136:139], v[156:159], v[164:167], v[136:139]
	v_mfma_f32_16x16x32_bf16 v[136:139], v[152:155], v[160:163], v[136:139]
	s_barrier
	s_setprio 0
	s_add_i32 s83, s78, s52
	v_lshl_add_u64 v[224:225], s[46:47], 0, v[186:187]
	s_mov_b32 m0, s83
	ds_read_b128 v[160:163], v218 offset:16384
	ds_read_b128 v[164:167], v218 offset:17408
	ds_read_b128 v[168:171], v218 offset:18432
	ds_read_b128 v[172:175], v218 offset:19456
	ds_read_b128 v[176:179], v218 offset:20480
	ds_read_b128 v[180:183], v218 offset:21504
	ds_read_b128 v[208:211], v218 offset:22528
	ds_read_b128 v[220:223], v218 offset:23552
	global_load_lds_dwordx4 v[224:225], off
	s_add_i32 m0, s83, 0x2000
	s_add_u32 s96, s46, 0x40000
	v_lshl_add_u64 v[226:227], s[46:47], 0, v[190:191]
	s_addc_u32 s97, s47, 0
	s_add_i32 s83, s79, s52
	global_load_lds_dwordx4 v[226:227], off
	v_lshl_add_u64 v[230:231], s[96:97], 0, v[186:187]
	s_mov_b32 m0, s83
	v_lshl_add_u64 v[232:233], s[48:49], 0, v[188:189]
	global_load_lds_dwordx4 v[230:231], off
	v_lshl_add_u64 v[230:231], s[96:97], 0, v[190:191]
	s_add_i32 m0, s83, 0x2000
	s_nop 0
	global_load_lds_dwordx4 v[230:231], off
	v_lshl_add_u64 v[230:231], s[48:49], 0, v[184:185]
	s_mov_b32 m0, s53
	s_nop 0
	global_load_lds_dwordx4 v[230:231], off
	s_mov_b32 m0, s54
	s_nop 0
	global_load_lds_dwordx4 v[232:233], off
	s_waitcnt vmcnt(8)
	s_waitcnt lgkmcnt(0)
	s_setprio 1
	s_barrier
	v_mfma_f32_16x16x32_bf16 v[60:63], v[80:83], v[160:163], v[60:63]
	v_mfma_f32_16x16x32_bf16 v[60:63], v[84:87], v[164:167], v[60:63]
	v_mfma_f32_16x16x32_bf16 v[44:47], v[84:87], v[172:175], v[44:47]
	v_mfma_f32_16x16x32_bf16 v[44:47], v[80:83], v[168:171], v[44:47]
	v_mfma_f32_16x16x32_bf16 v[28:31], v[80:83], v[176:179], v[28:31]
	v_mfma_f32_16x16x32_bf16 v[28:31], v[84:87], v[180:183], v[28:31]
	v_mfma_f32_16x16x32_bf16 v[12:15], v[84:87], v[220:223], v[12:15]
	v_mfma_f32_16x16x32_bf16 v[12:15], v[80:83], v[208:211], v[12:15]
	v_mfma_f32_16x16x32_bf16 v[8:11], v[104:107], v[208:211], v[8:11]
	v_mfma_f32_16x16x32_bf16 v[8:11], v[108:111], v[220:223], v[8:11]
	v_mfma_f32_16x16x32_bf16 v[24:27], v[108:111], v[180:183], v[24:27]
	v_mfma_f32_16x16x32_bf16 v[24:27], v[104:107], v[176:179], v[24:27]
	v_mfma_f32_16x16x32_bf16 v[40:43], v[104:107], v[168:171], v[40:43]
	v_mfma_f32_16x16x32_bf16 v[40:43], v[108:111], v[172:175], v[40:43]
	v_mfma_f32_16x16x32_bf16 v[56:59], v[108:111], v[164:167], v[56:59]
	v_mfma_f32_16x16x32_bf16 v[56:59], v[104:107], v[160:163], v[56:59]
	v_mfma_f32_16x16x32_bf16 v[52:55], v[128:131], v[160:163], v[52:55]
	v_mfma_f32_16x16x32_bf16 v[52:55], v[132:135], v[164:167], v[52:55]
	v_mfma_f32_16x16x32_bf16 v[36:39], v[132:135], v[172:175], v[36:39]
	v_mfma_f32_16x16x32_bf16 v[36:39], v[128:131], v[168:171], v[36:39]
	v_mfma_f32_16x16x32_bf16 v[20:23], v[128:131], v[176:179], v[20:23]
	v_mfma_f32_16x16x32_bf16 v[20:23], v[132:135], v[180:183], v[20:23]
	v_mfma_f32_16x16x32_bf16 v[4:7], v[132:135], v[220:223], v[4:7]
	v_mfma_f32_16x16x32_bf16 v[4:7], v[128:131], v[208:211], v[4:7]
	v_mfma_f32_16x16x32_bf16 v[0:3], v[152:155], v[208:211], v[0:3]
	v_mfma_f32_16x16x32_bf16 v[0:3], v[156:159], v[220:223], v[0:3]
	v_mfma_f32_16x16x32_bf16 v[16:19], v[156:159], v[180:183], v[16:19]
	v_mfma_f32_16x16x32_bf16 v[16:19], v[152:155], v[176:179], v[16:19]
	v_mfma_f32_16x16x32_bf16 v[32:35], v[152:155], v[168:171], v[32:35]
	v_mfma_f32_16x16x32_bf16 v[32:35], v[156:159], v[172:175], v[32:35]
	v_mfma_f32_16x16x32_bf16 v[48:51], v[156:159], v[164:167], v[48:51]
	v_mfma_f32_16x16x32_bf16 v[48:51], v[152:155], v[160:163], v[48:51]
	s_barrier
	s_setprio 0
	s_add_i32 s83, 0, 0x18000
	s_add_i32 s96, 0, 0x1c000
	v_add_u32_e32 v108, s83, v213
	v_add_u32_e32 v156, s96, v213
	ds_read_b128 v[80:83], v108
	ds_read_b128 v[84:87], v108 offset:1024
	ds_read_b128 v[104:107], v108 offset:2048
	ds_read_b128 v[108:111], v108 offset:3072
	ds_read_b128 v[128:131], v156
	ds_read_b128 v[132:135], v156 offset:1024
	ds_read_b128 v[152:155], v156 offset:2048
	ds_read_b128 v[156:159], v156 offset:3072
	s_add_u32 s48, s48, 0x40000
	s_addc_u32 s49, s49, 0
	s_mov_b32 m0, s55
	v_lshl_add_u64 v[234:235], s[48:49], 0, v[184:185]
	ds_read_b128 v[160:163], v218 offset:32768
	ds_read_b128 v[164:167], v218 offset:33792
	ds_read_b128 v[168:171], v218 offset:34816
	ds_read_b128 v[172:175], v218 offset:35840
	ds_read_b128 v[176:179], v218 offset:36864
	ds_read_b128 v[180:183], v218 offset:37888
	ds_read_b128 v[208:211], v218 offset:38912
	ds_read_b128 v[220:223], v218 offset:39936
	global_load_lds_dwordx4 v[234:235], off
	v_lshl_add_u64 v[234:235], s[48:49], 0, v[188:189]
	s_mov_b32 m0, s56
	s_nop 0
	global_load_lds_dwordx4 v[234:235], off
	s_waitcnt vmcnt(8)
	s_waitcnt lgkmcnt(0)
	s_setprio 1
	s_barrier
	v_mfma_f32_16x16x32_bf16 v[148:151], v[80:83], v[160:163], v[148:151]
	v_mfma_f32_16x16x32_bf16 v[148:151], v[84:87], v[164:167], v[148:151]
	v_mfma_f32_16x16x32_bf16 v[124:127], v[84:87], v[172:175], v[124:127]
	v_mfma_f32_16x16x32_bf16 v[124:127], v[80:83], v[168:171], v[124:127]
	v_mfma_f32_16x16x32_bf16 v[100:103], v[80:83], v[176:179], v[100:103]
	v_mfma_f32_16x16x32_bf16 v[100:103], v[84:87], v[180:183], v[100:103]
	v_mfma_f32_16x16x32_bf16 v[76:79], v[84:87], v[220:223], v[76:79]
	v_mfma_f32_16x16x32_bf16 v[76:79], v[80:83], v[208:211], v[76:79]
	v_mfma_f32_16x16x32_bf16 v[72:75], v[104:107], v[208:211], v[72:75]
	v_mfma_f32_16x16x32_bf16 v[72:75], v[108:111], v[220:223], v[72:75]
	v_mfma_f32_16x16x32_bf16 v[96:99], v[108:111], v[180:183], v[96:99]
	v_mfma_f32_16x16x32_bf16 v[96:99], v[104:107], v[176:179], v[96:99]
	v_mfma_f32_16x16x32_bf16 v[120:123], v[104:107], v[168:171], v[120:123]
	v_mfma_f32_16x16x32_bf16 v[120:123], v[108:111], v[172:175], v[120:123]
	v_mfma_f32_16x16x32_bf16 v[144:147], v[108:111], v[164:167], v[144:147]
	v_mfma_f32_16x16x32_bf16 v[144:147], v[104:107], v[160:163], v[144:147]
	v_mfma_f32_16x16x32_bf16 v[140:143], v[128:131], v[160:163], v[140:143]
	v_mfma_f32_16x16x32_bf16 v[140:143], v[132:135], v[164:167], v[140:143]
	v_mfma_f32_16x16x32_bf16 v[116:119], v[132:135], v[172:175], v[116:119]
	v_mfma_f32_16x16x32_bf16 v[116:119], v[128:131], v[168:171], v[116:119]
	v_mfma_f32_16x16x32_bf16 v[92:95], v[128:131], v[176:179], v[92:95]
	v_mfma_f32_16x16x32_bf16 v[92:95], v[132:135], v[180:183], v[92:95]
	v_mfma_f32_16x16x32_bf16 v[68:71], v[132:135], v[220:223], v[68:71]
	v_mfma_f32_16x16x32_bf16 v[68:71], v[128:131], v[208:211], v[68:71]
	v_mfma_f32_16x16x32_bf16 v[64:67], v[152:155], v[208:211], v[64:67]
	v_mfma_f32_16x16x32_bf16 v[64:67], v[156:159], v[220:223], v[64:67]
	v_mfma_f32_16x16x32_bf16 v[88:91], v[156:159], v[180:183], v[88:91]
	v_mfma_f32_16x16x32_bf16 v[88:91], v[152:155], v[176:179], v[88:91]
	v_mfma_f32_16x16x32_bf16 v[112:115], v[152:155], v[168:171], v[112:115]
	v_mfma_f32_16x16x32_bf16 v[112:115], v[156:159], v[172:175], v[112:115]
	v_mfma_f32_16x16x32_bf16 v[136:139], v[156:159], v[164:167], v[136:139]
	v_mfma_f32_16x16x32_bf16 v[136:139], v[152:155], v[160:163], v[136:139]
	s_barrier
	s_setprio 0
	s_add_i32 s48, s83, s52
	v_lshl_add_u64 v[224:225], v[224:225], 0, s[18:19]
	s_mov_b32 m0, s48
	ds_read_b128 v[160:163], v218 offset:49152
	ds_read_b128 v[164:167], v218 offset:50176
	ds_read_b128 v[168:171], v218 offset:51200
	ds_read_b128 v[172:175], v218 offset:52224
	ds_read_b128 v[176:179], v218 offset:53248
	ds_read_b128 v[180:183], v218 offset:54272
	ds_read_b128 v[208:211], v218 offset:55296
	ds_read_b128 v[220:223], v218 offset:56320
	global_load_lds_dwordx4 v[224:225], off
	s_add_i32 m0, s48, 0x2000
	s_add_u32 s46, s46, 0x40080
	v_lshl_add_u64 v[224:225], v[226:227], 0, s[18:19]
	s_addc_u32 s47, s47, 0
	s_add_i32 s48, s96, s52
	global_load_lds_dwordx4 v[224:225], off
	v_lshl_add_u64 v[224:225], s[46:47], 0, v[186:187]
	s_mov_b32 m0, s48
	s_nop 0
	global_load_lds_dwordx4 v[224:225], off
	v_lshl_add_u64 v[224:225], s[46:47], 0, v[190:191]
	s_add_i32 m0, s48, 0x2000
	s_nop 0
	global_load_lds_dwordx4 v[224:225], off
	v_lshl_add_u64 v[224:225], v[230:231], 0, s[18:19]
	s_mov_b32 m0, s68
	s_nop 0
	global_load_lds_dwordx4 v[224:225], off
	v_lshl_add_u64 v[224:225], v[232:233], 0, s[18:19]
	s_mov_b32 m0, s69
	s_nop 0
	global_load_lds_dwordx4 v[224:225], off
	s_waitcnt vmcnt(8)
	s_waitcnt lgkmcnt(0)
	s_setprio 1
	s_barrier
	v_mfma_f32_16x16x32_bf16 v[60:63], v[80:83], v[160:163], v[60:63]
	v_mfma_f32_16x16x32_bf16 v[60:63], v[84:87], v[164:167], v[60:63]
	v_mfma_f32_16x16x32_bf16 v[44:47], v[84:87], v[172:175], v[44:47]
	v_mfma_f32_16x16x32_bf16 v[44:47], v[80:83], v[168:171], v[44:47]
	v_mfma_f32_16x16x32_bf16 v[28:31], v[80:83], v[176:179], v[28:31]
	v_mfma_f32_16x16x32_bf16 v[28:31], v[84:87], v[180:183], v[28:31]
	v_mfma_f32_16x16x32_bf16 v[12:15], v[84:87], v[220:223], v[12:15]
	v_mfma_f32_16x16x32_bf16 v[12:15], v[80:83], v[208:211], v[12:15]
	v_mfma_f32_16x16x32_bf16 v[8:11], v[104:107], v[208:211], v[8:11]
	v_mfma_f32_16x16x32_bf16 v[8:11], v[108:111], v[220:223], v[8:11]
	v_mfma_f32_16x16x32_bf16 v[24:27], v[108:111], v[180:183], v[24:27]
	v_mfma_f32_16x16x32_bf16 v[24:27], v[104:107], v[176:179], v[24:27]
	v_mfma_f32_16x16x32_bf16 v[40:43], v[104:107], v[168:171], v[40:43]
	v_mfma_f32_16x16x32_bf16 v[40:43], v[108:111], v[172:175], v[40:43]
	v_mfma_f32_16x16x32_bf16 v[56:59], v[108:111], v[164:167], v[56:59]
	v_mfma_f32_16x16x32_bf16 v[56:59], v[104:107], v[160:163], v[56:59]
	v_mfma_f32_16x16x32_bf16 v[52:55], v[128:131], v[160:163], v[52:55]
	v_mfma_f32_16x16x32_bf16 v[52:55], v[132:135], v[164:167], v[52:55]
	v_mfma_f32_16x16x32_bf16 v[36:39], v[132:135], v[172:175], v[36:39]
	v_mfma_f32_16x16x32_bf16 v[36:39], v[128:131], v[168:171], v[36:39]
	v_mfma_f32_16x16x32_bf16 v[20:23], v[128:131], v[176:179], v[20:23]
	v_mfma_f32_16x16x32_bf16 v[20:23], v[132:135], v[180:183], v[20:23]
	v_mfma_f32_16x16x32_bf16 v[4:7], v[132:135], v[220:223], v[4:7]
	v_mfma_f32_16x16x32_bf16 v[4:7], v[128:131], v[208:211], v[4:7]
	v_mfma_f32_16x16x32_bf16 v[0:3], v[152:155], v[208:211], v[0:3]
	v_mfma_f32_16x16x32_bf16 v[0:3], v[156:159], v[220:223], v[0:3]
	v_mfma_f32_16x16x32_bf16 v[16:19], v[156:159], v[180:183], v[16:19]
	v_mfma_f32_16x16x32_bf16 v[16:19], v[152:155], v[176:179], v[16:19]
	v_mfma_f32_16x16x32_bf16 v[32:35], v[152:155], v[168:171], v[32:35]
	v_mfma_f32_16x16x32_bf16 v[32:35], v[156:159], v[172:175], v[32:35]
	v_mfma_f32_16x16x32_bf16 v[48:51], v[156:159], v[164:167], v[48:51]
	v_mfma_f32_16x16x32_bf16 v[48:51], v[152:155], v[160:163], v[48:51]
	s_barrier
	s_setprio 0
	s_add_i32 s95, s95, 2
	s_add_u32 s44, s44, 0x100
	s_addc_u32 s45, s45, 0
	s_add_u32 s93, s93, 0x100
	s_addc_u32 s94, s94, 0
	s_cmp_gt_u32 s95, 13
	s_cbranch_scc0 .LBB0_668
	s_and_b64 vcc, exec, s[20:21]
	s_cbranch_vccz .LBB0_671
	s_barrier

.LBB0_758:
	s_ashr_i32 s19, s18, 31
	s_lshl_b64 s[20:21], s[18:19], 19
	s_add_u32 s20, s62, s20
	s_addc_u32 s21, s63, s21
	s_and_b64 s[22:23], s[4:5], exec
	s_cselect_b32 s19, s21, s39
	s_cselect_b32 s57, s20, s38
	s_ashr_i32 s11, s10, 31
	s_lshl_b64 s[22:23], s[10:11], 19
	s_add_u32 s22, s40, s22
	s_addc_u32 s23, s41, s23
	s_and_b64 s[4:5], s[4:5], exec
	s_cselect_b32 s11, s23, s37
	s_cselect_b32 s58, s22, s36
	s_add_u32 s4, s38, 0x40080
	s_addc_u32 s5, s39, 0
	s_add_u32 s59, s36, 0x100
	s_addc_u32 s66, s37, 0
	s_mov_b32 s67, -2
	ds_read_b128 v[146:149], v172
	ds_read_b128 v[166:169], v172 offset:1024
	ds_read_b128 v[176:179], v172 offset:2048
	ds_read_b128 v[180:183], v172 offset:3072
	ds_read_b128 v[184:187], v173
	ds_read_b128 v[188:191], v173 offset:1024
	ds_read_b128 v[192:195], v173 offset:2048
	ds_read_b128 v[196:199], v173 offset:3072
	s_add_u32 s36, s4, 0xfffc0080
	s_addc_u32 s37, s5, -1
	s_cmp_eq_u32 s67, 12
	s_cselect_b32 s39, s19, s37
	s_cselect_b32 s38, s57, s36
	s_cselect_b32 s37, s11, s66
	s_cselect_b32 s36, s58, s59
	v_lshl_add_u64 v[150:151], s[4:5], 0, v[138:139]
	s_add_i32 m0, s27, 0xc000
	ds_read_b128 v[200:203], v174
	ds_read_b128 v[204:207], v174 offset:1024
	ds_read_b128 v[208:211], v174 offset:2048
	ds_read_b128 v[212:215], v174 offset:3072
	ds_read_b128 v[216:219], v174 offset:4096
	ds_read_b128 v[220:223], v174 offset:5120
	ds_read_b128 v[224:227], v174 offset:6144
	ds_read_b128 v[230:233], v174 offset:7168
	global_load_lds_dwordx4 v[150:151], off
	v_lshl_add_u64 v[150:151], s[4:5], 0, v[140:141]
	s_add_i32 m0, s27, 0xe000
	s_nop 0
	global_load_lds_dwordx4 v[150:151], off
	s_waitcnt vmcnt(8)
	s_waitcnt lgkmcnt(0)
	s_setprio 1
	s_barrier
	v_mfma_f32_16x16x32_bf16 v[124:127], v[146:149], v[200:203], 0
	v_mfma_f32_16x16x32_bf16 v[124:127], v[166:169], v[204:207], v[124:127]
	v_mfma_f32_16x16x32_bf16 v[108:111], v[166:169], v[212:215], 0
	v_mfma_f32_16x16x32_bf16 v[108:111], v[146:149], v[208:211], v[108:111]
	v_mfma_f32_16x16x32_bf16 v[92:95], v[146:149], v[216:219], 0
	v_mfma_f32_16x16x32_bf16 v[92:95], v[166:169], v[220:223], v[92:95]
	v_mfma_f32_16x16x32_bf16 v[76:79], v[166:169], v[230:233], 0
	v_mfma_f32_16x16x32_bf16 v[76:79], v[146:149], v[224:227], v[76:79]
	v_mfma_f32_16x16x32_bf16 v[72:75], v[176:179], v[224:227], 0
	v_mfma_f32_16x16x32_bf16 v[72:75], v[180:183], v[230:233], v[72:75]
	v_mfma_f32_16x16x32_bf16 v[88:91], v[180:183], v[220:223], 0
	v_mfma_f32_16x16x32_bf16 v[88:91], v[176:179], v[216:219], v[88:91]
	v_mfma_f32_16x16x32_bf16 v[104:107], v[176:179], v[208:211], 0
	v_mfma_f32_16x16x32_bf16 v[104:107], v[180:183], v[212:215], v[104:107]
	v_mfma_f32_16x16x32_bf16 v[120:123], v[180:183], v[204:207], 0
	v_mfma_f32_16x16x32_bf16 v[120:123], v[176:179], v[200:203], v[120:123]
	v_mfma_f32_16x16x32_bf16 v[116:119], v[184:187], v[200:203], 0
	v_mfma_f32_16x16x32_bf16 v[116:119], v[188:191], v[204:207], v[116:119]
	v_mfma_f32_16x16x32_bf16 v[100:103], v[188:191], v[212:215], 0
	v_mfma_f32_16x16x32_bf16 v[100:103], v[184:187], v[208:211], v[100:103]
	v_mfma_f32_16x16x32_bf16 v[84:87], v[184:187], v[216:219], 0
	v_mfma_f32_16x16x32_bf16 v[84:87], v[188:191], v[220:223], v[84:87]
	v_mfma_f32_16x16x32_bf16 v[68:71], v[188:191], v[230:233], 0
	v_mfma_f32_16x16x32_bf16 v[68:71], v[184:187], v[224:227], v[68:71]
	v_mfma_f32_16x16x32_bf16 v[64:67], v[192:195], v[224:227], 0
	v_mfma_f32_16x16x32_bf16 v[64:67], v[196:199], v[230:233], v[64:67]
	v_mfma_f32_16x16x32_bf16 v[80:83], v[196:199], v[220:223], 0
	v_mfma_f32_16x16x32_bf16 v[80:83], v[192:195], v[216:219], v[80:83]
	v_mfma_f32_16x16x32_bf16 v[96:99], v[192:195], v[208:211], 0
	v_mfma_f32_16x16x32_bf16 v[96:99], v[196:199], v[212:215], v[96:99]
	v_mfma_f32_16x16x32_bf16 v[112:115], v[196:199], v[204:207], 0
	v_mfma_f32_16x16x32_bf16 v[112:115], v[192:195], v[200:203], v[112:115]
	s_barrier
	s_setprio 0
	s_add_i32 s68, s53, s42
	v_lshl_add_u64 v[150:151], s[36:37], 0, v[132:133]
	s_mov_b32 m0, s68
	ds_read_b128 v[200:203], v174 offset:16384
	ds_read_b128 v[204:207], v174 offset:17408
	ds_read_b128 v[208:211], v174 offset:18432
	ds_read_b128 v[212:215], v174 offset:19456
	ds_read_b128 v[216:219], v174 offset:20480
	ds_read_b128 v[220:223], v174 offset:21504
	ds_read_b128 v[224:227], v174 offset:22528
	ds_read_b128 v[230:233], v174 offset:23552
	global_load_lds_dwordx4 v[150:151], off
	s_add_i32 m0, s68, 0x2000
	s_add_u32 s68, s36, 0x40000
	v_lshl_add_u64 v[154:155], s[36:37], 0, v[128:129]
	s_addc_u32 s69, s37, 0
	s_add_i32 s70, s54, s42
	global_load_lds_dwordx4 v[154:155], off
	v_lshl_add_u64 v[158:159], s[68:69], 0, v[132:133]
	s_mov_b32 m0, s70
	v_lshl_add_u64 v[162:163], s[38:39], 0, v[130:131]
	global_load_lds_dwordx4 v[158:159], off
	v_lshl_add_u64 v[158:159], s[68:69], 0, v[128:129]
	s_add_i32 m0, s70, 0x2000
	s_nop 0
	global_load_lds_dwordx4 v[158:159], off
	v_lshl_add_u64 v[158:159], s[38:39], 0, v[134:135]
	s_mov_b32 m0, s27
	s_nop 0
	global_load_lds_dwordx4 v[158:159], off
	s_mov_b32 m0, s45
	s_nop 0
	global_load_lds_dwordx4 v[162:163], off
	s_waitcnt vmcnt(8)
	s_waitcnt lgkmcnt(0)
	s_setprio 1
	s_barrier
	v_mfma_f32_16x16x32_bf16 v[60:63], v[146:149], v[200:203], 0
	v_mfma_f32_16x16x32_bf16 v[60:63], v[166:169], v[204:207], v[60:63]
	v_mfma_f32_16x16x32_bf16 v[44:47], v[166:169], v[212:215], 0
	v_mfma_f32_16x16x32_bf16 v[44:47], v[146:149], v[208:211], v[44:47]
	v_mfma_f32_16x16x32_bf16 v[28:31], v[146:149], v[216:219], 0
	v_mfma_f32_16x16x32_bf16 v[28:31], v[166:169], v[220:223], v[28:31]
	v_mfma_f32_16x16x32_bf16 v[12:15], v[166:169], v[230:233], 0
	v_mfma_f32_16x16x32_bf16 v[12:15], v[146:149], v[224:227], v[12:15]
	v_mfma_f32_16x16x32_bf16 v[8:11], v[176:179], v[224:227], 0
	v_mfma_f32_16x16x32_bf16 v[8:11], v[180:183], v[230:233], v[8:11]
	v_mfma_f32_16x16x32_bf16 v[24:27], v[180:183], v[220:223], 0
	v_mfma_f32_16x16x32_bf16 v[24:27], v[176:179], v[216:219], v[24:27]
	v_mfma_f32_16x16x32_bf16 v[40:43], v[176:179], v[208:211], 0
	v_mfma_f32_16x16x32_bf16 v[40:43], v[180:183], v[212:215], v[40:43]
	v_mfma_f32_16x16x32_bf16 v[56:59], v[180:183], v[204:207], 0
	v_mfma_f32_16x16x32_bf16 v[56:59], v[176:179], v[200:203], v[56:59]
	v_mfma_f32_16x16x32_bf16 v[52:55], v[184:187], v[200:203], 0
	v_mfma_f32_16x16x32_bf16 v[52:55], v[188:191], v[204:207], v[52:55]
	v_mfma_f32_16x16x32_bf16 v[36:39], v[188:191], v[212:215], 0
	v_mfma_f32_16x16x32_bf16 v[36:39], v[184:187], v[208:211], v[36:39]
	v_mfma_f32_16x16x32_bf16 v[20:23], v[184:187], v[216:219], 0
	v_mfma_f32_16x16x32_bf16 v[20:23], v[188:191], v[220:223], v[20:23]
	v_mfma_f32_16x16x32_bf16 v[4:7], v[188:191], v[230:233], 0
	v_mfma_f32_16x16x32_bf16 v[4:7], v[184:187], v[224:227], v[4:7]
	v_mfma_f32_16x16x32_bf16 v[0:3], v[192:195], v[224:227], 0
	v_mfma_f32_16x16x32_bf16 v[0:3], v[196:199], v[230:233], v[0:3]
	v_mfma_f32_16x16x32_bf16 v[16:19], v[196:199], v[220:223], 0
	v_mfma_f32_16x16x32_bf16 v[16:19], v[192:195], v[216:219], v[16:19]
	v_mfma_f32_16x16x32_bf16 v[32:35], v[192:195], v[208:211], 0
	v_mfma_f32_16x16x32_bf16 v[32:35], v[196:199], v[212:215], v[32:35]
	v_mfma_f32_16x16x32_bf16 v[48:51], v[196:199], v[204:207], 0
	v_mfma_f32_16x16x32_bf16 v[48:51], v[192:195], v[200:203], v[48:51]
	s_barrier
	s_setprio 0
	s_add_i32 s68, 0, 0x18000
	v_add_u32_e32 v152, s68, v157
	s_add_i32 s69, 0, 0x1c000
	ds_read_b128 v[146:149], v152
	ds_read_b128 v[166:169], v152 offset:1024
	ds_read_b128 v[176:179], v152 offset:2048
	ds_read_b128 v[180:183], v152 offset:3072
	v_add_u32_e32 v152, s69, v157
	ds_read_b128 v[184:187], v152
	ds_read_b128 v[188:191], v152 offset:1024
	ds_read_b128 v[192:195], v152 offset:2048
	ds_read_b128 v[196:199], v152 offset:3072
	s_add_u32 s38, s38, 0x40000
	s_addc_u32 s39, s39, 0
	s_mov_b32 m0, s46
	v_lshl_add_u64 v[234:235], s[38:39], 0, v[134:135]
	ds_read_b128 v[200:203], v174 offset:32768
	ds_read_b128 v[204:207], v174 offset:33792
	ds_read_b128 v[208:211], v174 offset:34816
	ds_read_b128 v[212:215], v174 offset:35840
	ds_read_b128 v[216:219], v174 offset:36864
	ds_read_b128 v[220:223], v174 offset:37888
	ds_read_b128 v[224:227], v174 offset:38912
	ds_read_b128 v[230:233], v174 offset:39936
	global_load_lds_dwordx4 v[234:235], off
	v_lshl_add_u64 v[234:235], s[38:39], 0, v[130:131]
	s_mov_b32 m0, s47
	s_nop 0
	global_load_lds_dwordx4 v[234:235], off
	s_waitcnt vmcnt(8)
	s_waitcnt lgkmcnt(0)
	s_setprio 1
	s_barrier
	v_mfma_f32_16x16x32_bf16 v[124:127], v[146:149], v[200:203], v[124:127]
	v_mfma_f32_16x16x32_bf16 v[124:127], v[166:169], v[204:207], v[124:127]
	v_mfma_f32_16x16x32_bf16 v[108:111], v[166:169], v[212:215], v[108:111]
	v_mfma_f32_16x16x32_bf16 v[108:111], v[146:149], v[208:211], v[108:111]
	v_mfma_f32_16x16x32_bf16 v[92:95], v[146:149], v[216:219], v[92:95]
	v_mfma_f32_16x16x32_bf16 v[92:95], v[166:169], v[220:223], v[92:95]
	v_mfma_f32_16x16x32_bf16 v[76:79], v[166:169], v[230:233], v[76:79]
	v_mfma_f32_16x16x32_bf16 v[76:79], v[146:149], v[224:227], v[76:79]
	v_mfma_f32_16x16x32_bf16 v[72:75], v[176:179], v[224:227], v[72:75]
	v_mfma_f32_16x16x32_bf16 v[72:75], v[180:183], v[230:233], v[72:75]
	v_mfma_f32_16x16x32_bf16 v[88:91], v[180:183], v[220:223], v[88:91]
	v_mfma_f32_16x16x32_bf16 v[88:91], v[176:179], v[216:219], v[88:91]
	v_mfma_f32_16x16x32_bf16 v[104:107], v[176:179], v[208:211], v[104:107]
	v_mfma_f32_16x16x32_bf16 v[104:107], v[180:183], v[212:215], v[104:107]
	v_mfma_f32_16x16x32_bf16 v[120:123], v[180:183], v[204:207], v[120:123]
	v_mfma_f32_16x16x32_bf16 v[120:123], v[176:179], v[200:203], v[120:123]
	v_mfma_f32_16x16x32_bf16 v[116:119], v[184:187], v[200:203], v[116:119]
	v_mfma_f32_16x16x32_bf16 v[116:119], v[188:191], v[204:207], v[116:119]
	v_mfma_f32_16x16x32_bf16 v[100:103], v[188:191], v[212:215], v[100:103]
	v_mfma_f32_16x16x32_bf16 v[100:103], v[184:187], v[208:211], v[100:103]
	v_mfma_f32_16x16x32_bf16 v[84:87], v[184:187], v[216:219], v[84:87]
	v_mfma_f32_16x16x32_bf16 v[84:87], v[188:191], v[220:223], v[84:87]
	v_mfma_f32_16x16x32_bf16 v[68:71], v[188:191], v[230:233], v[68:71]
	v_mfma_f32_16x16x32_bf16 v[68:71], v[184:187], v[224:227], v[68:71]
	v_mfma_f32_16x16x32_bf16 v[64:67], v[192:195], v[224:227], v[64:67]
	v_mfma_f32_16x16x32_bf16 v[64:67], v[196:199], v[230:233], v[64:67]
	v_mfma_f32_16x16x32_bf16 v[80:83], v[196:199], v[220:223], v[80:83]
	v_mfma_f32_16x16x32_bf16 v[80:83], v[192:195], v[216:219], v[80:83]
	v_mfma_f32_16x16x32_bf16 v[96:99], v[192:195], v[208:211], v[96:99]
	v_mfma_f32_16x16x32_bf16 v[96:99], v[196:199], v[212:215], v[96:99]
	v_mfma_f32_16x16x32_bf16 v[112:115], v[196:199], v[204:207], v[112:115]
	v_mfma_f32_16x16x32_bf16 v[112:115], v[192:195], v[200:203], v[112:115]
	s_barrier
	s_setprio 0
	s_add_i32 s38, s68, s42
	v_lshl_add_u64 v[150:151], v[150:151], 0, s[14:15]
	s_mov_b32 m0, s38
	ds_read_b128 v[200:203], v174 offset:49152
	ds_read_b128 v[204:207], v174 offset:50176
	ds_read_b128 v[208:211], v174 offset:51200
	ds_read_b128 v[212:215], v174 offset:52224
	ds_read_b128 v[216:219], v174 offset:53248
	ds_read_b128 v[220:223], v174 offset:54272
	ds_read_b128 v[224:227], v174 offset:55296
	ds_read_b128 v[230:233], v174 offset:56320
	global_load_lds_dwordx4 v[150:151], off
	s_add_i32 m0, s38, 0x2000
	s_add_u32 s36, s36, 0x40080
	v_lshl_add_u64 v[150:151], v[154:155], 0, s[14:15]
	s_addc_u32 s37, s37, 0
	s_add_i32 s38, s69, s42
	global_load_lds_dwordx4 v[150:151], off
	v_lshl_add_u64 v[150:151], s[36:37], 0, v[132:133]
	s_mov_b32 m0, s38
	s_nop 0
	global_load_lds_dwordx4 v[150:151], off
	v_lshl_add_u64 v[150:151], s[36:37], 0, v[128:129]
	s_add_i32 m0, s38, 0x2000
	s_nop 0
	global_load_lds_dwordx4 v[150:151], off
	v_lshl_add_u64 v[150:151], v[158:159], 0, s[14:15]
	s_mov_b32 m0, s49
	s_nop 0
	global_load_lds_dwordx4 v[150:151], off
	v_lshl_add_u64 v[150:151], v[162:163], 0, s[14:15]
	s_mov_b32 m0, s50
	s_nop 0
	global_load_lds_dwordx4 v[150:151], off
	s_waitcnt vmcnt(8)
	s_waitcnt lgkmcnt(0)
	s_setprio 1
	s_barrier
	v_mfma_f32_16x16x32_bf16 v[60:63], v[146:149], v[200:203], v[60:63]
	v_mfma_f32_16x16x32_bf16 v[60:63], v[166:169], v[204:207], v[60:63]
	v_mfma_f32_16x16x32_bf16 v[44:47], v[166:169], v[212:215], v[44:47]
	v_mfma_f32_16x16x32_bf16 v[44:47], v[146:149], v[208:211], v[44:47]
	v_mfma_f32_16x16x32_bf16 v[28:31], v[146:149], v[216:219], v[28:31]
	v_mfma_f32_16x16x32_bf16 v[28:31], v[166:169], v[220:223], v[28:31]
	v_mfma_f32_16x16x32_bf16 v[12:15], v[166:169], v[230:233], v[12:15]
	v_mfma_f32_16x16x32_bf16 v[12:15], v[146:149], v[224:227], v[12:15]
	v_mfma_f32_16x16x32_bf16 v[8:11], v[176:179], v[224:227], v[8:11]
	v_mfma_f32_16x16x32_bf16 v[8:11], v[180:183], v[230:233], v[8:11]
	v_mfma_f32_16x16x32_bf16 v[24:27], v[180:183], v[220:223], v[24:27]
	v_mfma_f32_16x16x32_bf16 v[24:27], v[176:179], v[216:219], v[24:27]
	v_mfma_f32_16x16x32_bf16 v[40:43], v[176:179], v[208:211], v[40:43]
	v_mfma_f32_16x16x32_bf16 v[40:43], v[180:183], v[212:215], v[40:43]
	v_mfma_f32_16x16x32_bf16 v[56:59], v[180:183], v[204:207], v[56:59]
	v_mfma_f32_16x16x32_bf16 v[56:59], v[176:179], v[200:203], v[56:59]
	v_mfma_f32_16x16x32_bf16 v[52:55], v[184:187], v[200:203], v[52:55]
	v_mfma_f32_16x16x32_bf16 v[52:55], v[188:191], v[204:207], v[52:55]
	v_mfma_f32_16x16x32_bf16 v[36:39], v[188:191], v[212:215], v[36:39]
	v_mfma_f32_16x16x32_bf16 v[36:39], v[184:187], v[208:211], v[36:39]
	v_mfma_f32_16x16x32_bf16 v[20:23], v[184:187], v[216:219], v[20:23]
	v_mfma_f32_16x16x32_bf16 v[20:23], v[188:191], v[220:223], v[20:23]
	v_mfma_f32_16x16x32_bf16 v[4:7], v[188:191], v[230:233], v[4:7]
	v_mfma_f32_16x16x32_bf16 v[4:7], v[184:187], v[224:227], v[4:7]
	v_mfma_f32_16x16x32_bf16 v[0:3], v[192:195], v[224:227], v[0:3]
	v_mfma_f32_16x16x32_bf16 v[0:3], v[196:199], v[230:233], v[0:3]
	v_mfma_f32_16x16x32_bf16 v[16:19], v[196:199], v[220:223], v[16:19]
	v_mfma_f32_16x16x32_bf16 v[16:19], v[192:195], v[216:219], v[16:19]
	v_mfma_f32_16x16x32_bf16 v[32:35], v[192:195], v[208:211], v[32:35]
	v_mfma_f32_16x16x32_bf16 v[32:35], v[196:199], v[212:215], v[32:35]
	v_mfma_f32_16x16x32_bf16 v[48:51], v[196:199], v[204:207], v[48:51]
	v_mfma_f32_16x16x32_bf16 v[48:51], v[192:195], v[200:203], v[48:51]
	s_barrier
	s_setprio 0
	s_add_i32 s67, s67, 2
	s_add_u32 s4, s4, 0x100
	s_addc_u32 s5, s5, 0
	s_add_u32 s59, s59, 0x100
	s_addc_u32 s66, s66, 0
	s_cmp_gt_u32 s67, 13
.LBB0_759:
	ds_read_b128 v[146:149], v172
	ds_read_b128 v[166:169], v172 offset:1024
	ds_read_b128 v[176:179], v172 offset:2048
	ds_read_b128 v[180:183], v172 offset:3072
	ds_read_b128 v[184:187], v173
	ds_read_b128 v[188:191], v173 offset:1024
	ds_read_b128 v[192:195], v173 offset:2048
	ds_read_b128 v[196:199], v173 offset:3072
	s_add_u32 s36, s4, 0xfffc0080
	s_addc_u32 s37, s5, -1
	s_cmp_eq_u32 s67, 12
	s_cselect_b32 s39, s19, s37
	s_cselect_b32 s38, s57, s36
	s_cselect_b32 s37, s11, s66
	s_cselect_b32 s36, s58, s59
	v_lshl_add_u64 v[150:151], s[4:5], 0, v[138:139]
	s_add_i32 m0, s27, 0xc000
	ds_read_b128 v[200:203], v174
	ds_read_b128 v[204:207], v174 offset:1024
	ds_read_b128 v[208:211], v174 offset:2048
	ds_read_b128 v[212:215], v174 offset:3072
	ds_read_b128 v[216:219], v174 offset:4096
	ds_read_b128 v[220:223], v174 offset:5120
	ds_read_b128 v[224:227], v174 offset:6144
	ds_read_b128 v[230:233], v174 offset:7168
	global_load_lds_dwordx4 v[150:151], off
	v_lshl_add_u64 v[150:151], s[4:5], 0, v[140:141]
	s_add_i32 m0, s27, 0xe000
	s_nop 0
	global_load_lds_dwordx4 v[150:151], off
	s_waitcnt vmcnt(8)
	s_waitcnt lgkmcnt(0)
	s_setprio 1
	s_barrier
	v_mfma_f32_16x16x32_bf16 v[124:127], v[146:149], v[200:203], v[124:127]
	v_mfma_f32_16x16x32_bf16 v[124:127], v[166:169], v[204:207], v[124:127]
	v_mfma_f32_16x16x32_bf16 v[108:111], v[166:169], v[212:215], v[108:111]
	v_mfma_f32_16x16x32_bf16 v[108:111], v[146:149], v[208:211], v[108:111]
	v_mfma_f32_16x16x32_bf16 v[92:95], v[146:149], v[216:219], v[92:95]
	v_mfma_f32_16x16x32_bf16 v[92:95], v[166:169], v[220:223], v[92:95]
	v_mfma_f32_16x16x32_bf16 v[76:79], v[166:169], v[230:233], v[76:79]
	v_mfma_f32_16x16x32_bf16 v[76:79], v[146:149], v[224:227], v[76:79]
	v_mfma_f32_16x16x32_bf16 v[72:75], v[176:179], v[224:227], v[72:75]
	v_mfma_f32_16x16x32_bf16 v[72:75], v[180:183], v[230:233], v[72:75]
	v_mfma_f32_16x16x32_bf16 v[88:91], v[180:183], v[220:223], v[88:91]
	v_mfma_f32_16x16x32_bf16 v[88:91], v[176:179], v[216:219], v[88:91]
	v_mfma_f32_16x16x32_bf16 v[104:107], v[176:179], v[208:211], v[104:107]
	v_mfma_f32_16x16x32_bf16 v[104:107], v[180:183], v[212:215], v[104:107]
	v_mfma_f32_16x16x32_bf16 v[120:123], v[180:183], v[204:207], v[120:123]
	v_mfma_f32_16x16x32_bf16 v[120:123], v[176:179], v[200:203], v[120:123]
	v_mfma_f32_16x16x32_bf16 v[116:119], v[184:187], v[200:203], v[116:119]
	v_mfma_f32_16x16x32_bf16 v[116:119], v[188:191], v[204:207], v[116:119]
	v_mfma_f32_16x16x32_bf16 v[100:103], v[188:191], v[212:215], v[100:103]
	v_mfma_f32_16x16x32_bf16 v[100:103], v[184:187], v[208:211], v[100:103]
	v_mfma_f32_16x16x32_bf16 v[84:87], v[184:187], v[216:219], v[84:87]
	v_mfma_f32_16x16x32_bf16 v[84:87], v[188:191], v[220:223], v[84:87]
	v_mfma_f32_16x16x32_bf16 v[68:71], v[188:191], v[230:233], v[68:71]
	v_mfma_f32_16x16x32_bf16 v[68:71], v[184:187], v[224:227], v[68:71]
	v_mfma_f32_16x16x32_bf16 v[64:67], v[192:195], v[224:227], v[64:67]
	v_mfma_f32_16x16x32_bf16 v[64:67], v[196:199], v[230:233], v[64:67]
	v_mfma_f32_16x16x32_bf16 v[80:83], v[196:199], v[220:223], v[80:83]
	v_mfma_f32_16x16x32_bf16 v[80:83], v[192:195], v[216:219], v[80:83]
	v_mfma_f32_16x16x32_bf16 v[96:99], v[192:195], v[208:211], v[96:99]
	v_mfma_f32_16x16x32_bf16 v[96:99], v[196:199], v[212:215], v[96:99]
	v_mfma_f32_16x16x32_bf16 v[112:115], v[196:199], v[204:207], v[112:115]
	v_mfma_f32_16x16x32_bf16 v[112:115], v[192:195], v[200:203], v[112:115]
	s_barrier
	s_setprio 0
	s_add_i32 s68, s53, s42
	v_lshl_add_u64 v[150:151], s[36:37], 0, v[132:133]
	s_mov_b32 m0, s68
	ds_read_b128 v[200:203], v174 offset:16384
	ds_read_b128 v[204:207], v174 offset:17408
	ds_read_b128 v[208:211], v174 offset:18432
	ds_read_b128 v[212:215], v174 offset:19456
	ds_read_b128 v[216:219], v174 offset:20480
	ds_read_b128 v[220:223], v174 offset:21504
	ds_read_b128 v[224:227], v174 offset:22528
	ds_read_b128 v[230:233], v174 offset:23552
	global_load_lds_dwordx4 v[150:151], off
	s_add_i32 m0, s68, 0x2000
	s_add_u32 s68, s36, 0x40000
	v_lshl_add_u64 v[154:155], s[36:37], 0, v[128:129]
	s_addc_u32 s69, s37, 0
	s_add_i32 s70, s54, s42
	global_load_lds_dwordx4 v[154:155], off
	v_lshl_add_u64 v[158:159], s[68:69], 0, v[132:133]
	s_mov_b32 m0, s70
	v_lshl_add_u64 v[162:163], s[38:39], 0, v[130:131]
	global_load_lds_dwordx4 v[158:159], off
	v_lshl_add_u64 v[158:159], s[68:69], 0, v[128:129]
	s_add_i32 m0, s70, 0x2000
	s_nop 0
	global_load_lds_dwordx4 v[158:159], off
	v_lshl_add_u64 v[158:159], s[38:39], 0, v[134:135]
	s_mov_b32 m0, s27
	s_nop 0
	global_load_lds_dwordx4 v[158:159], off
	s_mov_b32 m0, s45
	s_nop 0
	global_load_lds_dwordx4 v[162:163], off
	s_waitcnt vmcnt(8)
	s_waitcnt lgkmcnt(0)
	s_setprio 1
	s_barrier
	v_mfma_f32_16x16x32_bf16 v[60:63], v[146:149], v[200:203], v[60:63]
	v_mfma_f32_16x16x32_bf16 v[60:63], v[166:169], v[204:207], v[60:63]
	v_mfma_f32_16x16x32_bf16 v[44:47], v[166:169], v[212:215], v[44:47]
	v_mfma_f32_16x16x32_bf16 v[44:47], v[146:149], v[208:211], v[44:47]
	v_mfma_f32_16x16x32_bf16 v[28:31], v[146:149], v[216:219], v[28:31]
	v_mfma_f32_16x16x32_bf16 v[28:31], v[166:169], v[220:223], v[28:31]
	v_mfma_f32_16x16x32_bf16 v[12:15], v[166:169], v[230:233], v[12:15]
	v_mfma_f32_16x16x32_bf16 v[12:15], v[146:149], v[224:227], v[12:15]
	v_mfma_f32_16x16x32_bf16 v[8:11], v[176:179], v[224:227], v[8:11]
	v_mfma_f32_16x16x32_bf16 v[8:11], v[180:183], v[230:233], v[8:11]
	v_mfma_f32_16x16x32_bf16 v[24:27], v[180:183], v[220:223], v[24:27]
	v_mfma_f32_16x16x32_bf16 v[24:27], v[176:179], v[216:219], v[24:27]
	v_mfma_f32_16x16x32_bf16 v[40:43], v[176:179], v[208:211], v[40:43]
	v_mfma_f32_16x16x32_bf16 v[40:43], v[180:183], v[212:215], v[40:43]
	v_mfma_f32_16x16x32_bf16 v[56:59], v[180:183], v[204:207], v[56:59]
	v_mfma_f32_16x16x32_bf16 v[56:59], v[176:179], v[200:203], v[56:59]
	v_mfma_f32_16x16x32_bf16 v[52:55], v[184:187], v[200:203], v[52:55]
	v_mfma_f32_16x16x32_bf16 v[52:55], v[188:191], v[204:207], v[52:55]
	v_mfma_f32_16x16x32_bf16 v[36:39], v[188:191], v[212:215], v[36:39]
	v_mfma_f32_16x16x32_bf16 v[36:39], v[184:187], v[208:211], v[36:39]
	v_mfma_f32_16x16x32_bf16 v[20:23], v[184:187], v[216:219], v[20:23]
	v_mfma_f32_16x16x32_bf16 v[20:23], v[188:191], v[220:223], v[20:23]
	v_mfma_f32_16x16x32_bf16 v[4:7], v[188:191], v[230:233], v[4:7]
	v_mfma_f32_16x16x32_bf16 v[4:7], v[184:187], v[224:227], v[4:7]
	v_mfma_f32_16x16x32_bf16 v[0:3], v[192:195], v[224:227], v[0:3]
	v_mfma_f32_16x16x32_bf16 v[0:3], v[196:199], v[230:233], v[0:3]
	v_mfma_f32_16x16x32_bf16 v[16:19], v[196:199], v[220:223], v[16:19]
	v_mfma_f32_16x16x32_bf16 v[16:19], v[192:195], v[216:219], v[16:19]
	v_mfma_f32_16x16x32_bf16 v[32:35], v[192:195], v[208:211], v[32:35]
	v_mfma_f32_16x16x32_bf16 v[32:35], v[196:199], v[212:215], v[32:35]
	v_mfma_f32_16x16x32_bf16 v[48:51], v[196:199], v[204:207], v[48:51]
	v_mfma_f32_16x16x32_bf16 v[48:51], v[192:195], v[200:203], v[48:51]
	s_barrier
	s_setprio 0
	s_add_i32 s68, 0, 0x18000
	v_add_u32_e32 v152, s68, v157
	s_add_i32 s69, 0, 0x1c000
	ds_read_b128 v[146:149], v152
	ds_read_b128 v[166:169], v152 offset:1024
	ds_read_b128 v[176:179], v152 offset:2048
	ds_read_b128 v[180:183], v152 offset:3072
	v_add_u32_e32 v152, s69, v157
	ds_read_b128 v[184:187], v152
	ds_read_b128 v[188:191], v152 offset:1024
	ds_read_b128 v[192:195], v152 offset:2048
	ds_read_b128 v[196:199], v152 offset:3072
	s_add_u32 s38, s38, 0x40000
	s_addc_u32 s39, s39, 0
	s_mov_b32 m0, s46
	v_lshl_add_u64 v[234:235], s[38:39], 0, v[134:135]
	ds_read_b128 v[200:203], v174 offset:32768
	ds_read_b128 v[204:207], v174 offset:33792
	ds_read_b128 v[208:211], v174 offset:34816
	ds_read_b128 v[212:215], v174 offset:35840
	ds_read_b128 v[216:219], v174 offset:36864
	ds_read_b128 v[220:223], v174 offset:37888
	ds_read_b128 v[224:227], v174 offset:38912
	ds_read_b128 v[230:233], v174 offset:39936
	global_load_lds_dwordx4 v[234:235], off
	v_lshl_add_u64 v[234:235], s[38:39], 0, v[130:131]
	s_mov_b32 m0, s47
	s_nop 0
	global_load_lds_dwordx4 v[234:235], off
	s_waitcnt vmcnt(8)
	s_waitcnt lgkmcnt(0)
	s_setprio 1
	s_barrier
	v_mfma_f32_16x16x32_bf16 v[124:127], v[146:149], v[200:203], v[124:127]
	v_mfma_f32_16x16x32_bf16 v[124:127], v[166:169], v[204:207], v[124:127]
	v_mfma_f32_16x16x32_bf16 v[108:111], v[166:169], v[212:215], v[108:111]
	v_mfma_f32_16x16x32_bf16 v[108:111], v[146:149], v[208:211], v[108:111]
	v_mfma_f32_16x16x32_bf16 v[92:95], v[146:149], v[216:219], v[92:95]
	v_mfma_f32_16x16x32_bf16 v[92:95], v[166:169], v[220:223], v[92:95]
	v_mfma_f32_16x16x32_bf16 v[76:79], v[166:169], v[230:233], v[76:79]
	v_mfma_f32_16x16x32_bf16 v[76:79], v[146:149], v[224:227], v[76:79]
	v_mfma_f32_16x16x32_bf16 v[72:75], v[176:179], v[224:227], v[72:75]
	v_mfma_f32_16x16x32_bf16 v[72:75], v[180:183], v[230:233], v[72:75]
	v_mfma_f32_16x16x32_bf16 v[88:91], v[180:183], v[220:223], v[88:91]
	v_mfma_f32_16x16x32_bf16 v[88:91], v[176:179], v[216:219], v[88:91]
	v_mfma_f32_16x16x32_bf16 v[104:107], v[176:179], v[208:211], v[104:107]
	v_mfma_f32_16x16x32_bf16 v[104:107], v[180:183], v[212:215], v[104:107]
	v_mfma_f32_16x16x32_bf16 v[120:123], v[180:183], v[204:207], v[120:123]
	v_mfma_f32_16x16x32_bf16 v[120:123], v[176:179], v[200:203], v[120:123]
	v_mfma_f32_16x16x32_bf16 v[116:119], v[184:187], v[200:203], v[116:119]
	v_mfma_f32_16x16x32_bf16 v[116:119], v[188:191], v[204:207], v[116:119]
	v_mfma_f32_16x16x32_bf16 v[100:103], v[188:191], v[212:215], v[100:103]
	v_mfma_f32_16x16x32_bf16 v[100:103], v[184:187], v[208:211], v[100:103]
	v_mfma_f32_16x16x32_bf16 v[84:87], v[184:187], v[216:219], v[84:87]
	v_mfma_f32_16x16x32_bf16 v[84:87], v[188:191], v[220:223], v[84:87]
	v_mfma_f32_16x16x32_bf16 v[68:71], v[188:191], v[230:233], v[68:71]
	v_mfma_f32_16x16x32_bf16 v[68:71], v[184:187], v[224:227], v[68:71]
	v_mfma_f32_16x16x32_bf16 v[64:67], v[192:195], v[224:227], v[64:67]
	v_mfma_f32_16x16x32_bf16 v[64:67], v[196:199], v[230:233], v[64:67]
	v_mfma_f32_16x16x32_bf16 v[80:83], v[196:199], v[220:223], v[80:83]
	v_mfma_f32_16x16x32_bf16 v[80:83], v[192:195], v[216:219], v[80:83]
	v_mfma_f32_16x16x32_bf16 v[96:99], v[192:195], v[208:211], v[96:99]
	v_mfma_f32_16x16x32_bf16 v[96:99], v[196:199], v[212:215], v[96:99]
	v_mfma_f32_16x16x32_bf16 v[112:115], v[196:199], v[204:207], v[112:115]
	v_mfma_f32_16x16x32_bf16 v[112:115], v[192:195], v[200:203], v[112:115]
	s_barrier
	s_setprio 0
	s_add_i32 s38, s68, s42
	v_lshl_add_u64 v[150:151], v[150:151], 0, s[14:15]
	s_mov_b32 m0, s38
	ds_read_b128 v[200:203], v174 offset:49152
	ds_read_b128 v[204:207], v174 offset:50176
	ds_read_b128 v[208:211], v174 offset:51200
	ds_read_b128 v[212:215], v174 offset:52224
	ds_read_b128 v[216:219], v174 offset:53248
	ds_read_b128 v[220:223], v174 offset:54272
	ds_read_b128 v[224:227], v174 offset:55296
	ds_read_b128 v[230:233], v174 offset:56320
	global_load_lds_dwordx4 v[150:151], off
	s_add_i32 m0, s38, 0x2000
	s_add_u32 s36, s36, 0x40080
	v_lshl_add_u64 v[150:151], v[154:155], 0, s[14:15]
	s_addc_u32 s37, s37, 0
	s_add_i32 s38, s69, s42
	global_load_lds_dwordx4 v[150:151], off
	v_lshl_add_u64 v[150:151], s[36:37], 0, v[132:133]
	s_mov_b32 m0, s38
	s_nop 0
	global_load_lds_dwordx4 v[150:151], off
	v_lshl_add_u64 v[150:151], s[36:37], 0, v[128:129]
	s_add_i32 m0, s38, 0x2000
	s_nop 0
	global_load_lds_dwordx4 v[150:151], off
	v_lshl_add_u64 v[150:151], v[158:159], 0, s[14:15]
	s_mov_b32 m0, s49
	s_nop 0
	global_load_lds_dwordx4 v[150:151], off
	v_lshl_add_u64 v[150:151], v[162:163], 0, s[14:15]
	s_mov_b32 m0, s50
	s_nop 0
	global_load_lds_dwordx4 v[150:151], off
	s_waitcnt vmcnt(8)
	s_waitcnt lgkmcnt(0)
	s_setprio 1
	s_barrier
	v_mfma_f32_16x16x32_bf16 v[60:63], v[146:149], v[200:203], v[60:63]
	v_mfma_f32_16x16x32_bf16 v[60:63], v[166:169], v[204:207], v[60:63]
	v_mfma_f32_16x16x32_bf16 v[44:47], v[166:169], v[212:215], v[44:47]
	v_mfma_f32_16x16x32_bf16 v[44:47], v[146:149], v[208:211], v[44:47]
	v_mfma_f32_16x16x32_bf16 v[28:31], v[146:149], v[216:219], v[28:31]
	v_mfma_f32_16x16x32_bf16 v[28:31], v[166:169], v[220:223], v[28:31]
	v_mfma_f32_16x16x32_bf16 v[12:15], v[166:169], v[230:233], v[12:15]
	v_mfma_f32_16x16x32_bf16 v[12:15], v[146:149], v[224:227], v[12:15]
	v_mfma_f32_16x16x32_bf16 v[8:11], v[176:179], v[224:227], v[8:11]
	v_mfma_f32_16x16x32_bf16 v[8:11], v[180:183], v[230:233], v[8:11]
	v_mfma_f32_16x16x32_bf16 v[24:27], v[180:183], v[220:223], v[24:27]
	v_mfma_f32_16x16x32_bf16 v[24:27], v[176:179], v[216:219], v[24:27]
	v_mfma_f32_16x16x32_bf16 v[40:43], v[176:179], v[208:211], v[40:43]
	v_mfma_f32_16x16x32_bf16 v[40:43], v[180:183], v[212:215], v[40:43]
	v_mfma_f32_16x16x32_bf16 v[56:59], v[180:183], v[204:207], v[56:59]
	v_mfma_f32_16x16x32_bf16 v[56:59], v[176:179], v[200:203], v[56:59]
	v_mfma_f32_16x16x32_bf16 v[52:55], v[184:187], v[200:203], v[52:55]
	v_mfma_f32_16x16x32_bf16 v[52:55], v[188:191], v[204:207], v[52:55]
	v_mfma_f32_16x16x32_bf16 v[36:39], v[188:191], v[212:215], v[36:39]
	v_mfma_f32_16x16x32_bf16 v[36:39], v[184:187], v[208:211], v[36:39]
	v_mfma_f32_16x16x32_bf16 v[20:23], v[184:187], v[216:219], v[20:23]
	v_mfma_f32_16x16x32_bf16 v[20:23], v[188:191], v[220:223], v[20:23]
	v_mfma_f32_16x16x32_bf16 v[4:7], v[188:191], v[230:233], v[4:7]
	v_mfma_f32_16x16x32_bf16 v[4:7], v[184:187], v[224:227], v[4:7]
	v_mfma_f32_16x16x32_bf16 v[0:3], v[192:195], v[224:227], v[0:3]
	v_mfma_f32_16x16x32_bf16 v[0:3], v[196:199], v[230:233], v[0:3]
	v_mfma_f32_16x16x32_bf16 v[16:19], v[196:199], v[220:223], v[16:19]
	v_mfma_f32_16x16x32_bf16 v[16:19], v[192:195], v[216:219], v[16:19]
	v_mfma_f32_16x16x32_bf16 v[32:35], v[192:195], v[208:211], v[32:35]
	v_mfma_f32_16x16x32_bf16 v[32:35], v[196:199], v[212:215], v[32:35]
	v_mfma_f32_16x16x32_bf16 v[48:51], v[196:199], v[204:207], v[48:51]
	v_mfma_f32_16x16x32_bf16 v[48:51], v[192:195], v[200:203], v[48:51]
	s_barrier
	s_setprio 0
	s_add_i32 s67, s67, 2
	s_add_u32 s4, s4, 0x100
	s_addc_u32 s5, s5, 0
	s_add_u32 s59, s59, 0x100
	s_addc_u32 s66, s66, 0
	s_cmp_gt_u32 s67, 13
	s_cbranch_scc0 .LBB0_759
	s_and_b64 vcc, exec, s[16:17]
	s_cbranch_vccz .LBB0_762
	s_barrier

.LBB0_835:
	s_add_u32 s80, s22, 0x100
	s_addc_u32 s81, s23, 0
	s_mov_b32 s82, -2
	ds_read_b128 v[112:115], v203
	ds_read_b128 v[116:119], v203 offset:1024
	ds_read_b128 v[136:139], v203 offset:2048
	ds_read_b128 v[140:143], v203 offset:3072
	ds_read_b128 v[144:147], v204
	ds_read_b128 v[148:151], v204 offset:1024
	ds_read_b128 v[152:155], v204 offset:2048
	ds_read_b128 v[156:159], v204 offset:3072
	s_add_u32 s22, s20, 0x100
	s_addc_u32 s23, s21, 0
	s_cmp_eq_u32 s82, 40
	s_cselect_b32 s37, s7, s23
	s_cselect_b32 s36, s6, s22
	s_cselect_b32 s27, s19, s81
	s_cselect_b32 s26, s18, s80
	v_lshl_add_u64 v[200:201], s[20:21], 0, v[186:187]
	s_add_i32 m0, s43, 0xc000
	ds_read_b128 v[160:163], v205
	ds_read_b128 v[164:167], v205 offset:1024
	ds_read_b128 v[168:171], v205 offset:2048
	ds_read_b128 v[172:175], v205 offset:3072
	ds_read_b128 v[206:209], v205 offset:4096
	ds_read_b128 v[210:213], v205 offset:5120
	ds_read_b128 v[214:217], v205 offset:6144
	ds_read_b128 v[218:221], v205 offset:7168
	global_load_lds_dwordx4 v[200:201], off
	v_lshl_add_u64 v[200:201], s[20:21], 0, v[188:189]
	s_add_i32 m0, s43, 0xe000
	s_nop 0
	global_load_lds_dwordx4 v[200:201], off
	s_waitcnt vmcnt(8)
	s_waitcnt lgkmcnt(0)
	s_setprio 1
	s_barrier
	v_mfma_f32_16x16x32_bf16 v[132:135], v[112:115], v[160:163], 0
	v_mfma_f32_16x16x32_bf16 v[132:135], v[116:119], v[164:167], v[132:135]
	v_mfma_f32_16x16x32_bf16 v[108:111], v[116:119], v[172:175], 0
	v_mfma_f32_16x16x32_bf16 v[108:111], v[112:115], v[168:171], v[108:111]
	v_mfma_f32_16x16x32_bf16 v[92:95], v[112:115], v[206:209], 0
	v_mfma_f32_16x16x32_bf16 v[92:95], v[116:119], v[210:213], v[92:95]
	v_mfma_f32_16x16x32_bf16 v[76:79], v[116:119], v[218:221], 0
	v_mfma_f32_16x16x32_bf16 v[76:79], v[112:115], v[214:217], v[76:79]
	v_mfma_f32_16x16x32_bf16 v[72:75], v[136:139], v[214:217], 0
	v_mfma_f32_16x16x32_bf16 v[72:75], v[140:143], v[218:221], v[72:75]
	v_mfma_f32_16x16x32_bf16 v[88:91], v[140:143], v[210:213], 0
	v_mfma_f32_16x16x32_bf16 v[88:91], v[136:139], v[206:209], v[88:91]
	v_mfma_f32_16x16x32_bf16 v[104:107], v[136:139], v[168:171], 0
	v_mfma_f32_16x16x32_bf16 v[104:107], v[140:143], v[172:175], v[104:107]
	v_mfma_f32_16x16x32_bf16 v[128:131], v[140:143], v[164:167], 0
	v_mfma_f32_16x16x32_bf16 v[128:131], v[136:139], v[160:163], v[128:131]
	v_mfma_f32_16x16x32_bf16 v[124:127], v[144:147], v[160:163], 0
	v_mfma_f32_16x16x32_bf16 v[124:127], v[148:151], v[164:167], v[124:127]
	v_mfma_f32_16x16x32_bf16 v[100:103], v[148:151], v[172:175], 0
	v_mfma_f32_16x16x32_bf16 v[100:103], v[144:147], v[168:171], v[100:103]
	v_mfma_f32_16x16x32_bf16 v[84:87], v[144:147], v[206:209], 0
	v_mfma_f32_16x16x32_bf16 v[84:87], v[148:151], v[210:213], v[84:87]
	v_mfma_f32_16x16x32_bf16 v[68:71], v[148:151], v[218:221], 0
	v_mfma_f32_16x16x32_bf16 v[68:71], v[144:147], v[214:217], v[68:71]
	v_mfma_f32_16x16x32_bf16 v[64:67], v[152:155], v[214:217], 0
	v_mfma_f32_16x16x32_bf16 v[64:67], v[156:159], v[218:221], v[64:67]
	v_mfma_f32_16x16x32_bf16 v[80:83], v[156:159], v[210:213], 0
	v_mfma_f32_16x16x32_bf16 v[80:83], v[152:155], v[206:209], v[80:83]
	v_mfma_f32_16x16x32_bf16 v[96:99], v[152:155], v[168:171], 0
	v_mfma_f32_16x16x32_bf16 v[96:99], v[156:159], v[172:175], v[96:99]
	v_mfma_f32_16x16x32_bf16 v[120:123], v[156:159], v[164:167], 0
	v_mfma_f32_16x16x32_bf16 v[120:123], v[152:155], v[160:163], v[120:123]
	s_barrier
	s_setprio 0
	s_add_i32 s20, s59, s40
	v_lshl_add_u64 v[200:201], s[26:27], 0, v[180:181]
	s_mov_b32 m0, s20
	ds_read_b128 v[160:163], v205 offset:16384
	ds_read_b128 v[164:167], v205 offset:17408
	ds_read_b128 v[168:171], v205 offset:18432
	ds_read_b128 v[172:175], v205 offset:19456
	ds_read_b128 v[206:209], v205 offset:20480
	ds_read_b128 v[210:213], v205 offset:21504
	ds_read_b128 v[214:217], v205 offset:22528
	ds_read_b128 v[218:221], v205 offset:23552
	global_load_lds_dwordx4 v[200:201], off
	s_add_i32 m0, s20, 0x2000
	s_add_u32 s20, s26, 0xb0000
	v_lshl_add_u64 v[222:223], s[26:27], 0, v[176:177]
	s_addc_u32 s21, s27, 0
	s_add_i32 s83, s66, s40
	global_load_lds_dwordx4 v[222:223], off
	v_lshl_add_u64 v[224:225], s[20:21], 0, v[180:181]
	s_mov_b32 m0, s83
	v_lshl_add_u64 v[226:227], s[36:37], 0, v[178:179]
	global_load_lds_dwordx4 v[224:225], off
	v_lshl_add_u64 v[224:225], s[20:21], 0, v[176:177]
	s_add_i32 m0, s83, 0x2000
	s_nop 0
	global_load_lds_dwordx4 v[224:225], off
	v_lshl_add_u64 v[224:225], s[36:37], 0, v[182:183]
	s_mov_b32 m0, s43
	s_nop 0
	global_load_lds_dwordx4 v[224:225], off
	s_mov_b32 m0, s44
	s_nop 0
	global_load_lds_dwordx4 v[226:227], off
	s_waitcnt vmcnt(8)
	s_waitcnt lgkmcnt(0)
	s_setprio 1
	s_barrier
	v_mfma_f32_16x16x32_bf16 v[60:63], v[112:115], v[160:163], 0
	v_mfma_f32_16x16x32_bf16 v[60:63], v[116:119], v[164:167], v[60:63]
	v_mfma_f32_16x16x32_bf16 v[44:47], v[116:119], v[172:175], 0
	v_mfma_f32_16x16x32_bf16 v[44:47], v[112:115], v[168:171], v[44:47]
	v_mfma_f32_16x16x32_bf16 v[28:31], v[112:115], v[206:209], 0
	v_mfma_f32_16x16x32_bf16 v[28:31], v[116:119], v[210:213], v[28:31]
	v_mfma_f32_16x16x32_bf16 v[12:15], v[116:119], v[218:221], 0
	v_mfma_f32_16x16x32_bf16 v[12:15], v[112:115], v[214:217], v[12:15]
	v_mfma_f32_16x16x32_bf16 v[8:11], v[136:139], v[214:217], 0
	v_mfma_f32_16x16x32_bf16 v[8:11], v[140:143], v[218:221], v[8:11]
	v_mfma_f32_16x16x32_bf16 v[24:27], v[140:143], v[210:213], 0
	v_mfma_f32_16x16x32_bf16 v[24:27], v[136:139], v[206:209], v[24:27]
	v_mfma_f32_16x16x32_bf16 v[40:43], v[136:139], v[168:171], 0
	v_mfma_f32_16x16x32_bf16 v[40:43], v[140:143], v[172:175], v[40:43]
	v_mfma_f32_16x16x32_bf16 v[56:59], v[140:143], v[164:167], 0
	v_mfma_f32_16x16x32_bf16 v[56:59], v[136:139], v[160:163], v[56:59]
	v_mfma_f32_16x16x32_bf16 v[52:55], v[144:147], v[160:163], 0
	v_mfma_f32_16x16x32_bf16 v[52:55], v[148:151], v[164:167], v[52:55]
	v_mfma_f32_16x16x32_bf16 v[36:39], v[148:151], v[172:175], 0
	v_mfma_f32_16x16x32_bf16 v[36:39], v[144:147], v[168:171], v[36:39]
	v_mfma_f32_16x16x32_bf16 v[20:23], v[144:147], v[206:209], 0
	v_mfma_f32_16x16x32_bf16 v[20:23], v[148:151], v[210:213], v[20:23]
	v_mfma_f32_16x16x32_bf16 v[4:7], v[148:151], v[218:221], 0
	v_mfma_f32_16x16x32_bf16 v[4:7], v[144:147], v[214:217], v[4:7]
	v_mfma_f32_16x16x32_bf16 v[0:3], v[152:155], v[214:217], 0
	v_mfma_f32_16x16x32_bf16 v[0:3], v[156:159], v[218:221], v[0:3]
	v_mfma_f32_16x16x32_bf16 v[16:19], v[156:159], v[210:213], 0
	v_mfma_f32_16x16x32_bf16 v[16:19], v[152:155], v[206:209], v[16:19]
	v_mfma_f32_16x16x32_bf16 v[32:35], v[152:155], v[168:171], 0
	v_mfma_f32_16x16x32_bf16 v[32:35], v[156:159], v[172:175], v[32:35]
	v_mfma_f32_16x16x32_bf16 v[48:51], v[156:159], v[164:167], 0
	v_mfma_f32_16x16x32_bf16 v[48:51], v[152:155], v[160:163], v[48:51]
	s_barrier
	s_setprio 0
	s_add_i32 s83, 0, 0x18000
	s_add_i32 s85, 0, 0x1c000
	v_add_u32_e32 v140, s83, v202
	v_add_u32_e32 v156, s85, v202
	ds_read_b128 v[112:115], v140
	ds_read_b128 v[116:119], v140 offset:1024
	ds_read_b128 v[136:139], v140 offset:2048
	ds_read_b128 v[140:143], v140 offset:3072
	ds_read_b128 v[144:147], v156
	ds_read_b128 v[148:151], v156 offset:1024
	ds_read_b128 v[152:155], v156 offset:2048
	ds_read_b128 v[156:159], v156 offset:3072
	s_add_u32 s20, s36, 0xb0000
	s_addc_u32 s21, s37, 0
	s_mov_b32 m0, s45
	v_lshl_add_u64 v[230:231], s[20:21], 0, v[182:183]
	ds_read_b128 v[160:163], v205 offset:32768
	ds_read_b128 v[164:167], v205 offset:33792
	ds_read_b128 v[168:171], v205 offset:34816
	ds_read_b128 v[172:175], v205 offset:35840
	ds_read_b128 v[206:209], v205 offset:36864
	ds_read_b128 v[210:213], v205 offset:37888
	ds_read_b128 v[214:217], v205 offset:38912
	ds_read_b128 v[218:221], v205 offset:39936
	global_load_lds_dwordx4 v[230:231], off
	v_lshl_add_u64 v[230:231], s[20:21], 0, v[178:179]
	s_mov_b32 m0, s46
	s_nop 0
	global_load_lds_dwordx4 v[230:231], off
	s_waitcnt vmcnt(8)
	s_waitcnt lgkmcnt(0)
	s_setprio 1
	s_barrier
	v_mfma_f32_16x16x32_bf16 v[132:135], v[112:115], v[160:163], v[132:135]
	v_mfma_f32_16x16x32_bf16 v[132:135], v[116:119], v[164:167], v[132:135]
	v_mfma_f32_16x16x32_bf16 v[108:111], v[116:119], v[172:175], v[108:111]
	v_mfma_f32_16x16x32_bf16 v[108:111], v[112:115], v[168:171], v[108:111]
	v_mfma_f32_16x16x32_bf16 v[92:95], v[112:115], v[206:209], v[92:95]
	v_mfma_f32_16x16x32_bf16 v[92:95], v[116:119], v[210:213], v[92:95]
	v_mfma_f32_16x16x32_bf16 v[76:79], v[116:119], v[218:221], v[76:79]
	v_mfma_f32_16x16x32_bf16 v[76:79], v[112:115], v[214:217], v[76:79]
	v_mfma_f32_16x16x32_bf16 v[72:75], v[136:139], v[214:217], v[72:75]
	v_mfma_f32_16x16x32_bf16 v[72:75], v[140:143], v[218:221], v[72:75]
	v_mfma_f32_16x16x32_bf16 v[88:91], v[140:143], v[210:213], v[88:91]
	v_mfma_f32_16x16x32_bf16 v[88:91], v[136:139], v[206:209], v[88:91]
	v_mfma_f32_16x16x32_bf16 v[104:107], v[136:139], v[168:171], v[104:107]
	v_mfma_f32_16x16x32_bf16 v[104:107], v[140:143], v[172:175], v[104:107]
	v_mfma_f32_16x16x32_bf16 v[128:131], v[140:143], v[164:167], v[128:131]
	v_mfma_f32_16x16x32_bf16 v[128:131], v[136:139], v[160:163], v[128:131]
	v_mfma_f32_16x16x32_bf16 v[124:127], v[144:147], v[160:163], v[124:127]
	v_mfma_f32_16x16x32_bf16 v[124:127], v[148:151], v[164:167], v[124:127]
	v_mfma_f32_16x16x32_bf16 v[100:103], v[148:151], v[172:175], v[100:103]
	v_mfma_f32_16x16x32_bf16 v[100:103], v[144:147], v[168:171], v[100:103]
	v_mfma_f32_16x16x32_bf16 v[84:87], v[144:147], v[206:209], v[84:87]
	v_mfma_f32_16x16x32_bf16 v[84:87], v[148:151], v[210:213], v[84:87]
	v_mfma_f32_16x16x32_bf16 v[68:71], v[148:151], v[218:221], v[68:71]
	v_mfma_f32_16x16x32_bf16 v[68:71], v[144:147], v[214:217], v[68:71]
	v_mfma_f32_16x16x32_bf16 v[64:67], v[152:155], v[214:217], v[64:67]
	v_mfma_f32_16x16x32_bf16 v[64:67], v[156:159], v[218:221], v[64:67]
	v_mfma_f32_16x16x32_bf16 v[80:83], v[156:159], v[210:213], v[80:83]
	v_mfma_f32_16x16x32_bf16 v[80:83], v[152:155], v[206:209], v[80:83]
	v_mfma_f32_16x16x32_bf16 v[96:99], v[152:155], v[168:171], v[96:99]
	v_mfma_f32_16x16x32_bf16 v[96:99], v[156:159], v[172:175], v[96:99]
	v_mfma_f32_16x16x32_bf16 v[120:123], v[156:159], v[164:167], v[120:123]
	v_mfma_f32_16x16x32_bf16 v[120:123], v[152:155], v[160:163], v[120:123]
	s_barrier
	s_setprio 0
	s_add_i32 s20, s83, s40
	v_lshl_add_u64 v[200:201], v[200:201], 0, s[14:15]
	s_mov_b32 m0, s20
	ds_read_b128 v[160:163], v205 offset:49152
	ds_read_b128 v[164:167], v205 offset:50176
	ds_read_b128 v[168:171], v205 offset:51200
	ds_read_b128 v[172:175], v205 offset:52224
	ds_read_b128 v[206:209], v205 offset:53248
	ds_read_b128 v[210:213], v205 offset:54272
	ds_read_b128 v[214:217], v205 offset:55296
	ds_read_b128 v[218:221], v205 offset:56320
	global_load_lds_dwordx4 v[200:201], off
	s_add_i32 m0, s20, 0x2000
	s_add_u32 s20, s26, 0xb0080
	v_lshl_add_u64 v[200:201], v[222:223], 0, s[14:15]
	s_addc_u32 s21, s27, 0
	s_add_i32 s26, s85, s40
	global_load_lds_dwordx4 v[200:201], off
	v_lshl_add_u64 v[200:201], s[20:21], 0, v[180:181]
	s_mov_b32 m0, s26
	s_nop 0
	global_load_lds_dwordx4 v[200:201], off
	v_lshl_add_u64 v[200:201], s[20:21], 0, v[176:177]
	s_add_i32 m0, s26, 0x2000
	s_nop 0
	global_load_lds_dwordx4 v[200:201], off
	v_lshl_add_u64 v[200:201], v[224:225], 0, s[14:15]
	s_mov_b32 m0, s52
	s_nop 0
	global_load_lds_dwordx4 v[200:201], off
	v_lshl_add_u64 v[200:201], v[226:227], 0, s[14:15]
	s_mov_b32 m0, s53
	s_nop 0
	global_load_lds_dwordx4 v[200:201], off
	s_waitcnt vmcnt(8)
	s_waitcnt lgkmcnt(0)
	s_setprio 1
	s_barrier
	v_mfma_f32_16x16x32_bf16 v[60:63], v[112:115], v[160:163], v[60:63]
	v_mfma_f32_16x16x32_bf16 v[60:63], v[116:119], v[164:167], v[60:63]
	v_mfma_f32_16x16x32_bf16 v[44:47], v[116:119], v[172:175], v[44:47]
	v_mfma_f32_16x16x32_bf16 v[44:47], v[112:115], v[168:171], v[44:47]
	v_mfma_f32_16x16x32_bf16 v[28:31], v[112:115], v[206:209], v[28:31]
	v_mfma_f32_16x16x32_bf16 v[28:31], v[116:119], v[210:213], v[28:31]
	v_mfma_f32_16x16x32_bf16 v[12:15], v[116:119], v[218:221], v[12:15]
	v_mfma_f32_16x16x32_bf16 v[12:15], v[112:115], v[214:217], v[12:15]
	v_mfma_f32_16x16x32_bf16 v[8:11], v[136:139], v[214:217], v[8:11]
	v_mfma_f32_16x16x32_bf16 v[8:11], v[140:143], v[218:221], v[8:11]
	v_mfma_f32_16x16x32_bf16 v[24:27], v[140:143], v[210:213], v[24:27]
	v_mfma_f32_16x16x32_bf16 v[24:27], v[136:139], v[206:209], v[24:27]
	v_mfma_f32_16x16x32_bf16 v[40:43], v[136:139], v[168:171], v[40:43]
	v_mfma_f32_16x16x32_bf16 v[40:43], v[140:143], v[172:175], v[40:43]
	v_mfma_f32_16x16x32_bf16 v[56:59], v[140:143], v[164:167], v[56:59]
	v_mfma_f32_16x16x32_bf16 v[56:59], v[136:139], v[160:163], v[56:59]
	v_mfma_f32_16x16x32_bf16 v[52:55], v[144:147], v[160:163], v[52:55]
	v_mfma_f32_16x16x32_bf16 v[52:55], v[148:151], v[164:167], v[52:55]
	v_mfma_f32_16x16x32_bf16 v[36:39], v[148:151], v[172:175], v[36:39]
	v_mfma_f32_16x16x32_bf16 v[36:39], v[144:147], v[168:171], v[36:39]
	v_mfma_f32_16x16x32_bf16 v[20:23], v[144:147], v[206:209], v[20:23]
	v_mfma_f32_16x16x32_bf16 v[20:23], v[148:151], v[210:213], v[20:23]
	v_mfma_f32_16x16x32_bf16 v[4:7], v[148:151], v[218:221], v[4:7]
	v_mfma_f32_16x16x32_bf16 v[4:7], v[144:147], v[214:217], v[4:7]
	v_mfma_f32_16x16x32_bf16 v[0:3], v[152:155], v[214:217], v[0:3]
	v_mfma_f32_16x16x32_bf16 v[0:3], v[156:159], v[218:221], v[0:3]
	v_mfma_f32_16x16x32_bf16 v[16:19], v[156:159], v[210:213], v[16:19]
	v_mfma_f32_16x16x32_bf16 v[16:19], v[152:155], v[206:209], v[16:19]
	v_mfma_f32_16x16x32_bf16 v[32:35], v[152:155], v[168:171], v[32:35]
	v_mfma_f32_16x16x32_bf16 v[32:35], v[156:159], v[172:175], v[32:35]
	v_mfma_f32_16x16x32_bf16 v[48:51], v[156:159], v[164:167], v[48:51]
	v_mfma_f32_16x16x32_bf16 v[48:51], v[152:155], v[160:163], v[48:51]
	s_barrier
	s_setprio 0
	s_add_i32 s82, s82, 2
	s_add_u32 s80, s80, 0x100
	s_addc_u32 s81, s81, 0
	s_cmp_gt_u32 s82, 41
	s_mov_b64 s[20:21], s[22:23]
.LBB0_836:
	ds_read_b128 v[112:115], v203
	ds_read_b128 v[116:119], v203 offset:1024
	ds_read_b128 v[136:139], v203 offset:2048
	ds_read_b128 v[140:143], v203 offset:3072
	ds_read_b128 v[144:147], v204
	ds_read_b128 v[148:151], v204 offset:1024
	ds_read_b128 v[152:155], v204 offset:2048
	ds_read_b128 v[156:159], v204 offset:3072
	s_add_u32 s22, s20, 0x100
	s_addc_u32 s23, s21, 0
	s_cmp_eq_u32 s82, 40
	s_cselect_b32 s37, s7, s23
	s_cselect_b32 s36, s6, s22
	s_cselect_b32 s27, s19, s81
	s_cselect_b32 s26, s18, s80
	v_lshl_add_u64 v[200:201], s[20:21], 0, v[186:187]
	s_add_i32 m0, s43, 0xc000
	ds_read_b128 v[160:163], v205
	ds_read_b128 v[164:167], v205 offset:1024
	ds_read_b128 v[168:171], v205 offset:2048
	ds_read_b128 v[172:175], v205 offset:3072
	ds_read_b128 v[206:209], v205 offset:4096
	ds_read_b128 v[210:213], v205 offset:5120
	ds_read_b128 v[214:217], v205 offset:6144
	ds_read_b128 v[218:221], v205 offset:7168
	global_load_lds_dwordx4 v[200:201], off
	v_lshl_add_u64 v[200:201], s[20:21], 0, v[188:189]
	s_add_i32 m0, s43, 0xe000
	s_nop 0
	global_load_lds_dwordx4 v[200:201], off
	s_waitcnt vmcnt(8)
	s_waitcnt lgkmcnt(0)
	s_setprio 1
	s_barrier
	v_mfma_f32_16x16x32_bf16 v[132:135], v[112:115], v[160:163], v[132:135]
	v_mfma_f32_16x16x32_bf16 v[132:135], v[116:119], v[164:167], v[132:135]
	v_mfma_f32_16x16x32_bf16 v[108:111], v[116:119], v[172:175], v[108:111]
	v_mfma_f32_16x16x32_bf16 v[108:111], v[112:115], v[168:171], v[108:111]
	v_mfma_f32_16x16x32_bf16 v[92:95], v[112:115], v[206:209], v[92:95]
	v_mfma_f32_16x16x32_bf16 v[92:95], v[116:119], v[210:213], v[92:95]
	v_mfma_f32_16x16x32_bf16 v[76:79], v[116:119], v[218:221], v[76:79]
	v_mfma_f32_16x16x32_bf16 v[76:79], v[112:115], v[214:217], v[76:79]
	v_mfma_f32_16x16x32_bf16 v[72:75], v[136:139], v[214:217], v[72:75]
	v_mfma_f32_16x16x32_bf16 v[72:75], v[140:143], v[218:221], v[72:75]
	v_mfma_f32_16x16x32_bf16 v[88:91], v[140:143], v[210:213], v[88:91]
	v_mfma_f32_16x16x32_bf16 v[88:91], v[136:139], v[206:209], v[88:91]
	v_mfma_f32_16x16x32_bf16 v[104:107], v[136:139], v[168:171], v[104:107]
	v_mfma_f32_16x16x32_bf16 v[104:107], v[140:143], v[172:175], v[104:107]
	v_mfma_f32_16x16x32_bf16 v[128:131], v[140:143], v[164:167], v[128:131]
	v_mfma_f32_16x16x32_bf16 v[128:131], v[136:139], v[160:163], v[128:131]
	v_mfma_f32_16x16x32_bf16 v[124:127], v[144:147], v[160:163], v[124:127]
	v_mfma_f32_16x16x32_bf16 v[124:127], v[148:151], v[164:167], v[124:127]
	v_mfma_f32_16x16x32_bf16 v[100:103], v[148:151], v[172:175], v[100:103]
	v_mfma_f32_16x16x32_bf16 v[100:103], v[144:147], v[168:171], v[100:103]
	v_mfma_f32_16x16x32_bf16 v[84:87], v[144:147], v[206:209], v[84:87]
	v_mfma_f32_16x16x32_bf16 v[84:87], v[148:151], v[210:213], v[84:87]
	v_mfma_f32_16x16x32_bf16 v[68:71], v[148:151], v[218:221], v[68:71]
	v_mfma_f32_16x16x32_bf16 v[68:71], v[144:147], v[214:217], v[68:71]
	v_mfma_f32_16x16x32_bf16 v[64:67], v[152:155], v[214:217], v[64:67]
	v_mfma_f32_16x16x32_bf16 v[64:67], v[156:159], v[218:221], v[64:67]
	v_mfma_f32_16x16x32_bf16 v[80:83], v[156:159], v[210:213], v[80:83]
	v_mfma_f32_16x16x32_bf16 v[80:83], v[152:155], v[206:209], v[80:83]
	v_mfma_f32_16x16x32_bf16 v[96:99], v[152:155], v[168:171], v[96:99]
	v_mfma_f32_16x16x32_bf16 v[96:99], v[156:159], v[172:175], v[96:99]
	v_mfma_f32_16x16x32_bf16 v[120:123], v[156:159], v[164:167], v[120:123]
	v_mfma_f32_16x16x32_bf16 v[120:123], v[152:155], v[160:163], v[120:123]
	s_barrier
	s_setprio 0
	s_add_i32 s20, s59, s40
	v_lshl_add_u64 v[200:201], s[26:27], 0, v[180:181]
	s_mov_b32 m0, s20
	ds_read_b128 v[160:163], v205 offset:16384
	ds_read_b128 v[164:167], v205 offset:17408
	ds_read_b128 v[168:171], v205 offset:18432
	ds_read_b128 v[172:175], v205 offset:19456
	ds_read_b128 v[206:209], v205 offset:20480
	ds_read_b128 v[210:213], v205 offset:21504
	ds_read_b128 v[214:217], v205 offset:22528
	ds_read_b128 v[218:221], v205 offset:23552
	global_load_lds_dwordx4 v[200:201], off
	s_add_i32 m0, s20, 0x2000
	s_add_u32 s20, s26, 0xb0000
	v_lshl_add_u64 v[222:223], s[26:27], 0, v[176:177]
	s_addc_u32 s21, s27, 0
	s_add_i32 s83, s66, s40
	global_load_lds_dwordx4 v[222:223], off
	v_lshl_add_u64 v[224:225], s[20:21], 0, v[180:181]
	s_mov_b32 m0, s83
	v_lshl_add_u64 v[226:227], s[36:37], 0, v[178:179]
	global_load_lds_dwordx4 v[224:225], off
	v_lshl_add_u64 v[224:225], s[20:21], 0, v[176:177]
	s_add_i32 m0, s83, 0x2000
	s_nop 0
	global_load_lds_dwordx4 v[224:225], off
	v_lshl_add_u64 v[224:225], s[36:37], 0, v[182:183]
	s_mov_b32 m0, s43
	s_nop 0
	global_load_lds_dwordx4 v[224:225], off
	s_mov_b32 m0, s44
	s_nop 0
	global_load_lds_dwordx4 v[226:227], off
	s_waitcnt vmcnt(8)
	s_waitcnt lgkmcnt(0)
	s_setprio 1
	s_barrier
	v_mfma_f32_16x16x32_bf16 v[60:63], v[112:115], v[160:163], v[60:63]
	v_mfma_f32_16x16x32_bf16 v[60:63], v[116:119], v[164:167], v[60:63]
	v_mfma_f32_16x16x32_bf16 v[44:47], v[116:119], v[172:175], v[44:47]
	v_mfma_f32_16x16x32_bf16 v[44:47], v[112:115], v[168:171], v[44:47]
	v_mfma_f32_16x16x32_bf16 v[28:31], v[112:115], v[206:209], v[28:31]
	v_mfma_f32_16x16x32_bf16 v[28:31], v[116:119], v[210:213], v[28:31]
	v_mfma_f32_16x16x32_bf16 v[12:15], v[116:119], v[218:221], v[12:15]
	v_mfma_f32_16x16x32_bf16 v[12:15], v[112:115], v[214:217], v[12:15]
	v_mfma_f32_16x16x32_bf16 v[8:11], v[136:139], v[214:217], v[8:11]
	v_mfma_f32_16x16x32_bf16 v[8:11], v[140:143], v[218:221], v[8:11]
	v_mfma_f32_16x16x32_bf16 v[24:27], v[140:143], v[210:213], v[24:27]
	v_mfma_f32_16x16x32_bf16 v[24:27], v[136:139], v[206:209], v[24:27]
	v_mfma_f32_16x16x32_bf16 v[40:43], v[136:139], v[168:171], v[40:43]
	v_mfma_f32_16x16x32_bf16 v[40:43], v[140:143], v[172:175], v[40:43]
	v_mfma_f32_16x16x32_bf16 v[56:59], v[140:143], v[164:167], v[56:59]
	v_mfma_f32_16x16x32_bf16 v[56:59], v[136:139], v[160:163], v[56:59]
	v_mfma_f32_16x16x32_bf16 v[52:55], v[144:147], v[160:163], v[52:55]
	v_mfma_f32_16x16x32_bf16 v[52:55], v[148:151], v[164:167], v[52:55]
	v_mfma_f32_16x16x32_bf16 v[36:39], v[148:151], v[172:175], v[36:39]
	v_mfma_f32_16x16x32_bf16 v[36:39], v[144:147], v[168:171], v[36:39]
	v_mfma_f32_16x16x32_bf16 v[20:23], v[144:147], v[206:209], v[20:23]
	v_mfma_f32_16x16x32_bf16 v[20:23], v[148:151], v[210:213], v[20:23]
	v_mfma_f32_16x16x32_bf16 v[4:7], v[148:151], v[218:221], v[4:7]
	v_mfma_f32_16x16x32_bf16 v[4:7], v[144:147], v[214:217], v[4:7]
	v_mfma_f32_16x16x32_bf16 v[0:3], v[152:155], v[214:217], v[0:3]
	v_mfma_f32_16x16x32_bf16 v[0:3], v[156:159], v[218:221], v[0:3]
	v_mfma_f32_16x16x32_bf16 v[16:19], v[156:159], v[210:213], v[16:19]
	v_mfma_f32_16x16x32_bf16 v[16:19], v[152:155], v[206:209], v[16:19]
	v_mfma_f32_16x16x32_bf16 v[32:35], v[152:155], v[168:171], v[32:35]
	v_mfma_f32_16x16x32_bf16 v[32:35], v[156:159], v[172:175], v[32:35]
	v_mfma_f32_16x16x32_bf16 v[48:51], v[156:159], v[164:167], v[48:51]
	v_mfma_f32_16x16x32_bf16 v[48:51], v[152:155], v[160:163], v[48:51]
	s_barrier
	s_setprio 0
	s_add_i32 s83, 0, 0x18000
	s_add_i32 s85, 0, 0x1c000
	v_add_u32_e32 v140, s83, v202
	v_add_u32_e32 v156, s85, v202
	ds_read_b128 v[112:115], v140
	ds_read_b128 v[116:119], v140 offset:1024
	ds_read_b128 v[136:139], v140 offset:2048
	ds_read_b128 v[140:143], v140 offset:3072
	ds_read_b128 v[144:147], v156
	ds_read_b128 v[148:151], v156 offset:1024
	ds_read_b128 v[152:155], v156 offset:2048
	ds_read_b128 v[156:159], v156 offset:3072
	s_add_u32 s20, s36, 0xb0000
	s_addc_u32 s21, s37, 0
	s_mov_b32 m0, s45
	v_lshl_add_u64 v[230:231], s[20:21], 0, v[182:183]
	ds_read_b128 v[160:163], v205 offset:32768
	ds_read_b128 v[164:167], v205 offset:33792
	ds_read_b128 v[168:171], v205 offset:34816
	ds_read_b128 v[172:175], v205 offset:35840
	ds_read_b128 v[206:209], v205 offset:36864
	ds_read_b128 v[210:213], v205 offset:37888
	ds_read_b128 v[214:217], v205 offset:38912
	ds_read_b128 v[218:221], v205 offset:39936
	global_load_lds_dwordx4 v[230:231], off
	v_lshl_add_u64 v[230:231], s[20:21], 0, v[178:179]
	s_mov_b32 m0, s46
	s_nop 0
	global_load_lds_dwordx4 v[230:231], off
	s_waitcnt vmcnt(8)
	s_waitcnt lgkmcnt(0)
	s_setprio 1
	s_barrier
	v_mfma_f32_16x16x32_bf16 v[132:135], v[112:115], v[160:163], v[132:135]
	v_mfma_f32_16x16x32_bf16 v[132:135], v[116:119], v[164:167], v[132:135]
	v_mfma_f32_16x16x32_bf16 v[108:111], v[116:119], v[172:175], v[108:111]
	v_mfma_f32_16x16x32_bf16 v[108:111], v[112:115], v[168:171], v[108:111]
	v_mfma_f32_16x16x32_bf16 v[92:95], v[112:115], v[206:209], v[92:95]
	v_mfma_f32_16x16x32_bf16 v[92:95], v[116:119], v[210:213], v[92:95]
	v_mfma_f32_16x16x32_bf16 v[76:79], v[116:119], v[218:221], v[76:79]
	v_mfma_f32_16x16x32_bf16 v[76:79], v[112:115], v[214:217], v[76:79]
	v_mfma_f32_16x16x32_bf16 v[72:75], v[136:139], v[214:217], v[72:75]
	v_mfma_f32_16x16x32_bf16 v[72:75], v[140:143], v[218:221], v[72:75]
	v_mfma_f32_16x16x32_bf16 v[88:91], v[140:143], v[210:213], v[88:91]
	v_mfma_f32_16x16x32_bf16 v[88:91], v[136:139], v[206:209], v[88:91]
	v_mfma_f32_16x16x32_bf16 v[104:107], v[136:139], v[168:171], v[104:107]
	v_mfma_f32_16x16x32_bf16 v[104:107], v[140:143], v[172:175], v[104:107]
	v_mfma_f32_16x16x32_bf16 v[128:131], v[140:143], v[164:167], v[128:131]
	v_mfma_f32_16x16x32_bf16 v[128:131], v[136:139], v[160:163], v[128:131]
	v_mfma_f32_16x16x32_bf16 v[124:127], v[144:147], v[160:163], v[124:127]
	v_mfma_f32_16x16x32_bf16 v[124:127], v[148:151], v[164:167], v[124:127]
	v_mfma_f32_16x16x32_bf16 v[100:103], v[148:151], v[172:175], v[100:103]
	v_mfma_f32_16x16x32_bf16 v[100:103], v[144:147], v[168:171], v[100:103]
	v_mfma_f32_16x16x32_bf16 v[84:87], v[144:147], v[206:209], v[84:87]
	v_mfma_f32_16x16x32_bf16 v[84:87], v[148:151], v[210:213], v[84:87]
	v_mfma_f32_16x16x32_bf16 v[68:71], v[148:151], v[218:221], v[68:71]
	v_mfma_f32_16x16x32_bf16 v[68:71], v[144:147], v[214:217], v[68:71]
	v_mfma_f32_16x16x32_bf16 v[64:67], v[152:155], v[214:217], v[64:67]
	v_mfma_f32_16x16x32_bf16 v[64:67], v[156:159], v[218:221], v[64:67]
	v_mfma_f32_16x16x32_bf16 v[80:83], v[156:159], v[210:213], v[80:83]
	v_mfma_f32_16x16x32_bf16 v[80:83], v[152:155], v[206:209], v[80:83]
	v_mfma_f32_16x16x32_bf16 v[96:99], v[152:155], v[168:171], v[96:99]
	v_mfma_f32_16x16x32_bf16 v[96:99], v[156:159], v[172:175], v[96:99]
	v_mfma_f32_16x16x32_bf16 v[120:123], v[156:159], v[164:167], v[120:123]
	v_mfma_f32_16x16x32_bf16 v[120:123], v[152:155], v[160:163], v[120:123]
	s_barrier
	s_setprio 0
	s_add_i32 s20, s83, s40
	v_lshl_add_u64 v[200:201], v[200:201], 0, s[14:15]
	s_mov_b32 m0, s20
	ds_read_b128 v[160:163], v205 offset:49152
	ds_read_b128 v[164:167], v205 offset:50176
	ds_read_b128 v[168:171], v205 offset:51200
	ds_read_b128 v[172:175], v205 offset:52224
	ds_read_b128 v[206:209], v205 offset:53248
	ds_read_b128 v[210:213], v205 offset:54272
	ds_read_b128 v[214:217], v205 offset:55296
	ds_read_b128 v[218:221], v205 offset:56320
	global_load_lds_dwordx4 v[200:201], off
	s_add_i32 m0, s20, 0x2000
	s_add_u32 s20, s26, 0xb0080
	v_lshl_add_u64 v[200:201], v[222:223], 0, s[14:15]
	s_addc_u32 s21, s27, 0
	s_add_i32 s26, s85, s40
	global_load_lds_dwordx4 v[200:201], off
	v_lshl_add_u64 v[200:201], s[20:21], 0, v[180:181]
	s_mov_b32 m0, s26
	s_nop 0
	global_load_lds_dwordx4 v[200:201], off
	v_lshl_add_u64 v[200:201], s[20:21], 0, v[176:177]
	s_add_i32 m0, s26, 0x2000
	s_nop 0
	global_load_lds_dwordx4 v[200:201], off
	v_lshl_add_u64 v[200:201], v[224:225], 0, s[14:15]
	s_mov_b32 m0, s52
	s_nop 0
	global_load_lds_dwordx4 v[200:201], off
	v_lshl_add_u64 v[200:201], v[226:227], 0, s[14:15]
	s_mov_b32 m0, s53
	s_nop 0
	global_load_lds_dwordx4 v[200:201], off
	s_waitcnt vmcnt(8)
	s_waitcnt lgkmcnt(0)
	s_setprio 1
	s_barrier
	v_mfma_f32_16x16x32_bf16 v[60:63], v[112:115], v[160:163], v[60:63]
	v_mfma_f32_16x16x32_bf16 v[60:63], v[116:119], v[164:167], v[60:63]
	v_mfma_f32_16x16x32_bf16 v[44:47], v[116:119], v[172:175], v[44:47]
	v_mfma_f32_16x16x32_bf16 v[44:47], v[112:115], v[168:171], v[44:47]
	v_mfma_f32_16x16x32_bf16 v[28:31], v[112:115], v[206:209], v[28:31]
	v_mfma_f32_16x16x32_bf16 v[28:31], v[116:119], v[210:213], v[28:31]
	v_mfma_f32_16x16x32_bf16 v[12:15], v[116:119], v[218:221], v[12:15]
	v_mfma_f32_16x16x32_bf16 v[12:15], v[112:115], v[214:217], v[12:15]
	v_mfma_f32_16x16x32_bf16 v[8:11], v[136:139], v[214:217], v[8:11]
	v_mfma_f32_16x16x32_bf16 v[8:11], v[140:143], v[218:221], v[8:11]
	v_mfma_f32_16x16x32_bf16 v[24:27], v[140:143], v[210:213], v[24:27]
	v_mfma_f32_16x16x32_bf16 v[24:27], v[136:139], v[206:209], v[24:27]
	v_mfma_f32_16x16x32_bf16 v[40:43], v[136:139], v[168:171], v[40:43]
	v_mfma_f32_16x16x32_bf16 v[40:43], v[140:143], v[172:175], v[40:43]
	v_mfma_f32_16x16x32_bf16 v[56:59], v[140:143], v[164:167], v[56:59]
	v_mfma_f32_16x16x32_bf16 v[56:59], v[136:139], v[160:163], v[56:59]
	v_mfma_f32_16x16x32_bf16 v[52:55], v[144:147], v[160:163], v[52:55]
	v_mfma_f32_16x16x32_bf16 v[52:55], v[148:151], v[164:167], v[52:55]
	v_mfma_f32_16x16x32_bf16 v[36:39], v[148:151], v[172:175], v[36:39]
	v_mfma_f32_16x16x32_bf16 v[36:39], v[144:147], v[168:171], v[36:39]
	v_mfma_f32_16x16x32_bf16 v[20:23], v[144:147], v[206:209], v[20:23]
	v_mfma_f32_16x16x32_bf16 v[20:23], v[148:151], v[210:213], v[20:23]
	v_mfma_f32_16x16x32_bf16 v[4:7], v[148:151], v[218:221], v[4:7]
	v_mfma_f32_16x16x32_bf16 v[4:7], v[144:147], v[214:217], v[4:7]
	v_mfma_f32_16x16x32_bf16 v[0:3], v[152:155], v[214:217], v[0:3]
	v_mfma_f32_16x16x32_bf16 v[0:3], v[156:159], v[218:221], v[0:3]
	v_mfma_f32_16x16x32_bf16 v[16:19], v[156:159], v[210:213], v[16:19]
	v_mfma_f32_16x16x32_bf16 v[16:19], v[152:155], v[206:209], v[16:19]
	v_mfma_f32_16x16x32_bf16 v[32:35], v[152:155], v[168:171], v[32:35]
	v_mfma_f32_16x16x32_bf16 v[32:35], v[156:159], v[172:175], v[32:35]
	v_mfma_f32_16x16x32_bf16 v[48:51], v[156:159], v[164:167], v[48:51]
	v_mfma_f32_16x16x32_bf16 v[48:51], v[152:155], v[160:163], v[48:51]
	s_barrier
	s_setprio 0
	s_add_i32 s82, s82, 2
	s_add_u32 s80, s80, 0x100
	s_addc_u32 s81, s81, 0
	s_cmp_gt_u32 s82, 41
	s_mov_b64 s[20:21], s[22:23]
	s_cbranch_scc0 .LBB0_836
	s_and_b64 vcc, exec, s[16:17]
	s_cbranch_vccz .LBB0_839
	s_barrier
